# conv+gelu phase regenerated by hand: gate/val register rings with loads 3-4 columns ahead (was 1-2), SGPR-base addressing
# speedup vs baseline: 1.0028x; 1.0027x over previous
.LBB0_1157:
	s_cmp_lt_i32 s56, 11
	s_cselect_b64 s[0:1], -1, 0
	s_and_b64 s[10:11], s[0:1], s[2:3]
	s_andn2_b64 vcc, exec, s[10:11]
	s_cbranch_vccnz .LBB0_1198
	s_mov_b32 s25, 0x58000
	v_cmp_gt_i32_e32 vcc, s25, v184
	s_and_saveexec_b64 s[12:13], vcc
	s_cbranch_execz .LBB0_1197
	s_add_u32 s14, s54, 0x6800000
	s_addc_u32 s15, s55, 0
	s_add_u32 s16, s54, 0x2300000
	s_addc_u32 s17, s55, 0
	v_readlane_b32 s18, v244, 19
	v_readlane_b32 s19, v244, 20
	s_lshl_b32 s27, s72, 9
	s_mov_b32 s24, 0x3e6d3388
	s_mov_b32 s26, 0x3f07dc22
	s_mov_b32 s28, 0xbf3a00e3
	s_mov_b32 s29, 0xbf3a00e3
	s_mov_b32 s30, 0x3f35f0e3
	s_mov_b32 s34, 0xbe11a98e
	s_mov_b32 s36, 0x3e027906
	s_mov_b32 s38, 0xbf38aa3b
	v_mov_b32_e32 v230, v184
.Lconv_item:
	s_mov_b32 s20, 0x2e8ba2e9
	v_mul_hi_i32 v232, v230, s20
	v_lshrrev_b32_e32 v233, 31, v232
	v_ashrrev_i32_e32 v232, 6, v232
	v_add_u32_e32 v232, v232, v233
	v_mul_i32_i24_e32 v233, 0x160, v232
	v_sub_u32_e32 v231, v230, v233
	v_lshlrev_b32_e32 v231, 4, v231
	v_mov_b32_e32 v233, v231
	global_load_dwordx4 v[146:149], v233, s[16:17]
	v_add_u32_e32 v233, 0x1600, v233
	global_load_dwordx4 v[150:153], v233, s[16:17]
	v_add_u32_e32 v233, 0x1600, v233
	global_load_dwordx4 v[154:157], v233, s[16:17]
	v_add_u32_e32 v233, 0x1600, v233
	global_load_dwordx4 v[158:161], v233, s[16:17]
	v_add_u32_e32 v233, 0x1600, v233
	global_load_dwordx4 v[162:165], v233, s[16:17]
	v_add_u32_e32 v233, 0x1600, v233
	global_load_dwordx4 v[166:169], v233, s[16:17]
	v_add_u32_e32 v233, 0x1600, v233
	global_load_dwordx4 v[170:173], v233, s[16:17]
	v_add_u32_e32 v233, 0x1600, v233
	global_load_dwordx4 v[174:177], v233, s[16:17]
	v_add_u32_e32 v233, 0x1600, v233
	global_load_dwordx4 v[178:181], v233, s[16:17]
	v_lshlrev_b32_e32 v234, 1, v231
	global_load_dwordx4 v[72:75], v234, s[18:19]
	global_load_dwordx4 v[76:79], v234, s[18:19] offset:16
	v_and_b32_e32 v233, 1, v232
	v_cmp_eq_u32_e64 s[4:5], 0, v233
	v_cmp_eq_u32_e64 s[6:7], 1, v233
	v_bfe_u32 v234, v232, 1, 6
	v_cmp_eq_u32_e64 s[0:1], 0, v234
	v_cmp_eq_u32_e64 s[2:3], 63, v234
	v_lshrrev_b32_e32 v234, 1, v232
	v_lshlrev_b32_e32 v234, 6, v234
	v_lshl_add_u32 v234, v233, 5, v234
	v_mul_u32_u24_e32 v234, 0x2c00, v234
	v_add_u32_e32 v139, v234, v231
	v_mov_b32_e32 v140, v139
	v_add_u32_e32 v137, 0x1600, v139
	v_subrev_u32_e32 v233, 0x2c00, v137
	v_cndmask_b32_e64 v137, v233, v137, s[4:5]
	v_mov_b32_e32 v233, 0xb0000
	v_sub_u32_e32 v136, v137, v233
	v_cndmask_b32_e64 v136, v136, v137, s[0:1]
	v_add_u32_e32 v138, v137, v233
	v_cndmask_b32_e64 v138, v138, v137, s[2:3]
	s_waitcnt vmcnt(10)
	v_lshlrev_b32_e32 v0, 16, v146
	v_and_b32_e32 v1, 0xffff0000, v146
	v_lshlrev_b32_e32 v2, 16, v147
	v_and_b32_e32 v3, 0xffff0000, v147
	v_lshlrev_b32_e32 v4, 16, v148
	v_and_b32_e32 v5, 0xffff0000, v148
	v_lshlrev_b32_e32 v6, 16, v149
	v_and_b32_e32 v7, 0xffff0000, v149
	s_waitcnt vmcnt(9)
	v_lshlrev_b32_e32 v8, 16, v150
	v_and_b32_e32 v9, 0xffff0000, v150
	v_lshlrev_b32_e32 v10, 16, v151
	v_and_b32_e32 v11, 0xffff0000, v151
	v_lshlrev_b32_e32 v12, 16, v152
	v_and_b32_e32 v13, 0xffff0000, v152
	v_lshlrev_b32_e32 v14, 16, v153
	v_and_b32_e32 v15, 0xffff0000, v153
	s_waitcnt vmcnt(8)
	v_lshlrev_b32_e32 v16, 16, v154
	v_and_b32_e32 v17, 0xffff0000, v154
	v_lshlrev_b32_e32 v18, 16, v155
	v_and_b32_e32 v19, 0xffff0000, v155
	v_lshlrev_b32_e32 v20, 16, v156
	v_and_b32_e32 v21, 0xffff0000, v156
	v_lshlrev_b32_e32 v22, 16, v157
	v_and_b32_e32 v23, 0xffff0000, v157
	s_waitcnt vmcnt(7)
	v_lshlrev_b32_e32 v24, 16, v158
	v_and_b32_e32 v25, 0xffff0000, v158
	v_lshlrev_b32_e32 v26, 16, v159
	v_and_b32_e32 v27, 0xffff0000, v159
	v_lshlrev_b32_e32 v28, 16, v160
	v_and_b32_e32 v29, 0xffff0000, v160
	v_lshlrev_b32_e32 v30, 16, v161
	v_and_b32_e32 v31, 0xffff0000, v161
	s_waitcnt vmcnt(6)
	v_lshlrev_b32_e32 v32, 16, v162
	v_and_b32_e32 v33, 0xffff0000, v162
	v_lshlrev_b32_e32 v34, 16, v163
	v_and_b32_e32 v35, 0xffff0000, v163
	v_lshlrev_b32_e32 v36, 16, v164
	v_and_b32_e32 v37, 0xffff0000, v164
	v_lshlrev_b32_e32 v38, 16, v165
	v_and_b32_e32 v39, 0xffff0000, v165
	s_waitcnt vmcnt(5)
	v_lshlrev_b32_e32 v40, 16, v166
	v_and_b32_e32 v41, 0xffff0000, v166
	v_lshlrev_b32_e32 v42, 16, v167
	v_and_b32_e32 v43, 0xffff0000, v167
	v_lshlrev_b32_e32 v44, 16, v168
	v_and_b32_e32 v45, 0xffff0000, v168
	v_lshlrev_b32_e32 v46, 16, v169
	v_and_b32_e32 v47, 0xffff0000, v169
	s_waitcnt vmcnt(4)
	v_lshlrev_b32_e32 v48, 16, v170
	v_and_b32_e32 v49, 0xffff0000, v170
	v_lshlrev_b32_e32 v50, 16, v171
	v_and_b32_e32 v51, 0xffff0000, v171
	v_lshlrev_b32_e32 v52, 16, v172
	v_and_b32_e32 v53, 0xffff0000, v172
	v_lshlrev_b32_e32 v54, 16, v173
	v_and_b32_e32 v55, 0xffff0000, v173
	s_waitcnt vmcnt(3)
	v_lshlrev_b32_e32 v56, 16, v174
	v_and_b32_e32 v57, 0xffff0000, v174
	v_lshlrev_b32_e32 v58, 16, v175
	v_and_b32_e32 v59, 0xffff0000, v175
	v_lshlrev_b32_e32 v60, 16, v176
	v_and_b32_e32 v61, 0xffff0000, v176
	v_lshlrev_b32_e32 v62, 16, v177
	v_and_b32_e32 v63, 0xffff0000, v177
	s_waitcnt vmcnt(2)
	v_lshlrev_b32_e32 v64, 16, v178
	v_and_b32_e32 v65, 0xffff0000, v178
	v_lshlrev_b32_e32 v66, 16, v179
	v_and_b32_e32 v67, 0xffff0000, v179
	v_lshlrev_b32_e32 v68, 16, v180
	v_and_b32_e32 v69, 0xffff0000, v180
	v_lshlrev_b32_e32 v70, 16, v181
	v_and_b32_e32 v71, 0xffff0000, v181
	v_cndmask_b32_e64 v0, v0, 0, s[0:1]
	v_cndmask_b32_e64 v1, v1, 0, s[0:1]
	v_cndmask_b32_e64 v2, v2, 0, s[0:1]
	v_cndmask_b32_e64 v3, v3, 0, s[0:1]
	v_cndmask_b32_e64 v4, v4, 0, s[0:1]
	v_cndmask_b32_e64 v5, v5, 0, s[0:1]
	v_cndmask_b32_e64 v6, v6, 0, s[0:1]
	v_cndmask_b32_e64 v7, v7, 0, s[0:1]
	v_cndmask_b32_e64 v8, v8, 0, s[0:1]
	v_cndmask_b32_e64 v9, v9, 0, s[0:1]
	v_cndmask_b32_e64 v10, v10, 0, s[0:1]
	v_cndmask_b32_e64 v11, v11, 0, s[0:1]
	v_cndmask_b32_e64 v12, v12, 0, s[0:1]
	v_cndmask_b32_e64 v13, v13, 0, s[0:1]
	v_cndmask_b32_e64 v14, v14, 0, s[0:1]
	v_cndmask_b32_e64 v15, v15, 0, s[0:1]
	v_cndmask_b32_e64 v16, v16, 0, s[0:1]
	v_cndmask_b32_e64 v17, v17, 0, s[0:1]
	v_cndmask_b32_e64 v18, v18, 0, s[0:1]
	v_cndmask_b32_e64 v19, v19, 0, s[0:1]
	v_cndmask_b32_e64 v20, v20, 0, s[0:1]
	v_cndmask_b32_e64 v21, v21, 0, s[0:1]
	v_cndmask_b32_e64 v22, v22, 0, s[0:1]
	v_cndmask_b32_e64 v23, v23, 0, s[0:1]
	v_cndmask_b32_e64 v48, v48, 0, s[2:3]
	v_cndmask_b32_e64 v49, v49, 0, s[2:3]
	v_cndmask_b32_e64 v50, v50, 0, s[2:3]
	v_cndmask_b32_e64 v51, v51, 0, s[2:3]
	v_cndmask_b32_e64 v52, v52, 0, s[2:3]
	v_cndmask_b32_e64 v53, v53, 0, s[2:3]
	v_cndmask_b32_e64 v54, v54, 0, s[2:3]
	v_cndmask_b32_e64 v55, v55, 0, s[2:3]
	v_cndmask_b32_e64 v56, v56, 0, s[2:3]
	v_cndmask_b32_e64 v57, v57, 0, s[2:3]
	v_cndmask_b32_e64 v58, v58, 0, s[2:3]
	v_cndmask_b32_e64 v59, v59, 0, s[2:3]
	v_cndmask_b32_e64 v60, v60, 0, s[2:3]
	v_cndmask_b32_e64 v61, v61, 0, s[2:3]
	v_cndmask_b32_e64 v62, v62, 0, s[2:3]
	v_cndmask_b32_e64 v63, v63, 0, s[2:3]
	v_cndmask_b32_e64 v64, v64, 0, s[2:3]
	v_cndmask_b32_e64 v65, v65, 0, s[2:3]
	v_cndmask_b32_e64 v66, v66, 0, s[2:3]
	v_cndmask_b32_e64 v67, v67, 0, s[2:3]
	v_cndmask_b32_e64 v68, v68, 0, s[2:3]
	v_cndmask_b32_e64 v69, v69, 0, s[2:3]
	v_cndmask_b32_e64 v70, v70, 0, s[2:3]
	v_cndmask_b32_e64 v71, v71, 0, s[2:3]
	s_waitcnt vmcnt(0)
	global_load_dwordx4 v[146:149], v136, s[14:15]
	global_load_dwordx4 v[150:153], v137, s[14:15]
	global_load_dwordx4 v[154:157], v138, s[14:15]
	v_add_u32_e32 v136, 0x2c00, v136
	v_add_u32_e32 v137, 0x2c00, v137
	v_add_u32_e32 v138, 0x2c00, v138
	v_subrev_u32_e32 v233, 0x2c00, v136
	v_cndmask_b32_e64 v136, v136, v233, s[4:5]
	v_subrev_u32_e32 v233, 0x2c00, v137
	v_cndmask_b32_e64 v137, v137, v233, s[4:5]
	v_subrev_u32_e32 v233, 0x2c00, v138
	v_cndmask_b32_e64 v138, v138, v233, s[4:5]
	global_load_dwordx4 v[158:161], v136, s[14:15]
	global_load_dwordx4 v[162:165], v137, s[14:15]
	global_load_dwordx4 v[166:169], v138, s[14:15]
	v_add_u32_e32 v136, 0x2c00, v136
	v_add_u32_e32 v137, 0x2c00, v137
	v_add_u32_e32 v138, 0x2c00, v138
	global_load_dwordx4 v[170:173], v136, s[14:15]
	global_load_dwordx4 v[174:177], v137, s[14:15]
	global_load_dwordx4 v[178:181], v138, s[14:15]
	v_add_u32_e32 v136, 0x2c00, v136
	v_add_u32_e32 v137, 0x2c00, v137
	v_add_u32_e32 v138, 0x2c00, v138
	global_load_dwordx4 v[182:185], v136, s[14:15]
	global_load_dwordx4 v[186:189], v137, s[14:15]
	global_load_dwordx4 v[190:193], v138, s[14:15]
	v_add_u32_e32 v136, 0x2c00, v136
	v_add_u32_e32 v137, 0x2c00, v137
	v_add_u32_e32 v138, 0x2c00, v138
	global_load_dwordx4 v[194:197], v136, s[14:15]
	global_load_dwordx4 v[198:201], v137, s[14:15]
	global_load_dwordx4 v[202:205], v138, s[14:15]
	v_add_u32_e32 v136, 0x2c00, v136
	v_add_u32_e32 v137, 0x2c00, v137
	v_add_u32_e32 v138, 0x2c00, v138
	global_load_dwordx4 v[80:83], v139, s[14:15]
	v_add_u32_e32 v139, 0x2c00, v139
	global_load_dwordx4 v[84:87], v139, s[14:15]
	v_add_u32_e32 v139, 0x2c00, v139
	global_load_dwordx4 v[88:91], v139, s[14:15]
	v_add_u32_e32 v139, 0x2c00, v139
	global_load_dwordx4 v[92:95], v139, s[14:15]
	v_add_u32_e32 v139, 0x2c00, v139
	s_waitcnt vmcnt(16)
	v_cndmask_b32_e64 v146, v146, 0, s[4:5]
	v_cndmask_b32_e64 v147, v147, 0, s[4:5]
	v_cndmask_b32_e64 v148, v148, 0, s[4:5]
	v_cndmask_b32_e64 v149, v149, 0, s[4:5]
	v_cndmask_b32_e64 v150, v150, 0, s[4:5]
	v_cndmask_b32_e64 v151, v151, 0, s[4:5]
	v_cndmask_b32_e64 v152, v152, 0, s[4:5]
	v_cndmask_b32_e64 v153, v153, 0, s[4:5]
	v_cndmask_b32_e64 v154, v154, 0, s[4:5]
	v_cndmask_b32_e64 v155, v155, 0, s[4:5]
	v_cndmask_b32_e64 v156, v156, 0, s[4:5]
	v_cndmask_b32_e64 v157, v157, 0, s[4:5]
	global_load_dwordx4 v[206:209], v136, s[14:15]
	global_load_dwordx4 v[210:213], v137, s[14:15]
	global_load_dwordx4 v[214:217], v138, s[14:15]
	v_add_u32_e32 v136, 0x2c00, v136
	v_add_u32_e32 v137, 0x2c00, v137
	v_add_u32_e32 v138, 0x2c00, v138
	global_load_dwordx4 v[96:99], v139, s[14:15]
	v_add_u32_e32 v139, 0x2c00, v139
	s_waitcnt vmcnt(14)
	s_waitcnt vmcnt(7)
	v_mov_b64_e32 v[104:105], v[72:73]
	v_mov_b64_e32 v[106:107], v[74:75]
	v_mov_b64_e32 v[108:109], v[76:77]
	v_mov_b64_e32 v[110:111], v[78:79]
	v_lshlrev_b32_e32 v112, 16, v146
	v_and_b32_e32 v113, 0xffff0000, v146
	v_pk_fma_f32 v[104:105], v[112:113], v[0:1], v[104:105]
	v_lshlrev_b32_e32 v114, 16, v147
	v_and_b32_e32 v115, 0xffff0000, v147
	v_pk_fma_f32 v[106:107], v[114:115], v[2:3], v[106:107]
	v_lshlrev_b32_e32 v112, 16, v148
	v_and_b32_e32 v113, 0xffff0000, v148
	v_pk_fma_f32 v[108:109], v[112:113], v[4:5], v[108:109]
	v_lshlrev_b32_e32 v114, 16, v149
	v_and_b32_e32 v115, 0xffff0000, v149
	v_pk_fma_f32 v[110:111], v[114:115], v[6:7], v[110:111]
	v_lshlrev_b32_e32 v112, 16, v158
	v_and_b32_e32 v113, 0xffff0000, v158
	v_pk_fma_f32 v[104:105], v[112:113], v[8:9], v[104:105]
	v_lshlrev_b32_e32 v114, 16, v159
	v_and_b32_e32 v115, 0xffff0000, v159
	v_pk_fma_f32 v[106:107], v[114:115], v[10:11], v[106:107]
	v_lshlrev_b32_e32 v112, 16, v160
	v_and_b32_e32 v113, 0xffff0000, v160
	v_pk_fma_f32 v[108:109], v[112:113], v[12:13], v[108:109]
	v_lshlrev_b32_e32 v114, 16, v161
	v_and_b32_e32 v115, 0xffff0000, v161
	v_pk_fma_f32 v[110:111], v[114:115], v[14:15], v[110:111]
	v_lshlrev_b32_e32 v112, 16, v170
	v_and_b32_e32 v113, 0xffff0000, v170
	v_pk_fma_f32 v[104:105], v[112:113], v[16:17], v[104:105]
	v_lshlrev_b32_e32 v114, 16, v171
	v_and_b32_e32 v115, 0xffff0000, v171
	v_pk_fma_f32 v[106:107], v[114:115], v[18:19], v[106:107]
	v_lshlrev_b32_e32 v112, 16, v172
	v_and_b32_e32 v113, 0xffff0000, v172
	v_pk_fma_f32 v[108:109], v[112:113], v[20:21], v[108:109]
	v_lshlrev_b32_e32 v114, 16, v173
	v_and_b32_e32 v115, 0xffff0000, v173
	v_pk_fma_f32 v[110:111], v[114:115], v[22:23], v[110:111]
	v_lshlrev_b32_e32 v112, 16, v150
	v_and_b32_e32 v113, 0xffff0000, v150
	v_pk_fma_f32 v[104:105], v[112:113], v[24:25], v[104:105]
	v_lshlrev_b32_e32 v114, 16, v151
	v_and_b32_e32 v115, 0xffff0000, v151
	v_pk_fma_f32 v[106:107], v[114:115], v[26:27], v[106:107]
	v_lshlrev_b32_e32 v112, 16, v152
	v_and_b32_e32 v113, 0xffff0000, v152
	v_pk_fma_f32 v[108:109], v[112:113], v[28:29], v[108:109]
	v_lshlrev_b32_e32 v114, 16, v153
	v_and_b32_e32 v115, 0xffff0000, v153
	v_pk_fma_f32 v[110:111], v[114:115], v[30:31], v[110:111]
	v_lshlrev_b32_e32 v112, 16, v162
	v_and_b32_e32 v113, 0xffff0000, v162
	v_pk_fma_f32 v[104:105], v[112:113], v[32:33], v[104:105]
	v_lshlrev_b32_e32 v114, 16, v163
	v_and_b32_e32 v115, 0xffff0000, v163
	v_pk_fma_f32 v[106:107], v[114:115], v[34:35], v[106:107]
	v_lshlrev_b32_e32 v112, 16, v164
	v_and_b32_e32 v113, 0xffff0000, v164
	v_pk_fma_f32 v[108:109], v[112:113], v[36:37], v[108:109]
	v_lshlrev_b32_e32 v114, 16, v165
	v_and_b32_e32 v115, 0xffff0000, v165
	v_pk_fma_f32 v[110:111], v[114:115], v[38:39], v[110:111]
	v_lshlrev_b32_e32 v112, 16, v174
	v_and_b32_e32 v113, 0xffff0000, v174
	v_pk_fma_f32 v[104:105], v[112:113], v[40:41], v[104:105]
	v_lshlrev_b32_e32 v114, 16, v175
	v_and_b32_e32 v115, 0xffff0000, v175
	v_pk_fma_f32 v[106:107], v[114:115], v[42:43], v[106:107]
	v_lshlrev_b32_e32 v112, 16, v176
	v_and_b32_e32 v113, 0xffff0000, v176
	v_pk_fma_f32 v[108:109], v[112:113], v[44:45], v[108:109]
	v_lshlrev_b32_e32 v114, 16, v177
	v_and_b32_e32 v115, 0xffff0000, v177
	v_pk_fma_f32 v[110:111], v[114:115], v[46:47], v[110:111]
	v_lshlrev_b32_e32 v112, 16, v154
	v_and_b32_e32 v113, 0xffff0000, v154
	v_pk_fma_f32 v[104:105], v[112:113], v[48:49], v[104:105]
	v_lshlrev_b32_e32 v114, 16, v155
	v_and_b32_e32 v115, 0xffff0000, v155
	v_pk_fma_f32 v[106:107], v[114:115], v[50:51], v[106:107]
	v_lshlrev_b32_e32 v112, 16, v156
	v_and_b32_e32 v113, 0xffff0000, v156
	v_pk_fma_f32 v[108:109], v[112:113], v[52:53], v[108:109]
	v_lshlrev_b32_e32 v114, 16, v157
	v_and_b32_e32 v115, 0xffff0000, v157
	v_pk_fma_f32 v[110:111], v[114:115], v[54:55], v[110:111]
	v_lshlrev_b32_e32 v112, 16, v166
	v_and_b32_e32 v113, 0xffff0000, v166
	v_pk_fma_f32 v[104:105], v[112:113], v[56:57], v[104:105]
	v_lshlrev_b32_e32 v114, 16, v167
	v_and_b32_e32 v115, 0xffff0000, v167
	v_pk_fma_f32 v[106:107], v[114:115], v[58:59], v[106:107]
	v_lshlrev_b32_e32 v112, 16, v168
	v_and_b32_e32 v113, 0xffff0000, v168
	v_pk_fma_f32 v[108:109], v[112:113], v[60:61], v[108:109]
	v_lshlrev_b32_e32 v114, 16, v169
	v_and_b32_e32 v115, 0xffff0000, v169
	v_pk_fma_f32 v[110:111], v[114:115], v[62:63], v[110:111]
	v_lshlrev_b32_e32 v112, 16, v178
	v_and_b32_e32 v113, 0xffff0000, v178
	v_pk_fma_f32 v[104:105], v[112:113], v[64:65], v[104:105]
	v_lshlrev_b32_e32 v114, 16, v179
	v_and_b32_e32 v115, 0xffff0000, v179
	v_pk_fma_f32 v[106:107], v[114:115], v[66:67], v[106:107]
	v_lshlrev_b32_e32 v112, 16, v180
	v_and_b32_e32 v113, 0xffff0000, v180
	v_pk_fma_f32 v[108:109], v[112:113], v[68:69], v[108:109]
	v_lshlrev_b32_e32 v114, 16, v181
	v_and_b32_e32 v115, 0xffff0000, v181
	v_pk_fma_f32 v[110:111], v[114:115], v[70:71], v[110:111]
	v_mov_b64_e32 v[132:133], s[28:29]
	v_and_b32_e32 v116, 0x7fffffff, v104
	v_and_b32_e32 v117, 0x7fffffff, v105
	v_pk_fma_f32 v[116:117], v[116:117], s[24:25], 1.0 op_sel_hi:[1,0,0]
	v_pk_mul_f32 v[218:219], v[104:105], v[104:105]
	v_rcp_f32_e32 v116, v116
	v_rcp_f32_e32 v117, v117
	v_pk_mul_f32 v[218:219], v[218:219], s[38:39] op_sel_hi:[1,0]
	v_and_b32_e32 v118, 0x7fffffff, v106
	v_and_b32_e32 v119, 0x7fffffff, v107
	v_pk_fma_f32 v[118:119], v[118:119], s[24:25], 1.0 op_sel_hi:[1,0,0]
	v_pk_mul_f32 v[220:221], v[106:107], v[106:107]
	v_rcp_f32_e32 v118, v118
	v_rcp_f32_e32 v119, v119
	v_pk_mul_f32 v[220:221], v[220:221], s[38:39] op_sel_hi:[1,0]
	v_and_b32_e32 v120, 0x7fffffff, v108
	v_and_b32_e32 v121, 0x7fffffff, v109
	v_pk_fma_f32 v[120:121], v[120:121], s[24:25], 1.0 op_sel_hi:[1,0,0]
	v_pk_mul_f32 v[222:223], v[108:109], v[108:109]
	v_rcp_f32_e32 v120, v120
	v_rcp_f32_e32 v121, v121
	v_pk_mul_f32 v[222:223], v[222:223], s[38:39] op_sel_hi:[1,0]
	v_and_b32_e32 v122, 0x7fffffff, v110
	v_and_b32_e32 v123, 0x7fffffff, v111
	v_pk_fma_f32 v[122:123], v[122:123], s[24:25], 1.0 op_sel_hi:[1,0,0]
	v_pk_mul_f32 v[224:225], v[110:111], v[110:111]
	v_rcp_f32_e32 v122, v122
	v_rcp_f32_e32 v123, v123
	v_pk_mul_f32 v[224:225], v[224:225], s[38:39] op_sel_hi:[1,0]
	v_pk_fma_f32 v[124:125], v[116:117], s[26:27], v[132:133] op_sel_hi:[1,0,0]
	v_exp_f32_e32 v218, v218
	v_pk_fma_f32 v[124:125], v[116:117], v[124:125], s[30:31] op_sel_hi:[1,1,0]
	v_exp_f32_e32 v219, v219
	v_pk_fma_f32 v[124:125], v[116:117], v[124:125], s[34:35] op_sel_hi:[1,1,0]
	v_pk_fma_f32 v[124:125], v[116:117], v[124:125], s[36:37] op_sel_hi:[1,1,0]
	v_pk_mul_f32 v[124:125], v[116:117], v[124:125]
	v_pk_fma_f32 v[126:127], v[118:119], s[26:27], v[132:133] op_sel_hi:[1,0,0]
	v_exp_f32_e32 v220, v220
	v_pk_fma_f32 v[126:127], v[118:119], v[126:127], s[30:31] op_sel_hi:[1,1,0]
	v_exp_f32_e32 v221, v221
	v_pk_fma_f32 v[126:127], v[118:119], v[126:127], s[34:35] op_sel_hi:[1,1,0]
	v_pk_fma_f32 v[126:127], v[118:119], v[126:127], s[36:37] op_sel_hi:[1,1,0]
	v_pk_mul_f32 v[126:127], v[118:119], v[126:127]
	v_pk_fma_f32 v[128:129], v[120:121], s[26:27], v[132:133] op_sel_hi:[1,0,0]
	v_exp_f32_e32 v222, v222
	v_pk_fma_f32 v[128:129], v[120:121], v[128:129], s[30:31] op_sel_hi:[1,1,0]
	v_exp_f32_e32 v223, v223
	v_pk_fma_f32 v[128:129], v[120:121], v[128:129], s[34:35] op_sel_hi:[1,1,0]
	v_pk_fma_f32 v[128:129], v[120:121], v[128:129], s[36:37] op_sel_hi:[1,1,0]
	v_pk_mul_f32 v[128:129], v[120:121], v[128:129]
	v_pk_fma_f32 v[130:131], v[122:123], s[26:27], v[132:133] op_sel_hi:[1,0,0]
	v_exp_f32_e32 v224, v224
	v_pk_fma_f32 v[130:131], v[122:123], v[130:131], s[30:31] op_sel_hi:[1,1,0]
	v_exp_f32_e32 v225, v225
	v_pk_fma_f32 v[130:131], v[122:123], v[130:131], s[34:35] op_sel_hi:[1,1,0]
	v_pk_fma_f32 v[130:131], v[122:123], v[130:131], s[36:37] op_sel_hi:[1,1,0]
	v_pk_mul_f32 v[130:131], v[122:123], v[130:131]
	v_pk_mul_f32 v[124:125], v[218:219], v[124:125]
	v_pk_mul_f32 v[218:219], v[104:105], v[124:125]
	v_pk_fma_f32 v[124:125], v[104:105], v[124:125], v[104:105] neg_lo:[1,0,0] neg_hi:[1,0,0]
	v_cmp_gt_f32_e64 s[8:9], 0, v104
	v_cmp_gt_f32_e64 s[22:23], 0, v105
	v_lshlrev_b32_e32 v112, 16, v80
	v_and_b32_e32 v113, 0xffff0000, v80
	v_cndmask_b32_e64 v104, v124, v218, s[8:9]
	v_cndmask_b32_e64 v105, v125, v219, s[22:23]
	v_pk_mul_f32 v[104:105], v[104:105], v[112:113]
	v_cvt_pk_bf16_f32 v226, v104, v105
	v_pk_mul_f32 v[126:127], v[220:221], v[126:127]
	v_pk_mul_f32 v[220:221], v[106:107], v[126:127]
	v_pk_fma_f32 v[126:127], v[106:107], v[126:127], v[106:107] neg_lo:[1,0,0] neg_hi:[1,0,0]
	v_cmp_gt_f32_e64 s[8:9], 0, v106
	v_cmp_gt_f32_e64 s[22:23], 0, v107
	v_lshlrev_b32_e32 v112, 16, v81
	v_and_b32_e32 v113, 0xffff0000, v81
	v_cndmask_b32_e64 v106, v126, v220, s[8:9]
	v_cndmask_b32_e64 v107, v127, v221, s[22:23]
	v_pk_mul_f32 v[106:107], v[106:107], v[112:113]
	v_cvt_pk_bf16_f32 v227, v106, v107
	v_pk_mul_f32 v[128:129], v[222:223], v[128:129]
	v_pk_mul_f32 v[222:223], v[108:109], v[128:129]
	v_pk_fma_f32 v[128:129], v[108:109], v[128:129], v[108:109] neg_lo:[1,0,0] neg_hi:[1,0,0]
	v_cmp_gt_f32_e64 s[8:9], 0, v108
	v_cmp_gt_f32_e64 s[22:23], 0, v109
	v_lshlrev_b32_e32 v112, 16, v82
	v_and_b32_e32 v113, 0xffff0000, v82
	v_cndmask_b32_e64 v108, v128, v222, s[8:9]
	v_cndmask_b32_e64 v109, v129, v223, s[22:23]
	v_pk_mul_f32 v[108:109], v[108:109], v[112:113]
	v_cvt_pk_bf16_f32 v228, v108, v109
	v_pk_mul_f32 v[130:131], v[224:225], v[130:131]
	v_pk_mul_f32 v[224:225], v[110:111], v[130:131]
	v_pk_fma_f32 v[130:131], v[110:111], v[130:131], v[110:111] neg_lo:[1,0,0] neg_hi:[1,0,0]
	v_cmp_gt_f32_e64 s[8:9], 0, v110
	v_cmp_gt_f32_e64 s[22:23], 0, v111
	v_lshlrev_b32_e32 v112, 16, v83
	v_and_b32_e32 v113, 0xffff0000, v83
	v_cndmask_b32_e64 v110, v130, v224, s[8:9]
	v_cndmask_b32_e64 v111, v131, v225, s[22:23]
	v_pk_mul_f32 v[110:111], v[110:111], v[112:113]
	v_cvt_pk_bf16_f32 v229, v110, v111
	global_store_dwordx4 v140, v[226:229], s[14:15]
	v_add_u32_e32 v140, 0x2c00, v140
	global_load_dwordx4 v[146:149], v136, s[14:15]
	global_load_dwordx4 v[150:153], v137, s[14:15]
	global_load_dwordx4 v[154:157], v138, s[14:15]
	v_add_u32_e32 v136, 0x2c00, v136
	v_add_u32_e32 v137, 0x2c00, v137
	v_add_u32_e32 v138, 0x2c00, v138
	global_load_dwordx4 v[100:103], v139, s[14:15]
	v_add_u32_e32 v139, 0x2c00, v139
	s_waitcnt vmcnt(11)
	v_mov_b64_e32 v[104:105], v[72:73]
	v_mov_b64_e32 v[106:107], v[74:75]
	v_mov_b64_e32 v[108:109], v[76:77]
	v_mov_b64_e32 v[110:111], v[78:79]
	v_lshlrev_b32_e32 v112, 16, v158
	v_and_b32_e32 v113, 0xffff0000, v158
	v_pk_fma_f32 v[104:105], v[112:113], v[0:1], v[104:105]
	v_lshlrev_b32_e32 v114, 16, v159
	v_and_b32_e32 v115, 0xffff0000, v159
	v_pk_fma_f32 v[106:107], v[114:115], v[2:3], v[106:107]
	v_lshlrev_b32_e32 v112, 16, v160
	v_and_b32_e32 v113, 0xffff0000, v160
	v_pk_fma_f32 v[108:109], v[112:113], v[4:5], v[108:109]
	v_lshlrev_b32_e32 v114, 16, v161
	v_and_b32_e32 v115, 0xffff0000, v161
	v_pk_fma_f32 v[110:111], v[114:115], v[6:7], v[110:111]
	v_lshlrev_b32_e32 v112, 16, v170
	v_and_b32_e32 v113, 0xffff0000, v170
	v_pk_fma_f32 v[104:105], v[112:113], v[8:9], v[104:105]
	v_lshlrev_b32_e32 v114, 16, v171
	v_and_b32_e32 v115, 0xffff0000, v171
	v_pk_fma_f32 v[106:107], v[114:115], v[10:11], v[106:107]
	v_lshlrev_b32_e32 v112, 16, v172
	v_and_b32_e32 v113, 0xffff0000, v172
	v_pk_fma_f32 v[108:109], v[112:113], v[12:13], v[108:109]
	v_lshlrev_b32_e32 v114, 16, v173
	v_and_b32_e32 v115, 0xffff0000, v173
	v_pk_fma_f32 v[110:111], v[114:115], v[14:15], v[110:111]
	v_lshlrev_b32_e32 v112, 16, v182
	v_and_b32_e32 v113, 0xffff0000, v182
	v_pk_fma_f32 v[104:105], v[112:113], v[16:17], v[104:105]
	v_lshlrev_b32_e32 v114, 16, v183
	v_and_b32_e32 v115, 0xffff0000, v183
	v_pk_fma_f32 v[106:107], v[114:115], v[18:19], v[106:107]
	v_lshlrev_b32_e32 v112, 16, v184
	v_and_b32_e32 v113, 0xffff0000, v184
	v_pk_fma_f32 v[108:109], v[112:113], v[20:21], v[108:109]
	v_lshlrev_b32_e32 v114, 16, v185
	v_and_b32_e32 v115, 0xffff0000, v185
	v_pk_fma_f32 v[110:111], v[114:115], v[22:23], v[110:111]
	v_lshlrev_b32_e32 v112, 16, v162
	v_and_b32_e32 v113, 0xffff0000, v162
	v_pk_fma_f32 v[104:105], v[112:113], v[24:25], v[104:105]
	v_lshlrev_b32_e32 v114, 16, v163
	v_and_b32_e32 v115, 0xffff0000, v163
	v_pk_fma_f32 v[106:107], v[114:115], v[26:27], v[106:107]
	v_lshlrev_b32_e32 v112, 16, v164
	v_and_b32_e32 v113, 0xffff0000, v164
	v_pk_fma_f32 v[108:109], v[112:113], v[28:29], v[108:109]
	v_lshlrev_b32_e32 v114, 16, v165
	v_and_b32_e32 v115, 0xffff0000, v165
	v_pk_fma_f32 v[110:111], v[114:115], v[30:31], v[110:111]
	v_lshlrev_b32_e32 v112, 16, v174
	v_and_b32_e32 v113, 0xffff0000, v174
	v_pk_fma_f32 v[104:105], v[112:113], v[32:33], v[104:105]
	v_lshlrev_b32_e32 v114, 16, v175
	v_and_b32_e32 v115, 0xffff0000, v175
	v_pk_fma_f32 v[106:107], v[114:115], v[34:35], v[106:107]
	v_lshlrev_b32_e32 v112, 16, v176
	v_and_b32_e32 v113, 0xffff0000, v176
	v_pk_fma_f32 v[108:109], v[112:113], v[36:37], v[108:109]
	v_lshlrev_b32_e32 v114, 16, v177
	v_and_b32_e32 v115, 0xffff0000, v177
	v_pk_fma_f32 v[110:111], v[114:115], v[38:39], v[110:111]
	v_lshlrev_b32_e32 v112, 16, v186
	v_and_b32_e32 v113, 0xffff0000, v186
	v_pk_fma_f32 v[104:105], v[112:113], v[40:41], v[104:105]
	v_lshlrev_b32_e32 v114, 16, v187
	v_and_b32_e32 v115, 0xffff0000, v187
	v_pk_fma_f32 v[106:107], v[114:115], v[42:43], v[106:107]
	v_lshlrev_b32_e32 v112, 16, v188
	v_and_b32_e32 v113, 0xffff0000, v188
	v_pk_fma_f32 v[108:109], v[112:113], v[44:45], v[108:109]
	v_lshlrev_b32_e32 v114, 16, v189
	v_and_b32_e32 v115, 0xffff0000, v189
	v_pk_fma_f32 v[110:111], v[114:115], v[46:47], v[110:111]
	v_lshlrev_b32_e32 v112, 16, v166
	v_and_b32_e32 v113, 0xffff0000, v166
	v_pk_fma_f32 v[104:105], v[112:113], v[48:49], v[104:105]
	v_lshlrev_b32_e32 v114, 16, v167
	v_and_b32_e32 v115, 0xffff0000, v167
	v_pk_fma_f32 v[106:107], v[114:115], v[50:51], v[106:107]
	v_lshlrev_b32_e32 v112, 16, v168
	v_and_b32_e32 v113, 0xffff0000, v168
	v_pk_fma_f32 v[108:109], v[112:113], v[52:53], v[108:109]
	v_lshlrev_b32_e32 v114, 16, v169
	v_and_b32_e32 v115, 0xffff0000, v169
	v_pk_fma_f32 v[110:111], v[114:115], v[54:55], v[110:111]
	v_lshlrev_b32_e32 v112, 16, v178
	v_and_b32_e32 v113, 0xffff0000, v178
	v_pk_fma_f32 v[104:105], v[112:113], v[56:57], v[104:105]
	v_lshlrev_b32_e32 v114, 16, v179
	v_and_b32_e32 v115, 0xffff0000, v179
	v_pk_fma_f32 v[106:107], v[114:115], v[58:59], v[106:107]
	v_lshlrev_b32_e32 v112, 16, v180
	v_and_b32_e32 v113, 0xffff0000, v180
	v_pk_fma_f32 v[108:109], v[112:113], v[60:61], v[108:109]
	v_lshlrev_b32_e32 v114, 16, v181
	v_and_b32_e32 v115, 0xffff0000, v181
	v_pk_fma_f32 v[110:111], v[114:115], v[62:63], v[110:111]
	v_lshlrev_b32_e32 v112, 16, v190
	v_and_b32_e32 v113, 0xffff0000, v190
	v_pk_fma_f32 v[104:105], v[112:113], v[64:65], v[104:105]
	v_lshlrev_b32_e32 v114, 16, v191
	v_and_b32_e32 v115, 0xffff0000, v191
	v_pk_fma_f32 v[106:107], v[114:115], v[66:67], v[106:107]
	v_lshlrev_b32_e32 v112, 16, v192
	v_and_b32_e32 v113, 0xffff0000, v192
	v_pk_fma_f32 v[108:109], v[112:113], v[68:69], v[108:109]
	v_lshlrev_b32_e32 v114, 16, v193
	v_and_b32_e32 v115, 0xffff0000, v193
	v_pk_fma_f32 v[110:111], v[114:115], v[70:71], v[110:111]
	v_mov_b64_e32 v[132:133], s[28:29]
	v_and_b32_e32 v116, 0x7fffffff, v104
	v_and_b32_e32 v117, 0x7fffffff, v105
	v_pk_fma_f32 v[116:117], v[116:117], s[24:25], 1.0 op_sel_hi:[1,0,0]
	v_pk_mul_f32 v[218:219], v[104:105], v[104:105]
	v_rcp_f32_e32 v116, v116
	v_rcp_f32_e32 v117, v117
	v_pk_mul_f32 v[218:219], v[218:219], s[38:39] op_sel_hi:[1,0]
	v_and_b32_e32 v118, 0x7fffffff, v106
	v_and_b32_e32 v119, 0x7fffffff, v107
	v_pk_fma_f32 v[118:119], v[118:119], s[24:25], 1.0 op_sel_hi:[1,0,0]
	v_pk_mul_f32 v[220:221], v[106:107], v[106:107]
	v_rcp_f32_e32 v118, v118
	v_rcp_f32_e32 v119, v119
	v_pk_mul_f32 v[220:221], v[220:221], s[38:39] op_sel_hi:[1,0]
	v_and_b32_e32 v120, 0x7fffffff, v108
	v_and_b32_e32 v121, 0x7fffffff, v109
	v_pk_fma_f32 v[120:121], v[120:121], s[24:25], 1.0 op_sel_hi:[1,0,0]
	v_pk_mul_f32 v[222:223], v[108:109], v[108:109]
	v_rcp_f32_e32 v120, v120
	v_rcp_f32_e32 v121, v121
	v_pk_mul_f32 v[222:223], v[222:223], s[38:39] op_sel_hi:[1,0]
	v_and_b32_e32 v122, 0x7fffffff, v110
	v_and_b32_e32 v123, 0x7fffffff, v111
	v_pk_fma_f32 v[122:123], v[122:123], s[24:25], 1.0 op_sel_hi:[1,0,0]
	v_pk_mul_f32 v[224:225], v[110:111], v[110:111]
	v_rcp_f32_e32 v122, v122
	v_rcp_f32_e32 v123, v123
	v_pk_mul_f32 v[224:225], v[224:225], s[38:39] op_sel_hi:[1,0]
	v_pk_fma_f32 v[124:125], v[116:117], s[26:27], v[132:133] op_sel_hi:[1,0,0]
	v_exp_f32_e32 v218, v218
	v_pk_fma_f32 v[124:125], v[116:117], v[124:125], s[30:31] op_sel_hi:[1,1,0]
	v_exp_f32_e32 v219, v219
	v_pk_fma_f32 v[124:125], v[116:117], v[124:125], s[34:35] op_sel_hi:[1,1,0]
	v_pk_fma_f32 v[124:125], v[116:117], v[124:125], s[36:37] op_sel_hi:[1,1,0]
	v_pk_mul_f32 v[124:125], v[116:117], v[124:125]
	v_pk_fma_f32 v[126:127], v[118:119], s[26:27], v[132:133] op_sel_hi:[1,0,0]
	v_exp_f32_e32 v220, v220
	v_pk_fma_f32 v[126:127], v[118:119], v[126:127], s[30:31] op_sel_hi:[1,1,0]
	v_exp_f32_e32 v221, v221
	v_pk_fma_f32 v[126:127], v[118:119], v[126:127], s[34:35] op_sel_hi:[1,1,0]
	v_pk_fma_f32 v[126:127], v[118:119], v[126:127], s[36:37] op_sel_hi:[1,1,0]
	v_pk_mul_f32 v[126:127], v[118:119], v[126:127]
	v_pk_fma_f32 v[128:129], v[120:121], s[26:27], v[132:133] op_sel_hi:[1,0,0]
	v_exp_f32_e32 v222, v222
	v_pk_fma_f32 v[128:129], v[120:121], v[128:129], s[30:31] op_sel_hi:[1,1,0]
	v_exp_f32_e32 v223, v223
	v_pk_fma_f32 v[128:129], v[120:121], v[128:129], s[34:35] op_sel_hi:[1,1,0]
	v_pk_fma_f32 v[128:129], v[120:121], v[128:129], s[36:37] op_sel_hi:[1,1,0]
	v_pk_mul_f32 v[128:129], v[120:121], v[128:129]
	v_pk_fma_f32 v[130:131], v[122:123], s[26:27], v[132:133] op_sel_hi:[1,0,0]
	v_exp_f32_e32 v224, v224
	v_pk_fma_f32 v[130:131], v[122:123], v[130:131], s[30:31] op_sel_hi:[1,1,0]
	v_exp_f32_e32 v225, v225
	v_pk_fma_f32 v[130:131], v[122:123], v[130:131], s[34:35] op_sel_hi:[1,1,0]
	v_pk_fma_f32 v[130:131], v[122:123], v[130:131], s[36:37] op_sel_hi:[1,1,0]
	v_pk_mul_f32 v[130:131], v[122:123], v[130:131]
	v_pk_mul_f32 v[124:125], v[218:219], v[124:125]
	v_pk_mul_f32 v[218:219], v[104:105], v[124:125]
	v_pk_fma_f32 v[124:125], v[104:105], v[124:125], v[104:105] neg_lo:[1,0,0] neg_hi:[1,0,0]
	v_cmp_gt_f32_e64 s[8:9], 0, v104
	v_cmp_gt_f32_e64 s[22:23], 0, v105
	v_lshlrev_b32_e32 v112, 16, v84
	v_and_b32_e32 v113, 0xffff0000, v84
	v_cndmask_b32_e64 v104, v124, v218, s[8:9]
	v_cndmask_b32_e64 v105, v125, v219, s[22:23]
	v_pk_mul_f32 v[104:105], v[104:105], v[112:113]
	v_cvt_pk_bf16_f32 v226, v104, v105
	v_pk_mul_f32 v[126:127], v[220:221], v[126:127]
	v_pk_mul_f32 v[220:221], v[106:107], v[126:127]
	v_pk_fma_f32 v[126:127], v[106:107], v[126:127], v[106:107] neg_lo:[1,0,0] neg_hi:[1,0,0]
	v_cmp_gt_f32_e64 s[8:9], 0, v106
	v_cmp_gt_f32_e64 s[22:23], 0, v107
	v_lshlrev_b32_e32 v112, 16, v85
	v_and_b32_e32 v113, 0xffff0000, v85
	v_cndmask_b32_e64 v106, v126, v220, s[8:9]
	v_cndmask_b32_e64 v107, v127, v221, s[22:23]
	v_pk_mul_f32 v[106:107], v[106:107], v[112:113]
	v_cvt_pk_bf16_f32 v227, v106, v107
	v_pk_mul_f32 v[128:129], v[222:223], v[128:129]
	v_pk_mul_f32 v[222:223], v[108:109], v[128:129]
	v_pk_fma_f32 v[128:129], v[108:109], v[128:129], v[108:109] neg_lo:[1,0,0] neg_hi:[1,0,0]
	v_cmp_gt_f32_e64 s[8:9], 0, v108
	v_cmp_gt_f32_e64 s[22:23], 0, v109
	v_lshlrev_b32_e32 v112, 16, v86
	v_and_b32_e32 v113, 0xffff0000, v86
	v_cndmask_b32_e64 v108, v128, v222, s[8:9]
	v_cndmask_b32_e64 v109, v129, v223, s[22:23]
	v_pk_mul_f32 v[108:109], v[108:109], v[112:113]
	v_cvt_pk_bf16_f32 v228, v108, v109
	v_pk_mul_f32 v[130:131], v[224:225], v[130:131]
	v_pk_mul_f32 v[224:225], v[110:111], v[130:131]
	v_pk_fma_f32 v[130:131], v[110:111], v[130:131], v[110:111] neg_lo:[1,0,0] neg_hi:[1,0,0]
	v_cmp_gt_f32_e64 s[8:9], 0, v110
	v_cmp_gt_f32_e64 s[22:23], 0, v111
	v_lshlrev_b32_e32 v112, 16, v87
	v_and_b32_e32 v113, 0xffff0000, v87
	v_cndmask_b32_e64 v110, v130, v224, s[8:9]
	v_cndmask_b32_e64 v111, v131, v225, s[22:23]
	v_pk_mul_f32 v[110:111], v[110:111], v[112:113]
	v_cvt_pk_bf16_f32 v229, v110, v111
	global_store_dwordx4 v140, v[226:229], s[14:15]
	v_add_u32_e32 v140, 0x2c00, v140
	global_load_dwordx4 v[158:161], v136, s[14:15]
	global_load_dwordx4 v[162:165], v137, s[14:15]
	global_load_dwordx4 v[166:169], v138, s[14:15]
	v_add_u32_e32 v136, 0x2c00, v136
	v_add_u32_e32 v137, 0x2c00, v137
	v_add_u32_e32 v138, 0x2c00, v138
	global_load_dwordx4 v[80:83], v139, s[14:15]
	v_add_u32_e32 v139, 0x2c00, v139
	s_waitcnt vmcnt(15)
	v_mov_b64_e32 v[104:105], v[72:73]
	v_mov_b64_e32 v[106:107], v[74:75]
	v_mov_b64_e32 v[108:109], v[76:77]
	v_mov_b64_e32 v[110:111], v[78:79]
	v_lshlrev_b32_e32 v112, 16, v170
	v_and_b32_e32 v113, 0xffff0000, v170
	v_pk_fma_f32 v[104:105], v[112:113], v[0:1], v[104:105]
	v_lshlrev_b32_e32 v114, 16, v171
	v_and_b32_e32 v115, 0xffff0000, v171
	v_pk_fma_f32 v[106:107], v[114:115], v[2:3], v[106:107]
	v_lshlrev_b32_e32 v112, 16, v172
	v_and_b32_e32 v113, 0xffff0000, v172
	v_pk_fma_f32 v[108:109], v[112:113], v[4:5], v[108:109]
	v_lshlrev_b32_e32 v114, 16, v173
	v_and_b32_e32 v115, 0xffff0000, v173
	v_pk_fma_f32 v[110:111], v[114:115], v[6:7], v[110:111]
	v_lshlrev_b32_e32 v112, 16, v182
	v_and_b32_e32 v113, 0xffff0000, v182
	v_pk_fma_f32 v[104:105], v[112:113], v[8:9], v[104:105]
	v_lshlrev_b32_e32 v114, 16, v183
	v_and_b32_e32 v115, 0xffff0000, v183
	v_pk_fma_f32 v[106:107], v[114:115], v[10:11], v[106:107]
	v_lshlrev_b32_e32 v112, 16, v184
	v_and_b32_e32 v113, 0xffff0000, v184
	v_pk_fma_f32 v[108:109], v[112:113], v[12:13], v[108:109]
	v_lshlrev_b32_e32 v114, 16, v185
	v_and_b32_e32 v115, 0xffff0000, v185
	v_pk_fma_f32 v[110:111], v[114:115], v[14:15], v[110:111]
	v_lshlrev_b32_e32 v112, 16, v194
	v_and_b32_e32 v113, 0xffff0000, v194
	v_pk_fma_f32 v[104:105], v[112:113], v[16:17], v[104:105]
	v_lshlrev_b32_e32 v114, 16, v195
	v_and_b32_e32 v115, 0xffff0000, v195
	v_pk_fma_f32 v[106:107], v[114:115], v[18:19], v[106:107]
	v_lshlrev_b32_e32 v112, 16, v196
	v_and_b32_e32 v113, 0xffff0000, v196
	v_pk_fma_f32 v[108:109], v[112:113], v[20:21], v[108:109]
	v_lshlrev_b32_e32 v114, 16, v197
	v_and_b32_e32 v115, 0xffff0000, v197
	v_pk_fma_f32 v[110:111], v[114:115], v[22:23], v[110:111]
	v_lshlrev_b32_e32 v112, 16, v174
	v_and_b32_e32 v113, 0xffff0000, v174
	v_pk_fma_f32 v[104:105], v[112:113], v[24:25], v[104:105]
	v_lshlrev_b32_e32 v114, 16, v175
	v_and_b32_e32 v115, 0xffff0000, v175
	v_pk_fma_f32 v[106:107], v[114:115], v[26:27], v[106:107]
	v_lshlrev_b32_e32 v112, 16, v176
	v_and_b32_e32 v113, 0xffff0000, v176
	v_pk_fma_f32 v[108:109], v[112:113], v[28:29], v[108:109]
	v_lshlrev_b32_e32 v114, 16, v177
	v_and_b32_e32 v115, 0xffff0000, v177
	v_pk_fma_f32 v[110:111], v[114:115], v[30:31], v[110:111]
	v_lshlrev_b32_e32 v112, 16, v186
	v_and_b32_e32 v113, 0xffff0000, v186
	v_pk_fma_f32 v[104:105], v[112:113], v[32:33], v[104:105]
	v_lshlrev_b32_e32 v114, 16, v187
	v_and_b32_e32 v115, 0xffff0000, v187
	v_pk_fma_f32 v[106:107], v[114:115], v[34:35], v[106:107]
	v_lshlrev_b32_e32 v112, 16, v188
	v_and_b32_e32 v113, 0xffff0000, v188
	v_pk_fma_f32 v[108:109], v[112:113], v[36:37], v[108:109]
	v_lshlrev_b32_e32 v114, 16, v189
	v_and_b32_e32 v115, 0xffff0000, v189
	v_pk_fma_f32 v[110:111], v[114:115], v[38:39], v[110:111]
	v_lshlrev_b32_e32 v112, 16, v198
	v_and_b32_e32 v113, 0xffff0000, v198
	v_pk_fma_f32 v[104:105], v[112:113], v[40:41], v[104:105]
	v_lshlrev_b32_e32 v114, 16, v199
	v_and_b32_e32 v115, 0xffff0000, v199
	v_pk_fma_f32 v[106:107], v[114:115], v[42:43], v[106:107]
	v_lshlrev_b32_e32 v112, 16, v200
	v_and_b32_e32 v113, 0xffff0000, v200
	v_pk_fma_f32 v[108:109], v[112:113], v[44:45], v[108:109]
	v_lshlrev_b32_e32 v114, 16, v201
	v_and_b32_e32 v115, 0xffff0000, v201
	v_pk_fma_f32 v[110:111], v[114:115], v[46:47], v[110:111]
	v_lshlrev_b32_e32 v112, 16, v178
	v_and_b32_e32 v113, 0xffff0000, v178
	v_pk_fma_f32 v[104:105], v[112:113], v[48:49], v[104:105]
	v_lshlrev_b32_e32 v114, 16, v179
	v_and_b32_e32 v115, 0xffff0000, v179
	v_pk_fma_f32 v[106:107], v[114:115], v[50:51], v[106:107]
	v_lshlrev_b32_e32 v112, 16, v180
	v_and_b32_e32 v113, 0xffff0000, v180
	v_pk_fma_f32 v[108:109], v[112:113], v[52:53], v[108:109]
	v_lshlrev_b32_e32 v114, 16, v181
	v_and_b32_e32 v115, 0xffff0000, v181
	v_pk_fma_f32 v[110:111], v[114:115], v[54:55], v[110:111]
	v_lshlrev_b32_e32 v112, 16, v190
	v_and_b32_e32 v113, 0xffff0000, v190
	v_pk_fma_f32 v[104:105], v[112:113], v[56:57], v[104:105]
	v_lshlrev_b32_e32 v114, 16, v191
	v_and_b32_e32 v115, 0xffff0000, v191
	v_pk_fma_f32 v[106:107], v[114:115], v[58:59], v[106:107]
	v_lshlrev_b32_e32 v112, 16, v192
	v_and_b32_e32 v113, 0xffff0000, v192
	v_pk_fma_f32 v[108:109], v[112:113], v[60:61], v[108:109]
	v_lshlrev_b32_e32 v114, 16, v193
	v_and_b32_e32 v115, 0xffff0000, v193
	v_pk_fma_f32 v[110:111], v[114:115], v[62:63], v[110:111]
	v_lshlrev_b32_e32 v112, 16, v202
	v_and_b32_e32 v113, 0xffff0000, v202
	v_pk_fma_f32 v[104:105], v[112:113], v[64:65], v[104:105]
	v_lshlrev_b32_e32 v114, 16, v203
	v_and_b32_e32 v115, 0xffff0000, v203
	v_pk_fma_f32 v[106:107], v[114:115], v[66:67], v[106:107]
	v_lshlrev_b32_e32 v112, 16, v204
	v_and_b32_e32 v113, 0xffff0000, v204
	v_pk_fma_f32 v[108:109], v[112:113], v[68:69], v[108:109]
	v_lshlrev_b32_e32 v114, 16, v205
	v_and_b32_e32 v115, 0xffff0000, v205
	v_pk_fma_f32 v[110:111], v[114:115], v[70:71], v[110:111]
	v_mov_b64_e32 v[132:133], s[28:29]
	v_and_b32_e32 v116, 0x7fffffff, v104
	v_and_b32_e32 v117, 0x7fffffff, v105
	v_pk_fma_f32 v[116:117], v[116:117], s[24:25], 1.0 op_sel_hi:[1,0,0]
	v_pk_mul_f32 v[218:219], v[104:105], v[104:105]
	v_rcp_f32_e32 v116, v116
	v_rcp_f32_e32 v117, v117
	v_pk_mul_f32 v[218:219], v[218:219], s[38:39] op_sel_hi:[1,0]
	v_and_b32_e32 v118, 0x7fffffff, v106
	v_and_b32_e32 v119, 0x7fffffff, v107
	v_pk_fma_f32 v[118:119], v[118:119], s[24:25], 1.0 op_sel_hi:[1,0,0]
	v_pk_mul_f32 v[220:221], v[106:107], v[106:107]
	v_rcp_f32_e32 v118, v118
	v_rcp_f32_e32 v119, v119
	v_pk_mul_f32 v[220:221], v[220:221], s[38:39] op_sel_hi:[1,0]
	v_and_b32_e32 v120, 0x7fffffff, v108
	v_and_b32_e32 v121, 0x7fffffff, v109
	v_pk_fma_f32 v[120:121], v[120:121], s[24:25], 1.0 op_sel_hi:[1,0,0]
	v_pk_mul_f32 v[222:223], v[108:109], v[108:109]
	v_rcp_f32_e32 v120, v120
	v_rcp_f32_e32 v121, v121
	v_pk_mul_f32 v[222:223], v[222:223], s[38:39] op_sel_hi:[1,0]
	v_and_b32_e32 v122, 0x7fffffff, v110
	v_and_b32_e32 v123, 0x7fffffff, v111
	v_pk_fma_f32 v[122:123], v[122:123], s[24:25], 1.0 op_sel_hi:[1,0,0]
	v_pk_mul_f32 v[224:225], v[110:111], v[110:111]
	v_rcp_f32_e32 v122, v122
	v_rcp_f32_e32 v123, v123
	v_pk_mul_f32 v[224:225], v[224:225], s[38:39] op_sel_hi:[1,0]
	v_pk_fma_f32 v[124:125], v[116:117], s[26:27], v[132:133] op_sel_hi:[1,0,0]
	v_exp_f32_e32 v218, v218
	v_pk_fma_f32 v[124:125], v[116:117], v[124:125], s[30:31] op_sel_hi:[1,1,0]
	v_exp_f32_e32 v219, v219
	v_pk_fma_f32 v[124:125], v[116:117], v[124:125], s[34:35] op_sel_hi:[1,1,0]
	v_pk_fma_f32 v[124:125], v[116:117], v[124:125], s[36:37] op_sel_hi:[1,1,0]
	v_pk_mul_f32 v[124:125], v[116:117], v[124:125]
	v_pk_fma_f32 v[126:127], v[118:119], s[26:27], v[132:133] op_sel_hi:[1,0,0]
	v_exp_f32_e32 v220, v220
	v_pk_fma_f32 v[126:127], v[118:119], v[126:127], s[30:31] op_sel_hi:[1,1,0]
	v_exp_f32_e32 v221, v221
	v_pk_fma_f32 v[126:127], v[118:119], v[126:127], s[34:35] op_sel_hi:[1,1,0]
	v_pk_fma_f32 v[126:127], v[118:119], v[126:127], s[36:37] op_sel_hi:[1,1,0]
	v_pk_mul_f32 v[126:127], v[118:119], v[126:127]
	v_pk_fma_f32 v[128:129], v[120:121], s[26:27], v[132:133] op_sel_hi:[1,0,0]
	v_exp_f32_e32 v222, v222
	v_pk_fma_f32 v[128:129], v[120:121], v[128:129], s[30:31] op_sel_hi:[1,1,0]
	v_exp_f32_e32 v223, v223
	v_pk_fma_f32 v[128:129], v[120:121], v[128:129], s[34:35] op_sel_hi:[1,1,0]
	v_pk_fma_f32 v[128:129], v[120:121], v[128:129], s[36:37] op_sel_hi:[1,1,0]
	v_pk_mul_f32 v[128:129], v[120:121], v[128:129]
	v_pk_fma_f32 v[130:131], v[122:123], s[26:27], v[132:133] op_sel_hi:[1,0,0]
	v_exp_f32_e32 v224, v224
	v_pk_fma_f32 v[130:131], v[122:123], v[130:131], s[30:31] op_sel_hi:[1,1,0]
	v_exp_f32_e32 v225, v225
	v_pk_fma_f32 v[130:131], v[122:123], v[130:131], s[34:35] op_sel_hi:[1,1,0]
	v_pk_fma_f32 v[130:131], v[122:123], v[130:131], s[36:37] op_sel_hi:[1,1,0]
	v_pk_mul_f32 v[130:131], v[122:123], v[130:131]
	v_pk_mul_f32 v[124:125], v[218:219], v[124:125]
	v_pk_mul_f32 v[218:219], v[104:105], v[124:125]
	v_pk_fma_f32 v[124:125], v[104:105], v[124:125], v[104:105] neg_lo:[1,0,0] neg_hi:[1,0,0]
	v_cmp_gt_f32_e64 s[8:9], 0, v104
	v_cmp_gt_f32_e64 s[22:23], 0, v105
	v_lshlrev_b32_e32 v112, 16, v88
	v_and_b32_e32 v113, 0xffff0000, v88
	v_cndmask_b32_e64 v104, v124, v218, s[8:9]
	v_cndmask_b32_e64 v105, v125, v219, s[22:23]
	v_pk_mul_f32 v[104:105], v[104:105], v[112:113]
	v_cvt_pk_bf16_f32 v226, v104, v105
	v_pk_mul_f32 v[126:127], v[220:221], v[126:127]
	v_pk_mul_f32 v[220:221], v[106:107], v[126:127]
	v_pk_fma_f32 v[126:127], v[106:107], v[126:127], v[106:107] neg_lo:[1,0,0] neg_hi:[1,0,0]
	v_cmp_gt_f32_e64 s[8:9], 0, v106
	v_cmp_gt_f32_e64 s[22:23], 0, v107
	v_lshlrev_b32_e32 v112, 16, v89
	v_and_b32_e32 v113, 0xffff0000, v89
	v_cndmask_b32_e64 v106, v126, v220, s[8:9]
	v_cndmask_b32_e64 v107, v127, v221, s[22:23]
	v_pk_mul_f32 v[106:107], v[106:107], v[112:113]
	v_cvt_pk_bf16_f32 v227, v106, v107
	v_pk_mul_f32 v[128:129], v[222:223], v[128:129]
	v_pk_mul_f32 v[222:223], v[108:109], v[128:129]
	v_pk_fma_f32 v[128:129], v[108:109], v[128:129], v[108:109] neg_lo:[1,0,0] neg_hi:[1,0,0]
	v_cmp_gt_f32_e64 s[8:9], 0, v108
	v_cmp_gt_f32_e64 s[22:23], 0, v109
	v_lshlrev_b32_e32 v112, 16, v90
	v_and_b32_e32 v113, 0xffff0000, v90
	v_cndmask_b32_e64 v108, v128, v222, s[8:9]
	v_cndmask_b32_e64 v109, v129, v223, s[22:23]
	v_pk_mul_f32 v[108:109], v[108:109], v[112:113]
	v_cvt_pk_bf16_f32 v228, v108, v109
	v_pk_mul_f32 v[130:131], v[224:225], v[130:131]
	v_pk_mul_f32 v[224:225], v[110:111], v[130:131]
	v_pk_fma_f32 v[130:131], v[110:111], v[130:131], v[110:111] neg_lo:[1,0,0] neg_hi:[1,0,0]
	v_cmp_gt_f32_e64 s[8:9], 0, v110
	v_cmp_gt_f32_e64 s[22:23], 0, v111
	v_lshlrev_b32_e32 v112, 16, v91
	v_and_b32_e32 v113, 0xffff0000, v91
	v_cndmask_b32_e64 v110, v130, v224, s[8:9]
	v_cndmask_b32_e64 v111, v131, v225, s[22:23]
	v_pk_mul_f32 v[110:111], v[110:111], v[112:113]
	v_cvt_pk_bf16_f32 v229, v110, v111
	global_store_dwordx4 v140, v[226:229], s[14:15]
	v_add_u32_e32 v140, 0x2c00, v140
	global_load_dwordx4 v[170:173], v136, s[14:15]
	global_load_dwordx4 v[174:177], v137, s[14:15]
	global_load_dwordx4 v[178:181], v138, s[14:15]
	v_add_u32_e32 v136, 0x2c00, v136
	v_add_u32_e32 v137, 0x2c00, v137
	v_add_u32_e32 v138, 0x2c00, v138
	global_load_dwordx4 v[84:87], v139, s[14:15]
	v_add_u32_e32 v139, 0x2c00, v139
	s_waitcnt vmcnt(16)
	v_mov_b64_e32 v[104:105], v[72:73]
	v_mov_b64_e32 v[106:107], v[74:75]
	v_mov_b64_e32 v[108:109], v[76:77]
	v_mov_b64_e32 v[110:111], v[78:79]
	v_lshlrev_b32_e32 v112, 16, v182
	v_and_b32_e32 v113, 0xffff0000, v182
	v_pk_fma_f32 v[104:105], v[112:113], v[0:1], v[104:105]
	v_lshlrev_b32_e32 v114, 16, v183
	v_and_b32_e32 v115, 0xffff0000, v183
	v_pk_fma_f32 v[106:107], v[114:115], v[2:3], v[106:107]
	v_lshlrev_b32_e32 v112, 16, v184
	v_and_b32_e32 v113, 0xffff0000, v184
	v_pk_fma_f32 v[108:109], v[112:113], v[4:5], v[108:109]
	v_lshlrev_b32_e32 v114, 16, v185
	v_and_b32_e32 v115, 0xffff0000, v185
	v_pk_fma_f32 v[110:111], v[114:115], v[6:7], v[110:111]
	v_lshlrev_b32_e32 v112, 16, v194
	v_and_b32_e32 v113, 0xffff0000, v194
	v_pk_fma_f32 v[104:105], v[112:113], v[8:9], v[104:105]
	v_lshlrev_b32_e32 v114, 16, v195
	v_and_b32_e32 v115, 0xffff0000, v195
	v_pk_fma_f32 v[106:107], v[114:115], v[10:11], v[106:107]
	v_lshlrev_b32_e32 v112, 16, v196
	v_and_b32_e32 v113, 0xffff0000, v196
	v_pk_fma_f32 v[108:109], v[112:113], v[12:13], v[108:109]
	v_lshlrev_b32_e32 v114, 16, v197
	v_and_b32_e32 v115, 0xffff0000, v197
	v_pk_fma_f32 v[110:111], v[114:115], v[14:15], v[110:111]
	v_lshlrev_b32_e32 v112, 16, v206
	v_and_b32_e32 v113, 0xffff0000, v206
	v_pk_fma_f32 v[104:105], v[112:113], v[16:17], v[104:105]
	v_lshlrev_b32_e32 v114, 16, v207
	v_and_b32_e32 v115, 0xffff0000, v207
	v_pk_fma_f32 v[106:107], v[114:115], v[18:19], v[106:107]
	v_lshlrev_b32_e32 v112, 16, v208
	v_and_b32_e32 v113, 0xffff0000, v208
	v_pk_fma_f32 v[108:109], v[112:113], v[20:21], v[108:109]
	v_lshlrev_b32_e32 v114, 16, v209
	v_and_b32_e32 v115, 0xffff0000, v209
	v_pk_fma_f32 v[110:111], v[114:115], v[22:23], v[110:111]
	v_lshlrev_b32_e32 v112, 16, v186
	v_and_b32_e32 v113, 0xffff0000, v186
	v_pk_fma_f32 v[104:105], v[112:113], v[24:25], v[104:105]
	v_lshlrev_b32_e32 v114, 16, v187
	v_and_b32_e32 v115, 0xffff0000, v187
	v_pk_fma_f32 v[106:107], v[114:115], v[26:27], v[106:107]
	v_lshlrev_b32_e32 v112, 16, v188
	v_and_b32_e32 v113, 0xffff0000, v188
	v_pk_fma_f32 v[108:109], v[112:113], v[28:29], v[108:109]
	v_lshlrev_b32_e32 v114, 16, v189
	v_and_b32_e32 v115, 0xffff0000, v189
	v_pk_fma_f32 v[110:111], v[114:115], v[30:31], v[110:111]
	v_lshlrev_b32_e32 v112, 16, v198
	v_and_b32_e32 v113, 0xffff0000, v198
	v_pk_fma_f32 v[104:105], v[112:113], v[32:33], v[104:105]
	v_lshlrev_b32_e32 v114, 16, v199
	v_and_b32_e32 v115, 0xffff0000, v199
	v_pk_fma_f32 v[106:107], v[114:115], v[34:35], v[106:107]
	v_lshlrev_b32_e32 v112, 16, v200
	v_and_b32_e32 v113, 0xffff0000, v200
	v_pk_fma_f32 v[108:109], v[112:113], v[36:37], v[108:109]
	v_lshlrev_b32_e32 v114, 16, v201
	v_and_b32_e32 v115, 0xffff0000, v201
	v_pk_fma_f32 v[110:111], v[114:115], v[38:39], v[110:111]
	v_lshlrev_b32_e32 v112, 16, v210
	v_and_b32_e32 v113, 0xffff0000, v210
	v_pk_fma_f32 v[104:105], v[112:113], v[40:41], v[104:105]
	v_lshlrev_b32_e32 v114, 16, v211
	v_and_b32_e32 v115, 0xffff0000, v211
	v_pk_fma_f32 v[106:107], v[114:115], v[42:43], v[106:107]
	v_lshlrev_b32_e32 v112, 16, v212
	v_and_b32_e32 v113, 0xffff0000, v212
	v_pk_fma_f32 v[108:109], v[112:113], v[44:45], v[108:109]
	v_lshlrev_b32_e32 v114, 16, v213
	v_and_b32_e32 v115, 0xffff0000, v213
	v_pk_fma_f32 v[110:111], v[114:115], v[46:47], v[110:111]
	v_lshlrev_b32_e32 v112, 16, v190
	v_and_b32_e32 v113, 0xffff0000, v190
	v_pk_fma_f32 v[104:105], v[112:113], v[48:49], v[104:105]
	v_lshlrev_b32_e32 v114, 16, v191
	v_and_b32_e32 v115, 0xffff0000, v191
	v_pk_fma_f32 v[106:107], v[114:115], v[50:51], v[106:107]
	v_lshlrev_b32_e32 v112, 16, v192
	v_and_b32_e32 v113, 0xffff0000, v192
	v_pk_fma_f32 v[108:109], v[112:113], v[52:53], v[108:109]
	v_lshlrev_b32_e32 v114, 16, v193
	v_and_b32_e32 v115, 0xffff0000, v193
	v_pk_fma_f32 v[110:111], v[114:115], v[54:55], v[110:111]
	v_lshlrev_b32_e32 v112, 16, v202
	v_and_b32_e32 v113, 0xffff0000, v202
	v_pk_fma_f32 v[104:105], v[112:113], v[56:57], v[104:105]
	v_lshlrev_b32_e32 v114, 16, v203
	v_and_b32_e32 v115, 0xffff0000, v203
	v_pk_fma_f32 v[106:107], v[114:115], v[58:59], v[106:107]
	v_lshlrev_b32_e32 v112, 16, v204
	v_and_b32_e32 v113, 0xffff0000, v204
	v_pk_fma_f32 v[108:109], v[112:113], v[60:61], v[108:109]
	v_lshlrev_b32_e32 v114, 16, v205
	v_and_b32_e32 v115, 0xffff0000, v205
	v_pk_fma_f32 v[110:111], v[114:115], v[62:63], v[110:111]
	v_lshlrev_b32_e32 v112, 16, v214
	v_and_b32_e32 v113, 0xffff0000, v214
	v_pk_fma_f32 v[104:105], v[112:113], v[64:65], v[104:105]
	v_lshlrev_b32_e32 v114, 16, v215
	v_and_b32_e32 v115, 0xffff0000, v215
	v_pk_fma_f32 v[106:107], v[114:115], v[66:67], v[106:107]
	v_lshlrev_b32_e32 v112, 16, v216
	v_and_b32_e32 v113, 0xffff0000, v216
	v_pk_fma_f32 v[108:109], v[112:113], v[68:69], v[108:109]
	v_lshlrev_b32_e32 v114, 16, v217
	v_and_b32_e32 v115, 0xffff0000, v217
	v_pk_fma_f32 v[110:111], v[114:115], v[70:71], v[110:111]
	v_mov_b64_e32 v[132:133], s[28:29]
	v_and_b32_e32 v116, 0x7fffffff, v104
	v_and_b32_e32 v117, 0x7fffffff, v105
	v_pk_fma_f32 v[116:117], v[116:117], s[24:25], 1.0 op_sel_hi:[1,0,0]
	v_pk_mul_f32 v[218:219], v[104:105], v[104:105]
	v_rcp_f32_e32 v116, v116
	v_rcp_f32_e32 v117, v117
	v_pk_mul_f32 v[218:219], v[218:219], s[38:39] op_sel_hi:[1,0]
	v_and_b32_e32 v118, 0x7fffffff, v106
	v_and_b32_e32 v119, 0x7fffffff, v107
	v_pk_fma_f32 v[118:119], v[118:119], s[24:25], 1.0 op_sel_hi:[1,0,0]
	v_pk_mul_f32 v[220:221], v[106:107], v[106:107]
	v_rcp_f32_e32 v118, v118
	v_rcp_f32_e32 v119, v119
	v_pk_mul_f32 v[220:221], v[220:221], s[38:39] op_sel_hi:[1,0]
	v_and_b32_e32 v120, 0x7fffffff, v108
	v_and_b32_e32 v121, 0x7fffffff, v109
	v_pk_fma_f32 v[120:121], v[120:121], s[24:25], 1.0 op_sel_hi:[1,0,0]
	v_pk_mul_f32 v[222:223], v[108:109], v[108:109]
	v_rcp_f32_e32 v120, v120
	v_rcp_f32_e32 v121, v121
	v_pk_mul_f32 v[222:223], v[222:223], s[38:39] op_sel_hi:[1,0]
	v_and_b32_e32 v122, 0x7fffffff, v110
	v_and_b32_e32 v123, 0x7fffffff, v111
	v_pk_fma_f32 v[122:123], v[122:123], s[24:25], 1.0 op_sel_hi:[1,0,0]
	v_pk_mul_f32 v[224:225], v[110:111], v[110:111]
	v_rcp_f32_e32 v122, v122
	v_rcp_f32_e32 v123, v123
	v_pk_mul_f32 v[224:225], v[224:225], s[38:39] op_sel_hi:[1,0]
	v_pk_fma_f32 v[124:125], v[116:117], s[26:27], v[132:133] op_sel_hi:[1,0,0]
	v_exp_f32_e32 v218, v218
	v_pk_fma_f32 v[124:125], v[116:117], v[124:125], s[30:31] op_sel_hi:[1,1,0]
	v_exp_f32_e32 v219, v219
	v_pk_fma_f32 v[124:125], v[116:117], v[124:125], s[34:35] op_sel_hi:[1,1,0]
	v_pk_fma_f32 v[124:125], v[116:117], v[124:125], s[36:37] op_sel_hi:[1,1,0]
	v_pk_mul_f32 v[124:125], v[116:117], v[124:125]
	v_pk_fma_f32 v[126:127], v[118:119], s[26:27], v[132:133] op_sel_hi:[1,0,0]
	v_exp_f32_e32 v220, v220
	v_pk_fma_f32 v[126:127], v[118:119], v[126:127], s[30:31] op_sel_hi:[1,1,0]
	v_exp_f32_e32 v221, v221
	v_pk_fma_f32 v[126:127], v[118:119], v[126:127], s[34:35] op_sel_hi:[1,1,0]
	v_pk_fma_f32 v[126:127], v[118:119], v[126:127], s[36:37] op_sel_hi:[1,1,0]
	v_pk_mul_f32 v[126:127], v[118:119], v[126:127]
	v_pk_fma_f32 v[128:129], v[120:121], s[26:27], v[132:133] op_sel_hi:[1,0,0]
	v_exp_f32_e32 v222, v222
	v_pk_fma_f32 v[128:129], v[120:121], v[128:129], s[30:31] op_sel_hi:[1,1,0]
	v_exp_f32_e32 v223, v223
	v_pk_fma_f32 v[128:129], v[120:121], v[128:129], s[34:35] op_sel_hi:[1,1,0]
	v_pk_fma_f32 v[128:129], v[120:121], v[128:129], s[36:37] op_sel_hi:[1,1,0]
	v_pk_mul_f32 v[128:129], v[120:121], v[128:129]
	v_pk_fma_f32 v[130:131], v[122:123], s[26:27], v[132:133] op_sel_hi:[1,0,0]
	v_exp_f32_e32 v224, v224
	v_pk_fma_f32 v[130:131], v[122:123], v[130:131], s[30:31] op_sel_hi:[1,1,0]
	v_exp_f32_e32 v225, v225
	v_pk_fma_f32 v[130:131], v[122:123], v[130:131], s[34:35] op_sel_hi:[1,1,0]
	v_pk_fma_f32 v[130:131], v[122:123], v[130:131], s[36:37] op_sel_hi:[1,1,0]
	v_pk_mul_f32 v[130:131], v[122:123], v[130:131]
	v_pk_mul_f32 v[124:125], v[218:219], v[124:125]
	v_pk_mul_f32 v[218:219], v[104:105], v[124:125]
	v_pk_fma_f32 v[124:125], v[104:105], v[124:125], v[104:105] neg_lo:[1,0,0] neg_hi:[1,0,0]
	v_cmp_gt_f32_e64 s[8:9], 0, v104
	v_cmp_gt_f32_e64 s[22:23], 0, v105
	v_lshlrev_b32_e32 v112, 16, v92
	v_and_b32_e32 v113, 0xffff0000, v92
	v_cndmask_b32_e64 v104, v124, v218, s[8:9]
	v_cndmask_b32_e64 v105, v125, v219, s[22:23]
	v_pk_mul_f32 v[104:105], v[104:105], v[112:113]
	v_cvt_pk_bf16_f32 v226, v104, v105
	v_pk_mul_f32 v[126:127], v[220:221], v[126:127]
	v_pk_mul_f32 v[220:221], v[106:107], v[126:127]
	v_pk_fma_f32 v[126:127], v[106:107], v[126:127], v[106:107] neg_lo:[1,0,0] neg_hi:[1,0,0]
	v_cmp_gt_f32_e64 s[8:9], 0, v106
	v_cmp_gt_f32_e64 s[22:23], 0, v107
	v_lshlrev_b32_e32 v112, 16, v93
	v_and_b32_e32 v113, 0xffff0000, v93
	v_cndmask_b32_e64 v106, v126, v220, s[8:9]
	v_cndmask_b32_e64 v107, v127, v221, s[22:23]
	v_pk_mul_f32 v[106:107], v[106:107], v[112:113]
	v_cvt_pk_bf16_f32 v227, v106, v107
	v_pk_mul_f32 v[128:129], v[222:223], v[128:129]
	v_pk_mul_f32 v[222:223], v[108:109], v[128:129]
	v_pk_fma_f32 v[128:129], v[108:109], v[128:129], v[108:109] neg_lo:[1,0,0] neg_hi:[1,0,0]
	v_cmp_gt_f32_e64 s[8:9], 0, v108
	v_cmp_gt_f32_e64 s[22:23], 0, v109
	v_lshlrev_b32_e32 v112, 16, v94
	v_and_b32_e32 v113, 0xffff0000, v94
	v_cndmask_b32_e64 v108, v128, v222, s[8:9]
	v_cndmask_b32_e64 v109, v129, v223, s[22:23]
	v_pk_mul_f32 v[108:109], v[108:109], v[112:113]
	v_cvt_pk_bf16_f32 v228, v108, v109
	v_pk_mul_f32 v[130:131], v[224:225], v[130:131]
	v_pk_mul_f32 v[224:225], v[110:111], v[130:131]
	v_pk_fma_f32 v[130:131], v[110:111], v[130:131], v[110:111] neg_lo:[1,0,0] neg_hi:[1,0,0]
	v_cmp_gt_f32_e64 s[8:9], 0, v110
	v_cmp_gt_f32_e64 s[22:23], 0, v111
	v_lshlrev_b32_e32 v112, 16, v95
	v_and_b32_e32 v113, 0xffff0000, v95
	v_cndmask_b32_e64 v110, v130, v224, s[8:9]
	v_cndmask_b32_e64 v111, v131, v225, s[22:23]
	v_pk_mul_f32 v[110:111], v[110:111], v[112:113]
	v_cvt_pk_bf16_f32 v229, v110, v111
	global_store_dwordx4 v140, v[226:229], s[14:15]
	v_add_u32_e32 v140, 0x2c00, v140
	global_load_dwordx4 v[182:185], v136, s[14:15]
	global_load_dwordx4 v[186:189], v137, s[14:15]
	global_load_dwordx4 v[190:193], v138, s[14:15]
	v_add_u32_e32 v136, 0x2c00, v136
	v_add_u32_e32 v137, 0x2c00, v137
	v_add_u32_e32 v138, 0x2c00, v138
	global_load_dwordx4 v[88:91], v139, s[14:15]
	v_add_u32_e32 v139, 0x2c00, v139
	s_waitcnt vmcnt(16)
	v_mov_b64_e32 v[104:105], v[72:73]
	v_mov_b64_e32 v[106:107], v[74:75]
	v_mov_b64_e32 v[108:109], v[76:77]
	v_mov_b64_e32 v[110:111], v[78:79]
	v_lshlrev_b32_e32 v112, 16, v194
	v_and_b32_e32 v113, 0xffff0000, v194
	v_pk_fma_f32 v[104:105], v[112:113], v[0:1], v[104:105]
	v_lshlrev_b32_e32 v114, 16, v195
	v_and_b32_e32 v115, 0xffff0000, v195
	v_pk_fma_f32 v[106:107], v[114:115], v[2:3], v[106:107]
	v_lshlrev_b32_e32 v112, 16, v196
	v_and_b32_e32 v113, 0xffff0000, v196
	v_pk_fma_f32 v[108:109], v[112:113], v[4:5], v[108:109]
	v_lshlrev_b32_e32 v114, 16, v197
	v_and_b32_e32 v115, 0xffff0000, v197
	v_pk_fma_f32 v[110:111], v[114:115], v[6:7], v[110:111]
	v_lshlrev_b32_e32 v112, 16, v206
	v_and_b32_e32 v113, 0xffff0000, v206
	v_pk_fma_f32 v[104:105], v[112:113], v[8:9], v[104:105]
	v_lshlrev_b32_e32 v114, 16, v207
	v_and_b32_e32 v115, 0xffff0000, v207
	v_pk_fma_f32 v[106:107], v[114:115], v[10:11], v[106:107]
	v_lshlrev_b32_e32 v112, 16, v208
	v_and_b32_e32 v113, 0xffff0000, v208
	v_pk_fma_f32 v[108:109], v[112:113], v[12:13], v[108:109]
	v_lshlrev_b32_e32 v114, 16, v209
	v_and_b32_e32 v115, 0xffff0000, v209
	v_pk_fma_f32 v[110:111], v[114:115], v[14:15], v[110:111]
	v_lshlrev_b32_e32 v112, 16, v146
	v_and_b32_e32 v113, 0xffff0000, v146
	v_pk_fma_f32 v[104:105], v[112:113], v[16:17], v[104:105]
	v_lshlrev_b32_e32 v114, 16, v147
	v_and_b32_e32 v115, 0xffff0000, v147
	v_pk_fma_f32 v[106:107], v[114:115], v[18:19], v[106:107]
	v_lshlrev_b32_e32 v112, 16, v148
	v_and_b32_e32 v113, 0xffff0000, v148
	v_pk_fma_f32 v[108:109], v[112:113], v[20:21], v[108:109]
	v_lshlrev_b32_e32 v114, 16, v149
	v_and_b32_e32 v115, 0xffff0000, v149
	v_pk_fma_f32 v[110:111], v[114:115], v[22:23], v[110:111]
	v_lshlrev_b32_e32 v112, 16, v198
	v_and_b32_e32 v113, 0xffff0000, v198
	v_pk_fma_f32 v[104:105], v[112:113], v[24:25], v[104:105]
	v_lshlrev_b32_e32 v114, 16, v199
	v_and_b32_e32 v115, 0xffff0000, v199
	v_pk_fma_f32 v[106:107], v[114:115], v[26:27], v[106:107]
	v_lshlrev_b32_e32 v112, 16, v200
	v_and_b32_e32 v113, 0xffff0000, v200
	v_pk_fma_f32 v[108:109], v[112:113], v[28:29], v[108:109]
	v_lshlrev_b32_e32 v114, 16, v201
	v_and_b32_e32 v115, 0xffff0000, v201
	v_pk_fma_f32 v[110:111], v[114:115], v[30:31], v[110:111]
	v_lshlrev_b32_e32 v112, 16, v210
	v_and_b32_e32 v113, 0xffff0000, v210
	v_pk_fma_f32 v[104:105], v[112:113], v[32:33], v[104:105]
	v_lshlrev_b32_e32 v114, 16, v211
	v_and_b32_e32 v115, 0xffff0000, v211
	v_pk_fma_f32 v[106:107], v[114:115], v[34:35], v[106:107]
	v_lshlrev_b32_e32 v112, 16, v212
	v_and_b32_e32 v113, 0xffff0000, v212
	v_pk_fma_f32 v[108:109], v[112:113], v[36:37], v[108:109]
	v_lshlrev_b32_e32 v114, 16, v213
	v_and_b32_e32 v115, 0xffff0000, v213
	v_pk_fma_f32 v[110:111], v[114:115], v[38:39], v[110:111]
	v_lshlrev_b32_e32 v112, 16, v150
	v_and_b32_e32 v113, 0xffff0000, v150
	v_pk_fma_f32 v[104:105], v[112:113], v[40:41], v[104:105]
	v_lshlrev_b32_e32 v114, 16, v151
	v_and_b32_e32 v115, 0xffff0000, v151
	v_pk_fma_f32 v[106:107], v[114:115], v[42:43], v[106:107]
	v_lshlrev_b32_e32 v112, 16, v152
	v_and_b32_e32 v113, 0xffff0000, v152
	v_pk_fma_f32 v[108:109], v[112:113], v[44:45], v[108:109]
	v_lshlrev_b32_e32 v114, 16, v153
	v_and_b32_e32 v115, 0xffff0000, v153
	v_pk_fma_f32 v[110:111], v[114:115], v[46:47], v[110:111]
	v_lshlrev_b32_e32 v112, 16, v202
	v_and_b32_e32 v113, 0xffff0000, v202
	v_pk_fma_f32 v[104:105], v[112:113], v[48:49], v[104:105]
	v_lshlrev_b32_e32 v114, 16, v203
	v_and_b32_e32 v115, 0xffff0000, v203
	v_pk_fma_f32 v[106:107], v[114:115], v[50:51], v[106:107]
	v_lshlrev_b32_e32 v112, 16, v204
	v_and_b32_e32 v113, 0xffff0000, v204
	v_pk_fma_f32 v[108:109], v[112:113], v[52:53], v[108:109]
	v_lshlrev_b32_e32 v114, 16, v205
	v_and_b32_e32 v115, 0xffff0000, v205
	v_pk_fma_f32 v[110:111], v[114:115], v[54:55], v[110:111]
	v_lshlrev_b32_e32 v112, 16, v214
	v_and_b32_e32 v113, 0xffff0000, v214
	v_pk_fma_f32 v[104:105], v[112:113], v[56:57], v[104:105]
	v_lshlrev_b32_e32 v114, 16, v215
	v_and_b32_e32 v115, 0xffff0000, v215
	v_pk_fma_f32 v[106:107], v[114:115], v[58:59], v[106:107]
	v_lshlrev_b32_e32 v112, 16, v216
	v_and_b32_e32 v113, 0xffff0000, v216
	v_pk_fma_f32 v[108:109], v[112:113], v[60:61], v[108:109]
	v_lshlrev_b32_e32 v114, 16, v217
	v_and_b32_e32 v115, 0xffff0000, v217
	v_pk_fma_f32 v[110:111], v[114:115], v[62:63], v[110:111]
	v_lshlrev_b32_e32 v112, 16, v154
	v_and_b32_e32 v113, 0xffff0000, v154
	v_pk_fma_f32 v[104:105], v[112:113], v[64:65], v[104:105]
	v_lshlrev_b32_e32 v114, 16, v155
	v_and_b32_e32 v115, 0xffff0000, v155
	v_pk_fma_f32 v[106:107], v[114:115], v[66:67], v[106:107]
	v_lshlrev_b32_e32 v112, 16, v156
	v_and_b32_e32 v113, 0xffff0000, v156
	v_pk_fma_f32 v[108:109], v[112:113], v[68:69], v[108:109]
	v_lshlrev_b32_e32 v114, 16, v157
	v_and_b32_e32 v115, 0xffff0000, v157
	v_pk_fma_f32 v[110:111], v[114:115], v[70:71], v[110:111]
	v_mov_b64_e32 v[132:133], s[28:29]
	v_and_b32_e32 v116, 0x7fffffff, v104
	v_and_b32_e32 v117, 0x7fffffff, v105
	v_pk_fma_f32 v[116:117], v[116:117], s[24:25], 1.0 op_sel_hi:[1,0,0]
	v_pk_mul_f32 v[218:219], v[104:105], v[104:105]
	v_rcp_f32_e32 v116, v116
	v_rcp_f32_e32 v117, v117
	v_pk_mul_f32 v[218:219], v[218:219], s[38:39] op_sel_hi:[1,0]
	v_and_b32_e32 v118, 0x7fffffff, v106
	v_and_b32_e32 v119, 0x7fffffff, v107
	v_pk_fma_f32 v[118:119], v[118:119], s[24:25], 1.0 op_sel_hi:[1,0,0]
	v_pk_mul_f32 v[220:221], v[106:107], v[106:107]
	v_rcp_f32_e32 v118, v118
	v_rcp_f32_e32 v119, v119
	v_pk_mul_f32 v[220:221], v[220:221], s[38:39] op_sel_hi:[1,0]
	v_and_b32_e32 v120, 0x7fffffff, v108
	v_and_b32_e32 v121, 0x7fffffff, v109
	v_pk_fma_f32 v[120:121], v[120:121], s[24:25], 1.0 op_sel_hi:[1,0,0]
	v_pk_mul_f32 v[222:223], v[108:109], v[108:109]
	v_rcp_f32_e32 v120, v120
	v_rcp_f32_e32 v121, v121
	v_pk_mul_f32 v[222:223], v[222:223], s[38:39] op_sel_hi:[1,0]
	v_and_b32_e32 v122, 0x7fffffff, v110
	v_and_b32_e32 v123, 0x7fffffff, v111
	v_pk_fma_f32 v[122:123], v[122:123], s[24:25], 1.0 op_sel_hi:[1,0,0]
	v_pk_mul_f32 v[224:225], v[110:111], v[110:111]
	v_rcp_f32_e32 v122, v122
	v_rcp_f32_e32 v123, v123
	v_pk_mul_f32 v[224:225], v[224:225], s[38:39] op_sel_hi:[1,0]
	v_pk_fma_f32 v[124:125], v[116:117], s[26:27], v[132:133] op_sel_hi:[1,0,0]
	v_exp_f32_e32 v218, v218
	v_pk_fma_f32 v[124:125], v[116:117], v[124:125], s[30:31] op_sel_hi:[1,1,0]
	v_exp_f32_e32 v219, v219
	v_pk_fma_f32 v[124:125], v[116:117], v[124:125], s[34:35] op_sel_hi:[1,1,0]
	v_pk_fma_f32 v[124:125], v[116:117], v[124:125], s[36:37] op_sel_hi:[1,1,0]
	v_pk_mul_f32 v[124:125], v[116:117], v[124:125]
	v_pk_fma_f32 v[126:127], v[118:119], s[26:27], v[132:133] op_sel_hi:[1,0,0]
	v_exp_f32_e32 v220, v220
	v_pk_fma_f32 v[126:127], v[118:119], v[126:127], s[30:31] op_sel_hi:[1,1,0]
	v_exp_f32_e32 v221, v221
	v_pk_fma_f32 v[126:127], v[118:119], v[126:127], s[34:35] op_sel_hi:[1,1,0]
	v_pk_fma_f32 v[126:127], v[118:119], v[126:127], s[36:37] op_sel_hi:[1,1,0]
	v_pk_mul_f32 v[126:127], v[118:119], v[126:127]
	v_pk_fma_f32 v[128:129], v[120:121], s[26:27], v[132:133] op_sel_hi:[1,0,0]
	v_exp_f32_e32 v222, v222
	v_pk_fma_f32 v[128:129], v[120:121], v[128:129], s[30:31] op_sel_hi:[1,1,0]
	v_exp_f32_e32 v223, v223
	v_pk_fma_f32 v[128:129], v[120:121], v[128:129], s[34:35] op_sel_hi:[1,1,0]
	v_pk_fma_f32 v[128:129], v[120:121], v[128:129], s[36:37] op_sel_hi:[1,1,0]
	v_pk_mul_f32 v[128:129], v[120:121], v[128:129]
	v_pk_fma_f32 v[130:131], v[122:123], s[26:27], v[132:133] op_sel_hi:[1,0,0]
	v_exp_f32_e32 v224, v224
	v_pk_fma_f32 v[130:131], v[122:123], v[130:131], s[30:31] op_sel_hi:[1,1,0]
	v_exp_f32_e32 v225, v225
	v_pk_fma_f32 v[130:131], v[122:123], v[130:131], s[34:35] op_sel_hi:[1,1,0]
	v_pk_fma_f32 v[130:131], v[122:123], v[130:131], s[36:37] op_sel_hi:[1,1,0]
	v_pk_mul_f32 v[130:131], v[122:123], v[130:131]
	v_pk_mul_f32 v[124:125], v[218:219], v[124:125]
	v_pk_mul_f32 v[218:219], v[104:105], v[124:125]
	v_pk_fma_f32 v[124:125], v[104:105], v[124:125], v[104:105] neg_lo:[1,0,0] neg_hi:[1,0,0]
	v_cmp_gt_f32_e64 s[8:9], 0, v104
	v_cmp_gt_f32_e64 s[22:23], 0, v105
	v_lshlrev_b32_e32 v112, 16, v96
	v_and_b32_e32 v113, 0xffff0000, v96
	v_cndmask_b32_e64 v104, v124, v218, s[8:9]
	v_cndmask_b32_e64 v105, v125, v219, s[22:23]
	v_pk_mul_f32 v[104:105], v[104:105], v[112:113]
	v_cvt_pk_bf16_f32 v226, v104, v105
	v_pk_mul_f32 v[126:127], v[220:221], v[126:127]
	v_pk_mul_f32 v[220:221], v[106:107], v[126:127]
	v_pk_fma_f32 v[126:127], v[106:107], v[126:127], v[106:107] neg_lo:[1,0,0] neg_hi:[1,0,0]
	v_cmp_gt_f32_e64 s[8:9], 0, v106
	v_cmp_gt_f32_e64 s[22:23], 0, v107
	v_lshlrev_b32_e32 v112, 16, v97
	v_and_b32_e32 v113, 0xffff0000, v97
	v_cndmask_b32_e64 v106, v126, v220, s[8:9]
	v_cndmask_b32_e64 v107, v127, v221, s[22:23]
	v_pk_mul_f32 v[106:107], v[106:107], v[112:113]
	v_cvt_pk_bf16_f32 v227, v106, v107
	v_pk_mul_f32 v[128:129], v[222:223], v[128:129]
	v_pk_mul_f32 v[222:223], v[108:109], v[128:129]
	v_pk_fma_f32 v[128:129], v[108:109], v[128:129], v[108:109] neg_lo:[1,0,0] neg_hi:[1,0,0]
	v_cmp_gt_f32_e64 s[8:9], 0, v108
	v_cmp_gt_f32_e64 s[22:23], 0, v109
	v_lshlrev_b32_e32 v112, 16, v98
	v_and_b32_e32 v113, 0xffff0000, v98
	v_cndmask_b32_e64 v108, v128, v222, s[8:9]
	v_cndmask_b32_e64 v109, v129, v223, s[22:23]
	v_pk_mul_f32 v[108:109], v[108:109], v[112:113]
	v_cvt_pk_bf16_f32 v228, v108, v109
	v_pk_mul_f32 v[130:131], v[224:225], v[130:131]
	v_pk_mul_f32 v[224:225], v[110:111], v[130:131]
	v_pk_fma_f32 v[130:131], v[110:111], v[130:131], v[110:111] neg_lo:[1,0,0] neg_hi:[1,0,0]
	v_cmp_gt_f32_e64 s[8:9], 0, v110
	v_cmp_gt_f32_e64 s[22:23], 0, v111
	v_lshlrev_b32_e32 v112, 16, v99
	v_and_b32_e32 v113, 0xffff0000, v99
	v_cndmask_b32_e64 v110, v130, v224, s[8:9]
	v_cndmask_b32_e64 v111, v131, v225, s[22:23]
	v_pk_mul_f32 v[110:111], v[110:111], v[112:113]
	v_cvt_pk_bf16_f32 v229, v110, v111
	global_store_dwordx4 v140, v[226:229], s[14:15]
	v_add_u32_e32 v140, 0x2c00, v140
	global_load_dwordx4 v[194:197], v136, s[14:15]
	global_load_dwordx4 v[198:201], v137, s[14:15]
	global_load_dwordx4 v[202:205], v138, s[14:15]
	v_add_u32_e32 v136, 0x2c00, v136
	v_add_u32_e32 v137, 0x2c00, v137
	v_add_u32_e32 v138, 0x2c00, v138
	global_load_dwordx4 v[92:95], v139, s[14:15]
	v_add_u32_e32 v139, 0x2c00, v139
	s_waitcnt vmcnt(16)
	v_mov_b64_e32 v[104:105], v[72:73]
	v_mov_b64_e32 v[106:107], v[74:75]
	v_mov_b64_e32 v[108:109], v[76:77]
	v_mov_b64_e32 v[110:111], v[78:79]
	v_lshlrev_b32_e32 v112, 16, v206
	v_and_b32_e32 v113, 0xffff0000, v206
	v_pk_fma_f32 v[104:105], v[112:113], v[0:1], v[104:105]
	v_lshlrev_b32_e32 v114, 16, v207
	v_and_b32_e32 v115, 0xffff0000, v207
	v_pk_fma_f32 v[106:107], v[114:115], v[2:3], v[106:107]
	v_lshlrev_b32_e32 v112, 16, v208
	v_and_b32_e32 v113, 0xffff0000, v208
	v_pk_fma_f32 v[108:109], v[112:113], v[4:5], v[108:109]
	v_lshlrev_b32_e32 v114, 16, v209
	v_and_b32_e32 v115, 0xffff0000, v209
	v_pk_fma_f32 v[110:111], v[114:115], v[6:7], v[110:111]
	v_lshlrev_b32_e32 v112, 16, v146
	v_and_b32_e32 v113, 0xffff0000, v146
	v_pk_fma_f32 v[104:105], v[112:113], v[8:9], v[104:105]
	v_lshlrev_b32_e32 v114, 16, v147
	v_and_b32_e32 v115, 0xffff0000, v147
	v_pk_fma_f32 v[106:107], v[114:115], v[10:11], v[106:107]
	v_lshlrev_b32_e32 v112, 16, v148
	v_and_b32_e32 v113, 0xffff0000, v148
	v_pk_fma_f32 v[108:109], v[112:113], v[12:13], v[108:109]
	v_lshlrev_b32_e32 v114, 16, v149
	v_and_b32_e32 v115, 0xffff0000, v149
	v_pk_fma_f32 v[110:111], v[114:115], v[14:15], v[110:111]
	v_lshlrev_b32_e32 v112, 16, v158
	v_and_b32_e32 v113, 0xffff0000, v158
	v_pk_fma_f32 v[104:105], v[112:113], v[16:17], v[104:105]
	v_lshlrev_b32_e32 v114, 16, v159
	v_and_b32_e32 v115, 0xffff0000, v159
	v_pk_fma_f32 v[106:107], v[114:115], v[18:19], v[106:107]
	v_lshlrev_b32_e32 v112, 16, v160
	v_and_b32_e32 v113, 0xffff0000, v160
	v_pk_fma_f32 v[108:109], v[112:113], v[20:21], v[108:109]
	v_lshlrev_b32_e32 v114, 16, v161
	v_and_b32_e32 v115, 0xffff0000, v161
	v_pk_fma_f32 v[110:111], v[114:115], v[22:23], v[110:111]
	v_lshlrev_b32_e32 v112, 16, v210
	v_and_b32_e32 v113, 0xffff0000, v210
	v_pk_fma_f32 v[104:105], v[112:113], v[24:25], v[104:105]
	v_lshlrev_b32_e32 v114, 16, v211
	v_and_b32_e32 v115, 0xffff0000, v211
	v_pk_fma_f32 v[106:107], v[114:115], v[26:27], v[106:107]
	v_lshlrev_b32_e32 v112, 16, v212
	v_and_b32_e32 v113, 0xffff0000, v212
	v_pk_fma_f32 v[108:109], v[112:113], v[28:29], v[108:109]
	v_lshlrev_b32_e32 v114, 16, v213
	v_and_b32_e32 v115, 0xffff0000, v213
	v_pk_fma_f32 v[110:111], v[114:115], v[30:31], v[110:111]
	v_lshlrev_b32_e32 v112, 16, v150
	v_and_b32_e32 v113, 0xffff0000, v150
	v_pk_fma_f32 v[104:105], v[112:113], v[32:33], v[104:105]
	v_lshlrev_b32_e32 v114, 16, v151
	v_and_b32_e32 v115, 0xffff0000, v151
	v_pk_fma_f32 v[106:107], v[114:115], v[34:35], v[106:107]
	v_lshlrev_b32_e32 v112, 16, v152
	v_and_b32_e32 v113, 0xffff0000, v152
	v_pk_fma_f32 v[108:109], v[112:113], v[36:37], v[108:109]
	v_lshlrev_b32_e32 v114, 16, v153
	v_and_b32_e32 v115, 0xffff0000, v153
	v_pk_fma_f32 v[110:111], v[114:115], v[38:39], v[110:111]
	v_lshlrev_b32_e32 v112, 16, v162
	v_and_b32_e32 v113, 0xffff0000, v162
	v_pk_fma_f32 v[104:105], v[112:113], v[40:41], v[104:105]
	v_lshlrev_b32_e32 v114, 16, v163
	v_and_b32_e32 v115, 0xffff0000, v163
	v_pk_fma_f32 v[106:107], v[114:115], v[42:43], v[106:107]
	v_lshlrev_b32_e32 v112, 16, v164
	v_and_b32_e32 v113, 0xffff0000, v164
	v_pk_fma_f32 v[108:109], v[112:113], v[44:45], v[108:109]
	v_lshlrev_b32_e32 v114, 16, v165
	v_and_b32_e32 v115, 0xffff0000, v165
	v_pk_fma_f32 v[110:111], v[114:115], v[46:47], v[110:111]
	v_lshlrev_b32_e32 v112, 16, v214
	v_and_b32_e32 v113, 0xffff0000, v214
	v_pk_fma_f32 v[104:105], v[112:113], v[48:49], v[104:105]
	v_lshlrev_b32_e32 v114, 16, v215
	v_and_b32_e32 v115, 0xffff0000, v215
	v_pk_fma_f32 v[106:107], v[114:115], v[50:51], v[106:107]
	v_lshlrev_b32_e32 v112, 16, v216
	v_and_b32_e32 v113, 0xffff0000, v216
	v_pk_fma_f32 v[108:109], v[112:113], v[52:53], v[108:109]
	v_lshlrev_b32_e32 v114, 16, v217
	v_and_b32_e32 v115, 0xffff0000, v217
	v_pk_fma_f32 v[110:111], v[114:115], v[54:55], v[110:111]
	v_lshlrev_b32_e32 v112, 16, v154
	v_and_b32_e32 v113, 0xffff0000, v154
	v_pk_fma_f32 v[104:105], v[112:113], v[56:57], v[104:105]
	v_lshlrev_b32_e32 v114, 16, v155
	v_and_b32_e32 v115, 0xffff0000, v155
	v_pk_fma_f32 v[106:107], v[114:115], v[58:59], v[106:107]
	v_lshlrev_b32_e32 v112, 16, v156
	v_and_b32_e32 v113, 0xffff0000, v156
	v_pk_fma_f32 v[108:109], v[112:113], v[60:61], v[108:109]
	v_lshlrev_b32_e32 v114, 16, v157
	v_and_b32_e32 v115, 0xffff0000, v157
	v_pk_fma_f32 v[110:111], v[114:115], v[62:63], v[110:111]
	v_lshlrev_b32_e32 v112, 16, v166
	v_and_b32_e32 v113, 0xffff0000, v166
	v_pk_fma_f32 v[104:105], v[112:113], v[64:65], v[104:105]
	v_lshlrev_b32_e32 v114, 16, v167
	v_and_b32_e32 v115, 0xffff0000, v167
	v_pk_fma_f32 v[106:107], v[114:115], v[66:67], v[106:107]
	v_lshlrev_b32_e32 v112, 16, v168
	v_and_b32_e32 v113, 0xffff0000, v168
	v_pk_fma_f32 v[108:109], v[112:113], v[68:69], v[108:109]
	v_lshlrev_b32_e32 v114, 16, v169
	v_and_b32_e32 v115, 0xffff0000, v169
	v_pk_fma_f32 v[110:111], v[114:115], v[70:71], v[110:111]
	v_mov_b64_e32 v[132:133], s[28:29]
	v_and_b32_e32 v116, 0x7fffffff, v104
	v_and_b32_e32 v117, 0x7fffffff, v105
	v_pk_fma_f32 v[116:117], v[116:117], s[24:25], 1.0 op_sel_hi:[1,0,0]
	v_pk_mul_f32 v[218:219], v[104:105], v[104:105]
	v_rcp_f32_e32 v116, v116
	v_rcp_f32_e32 v117, v117
	v_pk_mul_f32 v[218:219], v[218:219], s[38:39] op_sel_hi:[1,0]
	v_and_b32_e32 v118, 0x7fffffff, v106
	v_and_b32_e32 v119, 0x7fffffff, v107
	v_pk_fma_f32 v[118:119], v[118:119], s[24:25], 1.0 op_sel_hi:[1,0,0]
	v_pk_mul_f32 v[220:221], v[106:107], v[106:107]
	v_rcp_f32_e32 v118, v118
	v_rcp_f32_e32 v119, v119
	v_pk_mul_f32 v[220:221], v[220:221], s[38:39] op_sel_hi:[1,0]
	v_and_b32_e32 v120, 0x7fffffff, v108
	v_and_b32_e32 v121, 0x7fffffff, v109
	v_pk_fma_f32 v[120:121], v[120:121], s[24:25], 1.0 op_sel_hi:[1,0,0]
	v_pk_mul_f32 v[222:223], v[108:109], v[108:109]
	v_rcp_f32_e32 v120, v120
	v_rcp_f32_e32 v121, v121
	v_pk_mul_f32 v[222:223], v[222:223], s[38:39] op_sel_hi:[1,0]
	v_and_b32_e32 v122, 0x7fffffff, v110
	v_and_b32_e32 v123, 0x7fffffff, v111
	v_pk_fma_f32 v[122:123], v[122:123], s[24:25], 1.0 op_sel_hi:[1,0,0]
	v_pk_mul_f32 v[224:225], v[110:111], v[110:111]
	v_rcp_f32_e32 v122, v122
	v_rcp_f32_e32 v123, v123
	v_pk_mul_f32 v[224:225], v[224:225], s[38:39] op_sel_hi:[1,0]
	v_pk_fma_f32 v[124:125], v[116:117], s[26:27], v[132:133] op_sel_hi:[1,0,0]
	v_exp_f32_e32 v218, v218
	v_pk_fma_f32 v[124:125], v[116:117], v[124:125], s[30:31] op_sel_hi:[1,1,0]
	v_exp_f32_e32 v219, v219
	v_pk_fma_f32 v[124:125], v[116:117], v[124:125], s[34:35] op_sel_hi:[1,1,0]
	v_pk_fma_f32 v[124:125], v[116:117], v[124:125], s[36:37] op_sel_hi:[1,1,0]
	v_pk_mul_f32 v[124:125], v[116:117], v[124:125]
	v_pk_fma_f32 v[126:127], v[118:119], s[26:27], v[132:133] op_sel_hi:[1,0,0]
	v_exp_f32_e32 v220, v220
	v_pk_fma_f32 v[126:127], v[118:119], v[126:127], s[30:31] op_sel_hi:[1,1,0]
	v_exp_f32_e32 v221, v221
	v_pk_fma_f32 v[126:127], v[118:119], v[126:127], s[34:35] op_sel_hi:[1,1,0]
	v_pk_fma_f32 v[126:127], v[118:119], v[126:127], s[36:37] op_sel_hi:[1,1,0]
	v_pk_mul_f32 v[126:127], v[118:119], v[126:127]
	v_pk_fma_f32 v[128:129], v[120:121], s[26:27], v[132:133] op_sel_hi:[1,0,0]
	v_exp_f32_e32 v222, v222
	v_pk_fma_f32 v[128:129], v[120:121], v[128:129], s[30:31] op_sel_hi:[1,1,0]
	v_exp_f32_e32 v223, v223
	v_pk_fma_f32 v[128:129], v[120:121], v[128:129], s[34:35] op_sel_hi:[1,1,0]
	v_pk_fma_f32 v[128:129], v[120:121], v[128:129], s[36:37] op_sel_hi:[1,1,0]
	v_pk_mul_f32 v[128:129], v[120:121], v[128:129]
	v_pk_fma_f32 v[130:131], v[122:123], s[26:27], v[132:133] op_sel_hi:[1,0,0]
	v_exp_f32_e32 v224, v224
	v_pk_fma_f32 v[130:131], v[122:123], v[130:131], s[30:31] op_sel_hi:[1,1,0]
	v_exp_f32_e32 v225, v225
	v_pk_fma_f32 v[130:131], v[122:123], v[130:131], s[34:35] op_sel_hi:[1,1,0]
	v_pk_fma_f32 v[130:131], v[122:123], v[130:131], s[36:37] op_sel_hi:[1,1,0]
	v_pk_mul_f32 v[130:131], v[122:123], v[130:131]
	v_pk_mul_f32 v[124:125], v[218:219], v[124:125]
	v_pk_mul_f32 v[218:219], v[104:105], v[124:125]
	v_pk_fma_f32 v[124:125], v[104:105], v[124:125], v[104:105] neg_lo:[1,0,0] neg_hi:[1,0,0]
	v_cmp_gt_f32_e64 s[8:9], 0, v104
	v_cmp_gt_f32_e64 s[22:23], 0, v105
	v_lshlrev_b32_e32 v112, 16, v100
	v_and_b32_e32 v113, 0xffff0000, v100
	v_cndmask_b32_e64 v104, v124, v218, s[8:9]
	v_cndmask_b32_e64 v105, v125, v219, s[22:23]
	v_pk_mul_f32 v[104:105], v[104:105], v[112:113]
	v_cvt_pk_bf16_f32 v226, v104, v105
	v_pk_mul_f32 v[126:127], v[220:221], v[126:127]
	v_pk_mul_f32 v[220:221], v[106:107], v[126:127]
	v_pk_fma_f32 v[126:127], v[106:107], v[126:127], v[106:107] neg_lo:[1,0,0] neg_hi:[1,0,0]
	v_cmp_gt_f32_e64 s[8:9], 0, v106
	v_cmp_gt_f32_e64 s[22:23], 0, v107
	v_lshlrev_b32_e32 v112, 16, v101
	v_and_b32_e32 v113, 0xffff0000, v101
	v_cndmask_b32_e64 v106, v126, v220, s[8:9]
	v_cndmask_b32_e64 v107, v127, v221, s[22:23]
	v_pk_mul_f32 v[106:107], v[106:107], v[112:113]
	v_cvt_pk_bf16_f32 v227, v106, v107
	v_pk_mul_f32 v[128:129], v[222:223], v[128:129]
	v_pk_mul_f32 v[222:223], v[108:109], v[128:129]
	v_pk_fma_f32 v[128:129], v[108:109], v[128:129], v[108:109] neg_lo:[1,0,0] neg_hi:[1,0,0]
	v_cmp_gt_f32_e64 s[8:9], 0, v108
	v_cmp_gt_f32_e64 s[22:23], 0, v109
	v_lshlrev_b32_e32 v112, 16, v102
	v_and_b32_e32 v113, 0xffff0000, v102
	v_cndmask_b32_e64 v108, v128, v222, s[8:9]
	v_cndmask_b32_e64 v109, v129, v223, s[22:23]
	v_pk_mul_f32 v[108:109], v[108:109], v[112:113]
	v_cvt_pk_bf16_f32 v228, v108, v109
	v_pk_mul_f32 v[130:131], v[224:225], v[130:131]
	v_pk_mul_f32 v[224:225], v[110:111], v[130:131]
	v_pk_fma_f32 v[130:131], v[110:111], v[130:131], v[110:111] neg_lo:[1,0,0] neg_hi:[1,0,0]
	v_cmp_gt_f32_e64 s[8:9], 0, v110
	v_cmp_gt_f32_e64 s[22:23], 0, v111
	v_lshlrev_b32_e32 v112, 16, v103
	v_and_b32_e32 v113, 0xffff0000, v103
	v_cndmask_b32_e64 v110, v130, v224, s[8:9]
	v_cndmask_b32_e64 v111, v131, v225, s[22:23]
	v_pk_mul_f32 v[110:111], v[110:111], v[112:113]
	v_cvt_pk_bf16_f32 v229, v110, v111
	global_store_dwordx4 v140, v[226:229], s[14:15]
	v_add_u32_e32 v140, 0x2c00, v140
	s_mov_b32 s21, 4
.Lconv_cols:
	global_load_dwordx4 v[206:209], v136, s[14:15]
	global_load_dwordx4 v[210:213], v137, s[14:15]
	global_load_dwordx4 v[214:217], v138, s[14:15]
	v_add_u32_e32 v136, 0x2c00, v136
	v_add_u32_e32 v137, 0x2c00, v137
	v_add_u32_e32 v138, 0x2c00, v138
	global_load_dwordx4 v[96:99], v139, s[14:15]
	v_add_u32_e32 v139, 0x2c00, v139
	s_waitcnt vmcnt(16)
	v_mov_b64_e32 v[104:105], v[72:73]
	v_mov_b64_e32 v[106:107], v[74:75]
	v_mov_b64_e32 v[108:109], v[76:77]
	v_mov_b64_e32 v[110:111], v[78:79]
	v_lshlrev_b32_e32 v112, 16, v146
	v_and_b32_e32 v113, 0xffff0000, v146
	v_pk_fma_f32 v[104:105], v[112:113], v[0:1], v[104:105]
	v_lshlrev_b32_e32 v114, 16, v147
	v_and_b32_e32 v115, 0xffff0000, v147
	v_pk_fma_f32 v[106:107], v[114:115], v[2:3], v[106:107]
	v_lshlrev_b32_e32 v112, 16, v148
	v_and_b32_e32 v113, 0xffff0000, v148
	v_pk_fma_f32 v[108:109], v[112:113], v[4:5], v[108:109]
	v_lshlrev_b32_e32 v114, 16, v149
	v_and_b32_e32 v115, 0xffff0000, v149
	v_pk_fma_f32 v[110:111], v[114:115], v[6:7], v[110:111]
	v_lshlrev_b32_e32 v112, 16, v158
	v_and_b32_e32 v113, 0xffff0000, v158
	v_pk_fma_f32 v[104:105], v[112:113], v[8:9], v[104:105]
	v_lshlrev_b32_e32 v114, 16, v159
	v_and_b32_e32 v115, 0xffff0000, v159
	v_pk_fma_f32 v[106:107], v[114:115], v[10:11], v[106:107]
	v_lshlrev_b32_e32 v112, 16, v160
	v_and_b32_e32 v113, 0xffff0000, v160
	v_pk_fma_f32 v[108:109], v[112:113], v[12:13], v[108:109]
	v_lshlrev_b32_e32 v114, 16, v161
	v_and_b32_e32 v115, 0xffff0000, v161
	v_pk_fma_f32 v[110:111], v[114:115], v[14:15], v[110:111]
	v_lshlrev_b32_e32 v112, 16, v170
	v_and_b32_e32 v113, 0xffff0000, v170
	v_pk_fma_f32 v[104:105], v[112:113], v[16:17], v[104:105]
	v_lshlrev_b32_e32 v114, 16, v171
	v_and_b32_e32 v115, 0xffff0000, v171
	v_pk_fma_f32 v[106:107], v[114:115], v[18:19], v[106:107]
	v_lshlrev_b32_e32 v112, 16, v172
	v_and_b32_e32 v113, 0xffff0000, v172
	v_pk_fma_f32 v[108:109], v[112:113], v[20:21], v[108:109]
	v_lshlrev_b32_e32 v114, 16, v173
	v_and_b32_e32 v115, 0xffff0000, v173
	v_pk_fma_f32 v[110:111], v[114:115], v[22:23], v[110:111]
	v_lshlrev_b32_e32 v112, 16, v150
	v_and_b32_e32 v113, 0xffff0000, v150
	v_pk_fma_f32 v[104:105], v[112:113], v[24:25], v[104:105]
	v_lshlrev_b32_e32 v114, 16, v151
	v_and_b32_e32 v115, 0xffff0000, v151
	v_pk_fma_f32 v[106:107], v[114:115], v[26:27], v[106:107]
	v_lshlrev_b32_e32 v112, 16, v152
	v_and_b32_e32 v113, 0xffff0000, v152
	v_pk_fma_f32 v[108:109], v[112:113], v[28:29], v[108:109]
	v_lshlrev_b32_e32 v114, 16, v153
	v_and_b32_e32 v115, 0xffff0000, v153
	v_pk_fma_f32 v[110:111], v[114:115], v[30:31], v[110:111]
	v_lshlrev_b32_e32 v112, 16, v162
	v_and_b32_e32 v113, 0xffff0000, v162
	v_pk_fma_f32 v[104:105], v[112:113], v[32:33], v[104:105]
	v_lshlrev_b32_e32 v114, 16, v163
	v_and_b32_e32 v115, 0xffff0000, v163
	v_pk_fma_f32 v[106:107], v[114:115], v[34:35], v[106:107]
	v_lshlrev_b32_e32 v112, 16, v164
	v_and_b32_e32 v113, 0xffff0000, v164
	v_pk_fma_f32 v[108:109], v[112:113], v[36:37], v[108:109]
	v_lshlrev_b32_e32 v114, 16, v165
	v_and_b32_e32 v115, 0xffff0000, v165
	v_pk_fma_f32 v[110:111], v[114:115], v[38:39], v[110:111]
	v_lshlrev_b32_e32 v112, 16, v174
	v_and_b32_e32 v113, 0xffff0000, v174
	v_pk_fma_f32 v[104:105], v[112:113], v[40:41], v[104:105]
	v_lshlrev_b32_e32 v114, 16, v175
	v_and_b32_e32 v115, 0xffff0000, v175
	v_pk_fma_f32 v[106:107], v[114:115], v[42:43], v[106:107]
	v_lshlrev_b32_e32 v112, 16, v176
	v_and_b32_e32 v113, 0xffff0000, v176
	v_pk_fma_f32 v[108:109], v[112:113], v[44:45], v[108:109]
	v_lshlrev_b32_e32 v114, 16, v177
	v_and_b32_e32 v115, 0xffff0000, v177
	v_pk_fma_f32 v[110:111], v[114:115], v[46:47], v[110:111]
	v_lshlrev_b32_e32 v112, 16, v154
	v_and_b32_e32 v113, 0xffff0000, v154
	v_pk_fma_f32 v[104:105], v[112:113], v[48:49], v[104:105]
	v_lshlrev_b32_e32 v114, 16, v155
	v_and_b32_e32 v115, 0xffff0000, v155
	v_pk_fma_f32 v[106:107], v[114:115], v[50:51], v[106:107]
	v_lshlrev_b32_e32 v112, 16, v156
	v_and_b32_e32 v113, 0xffff0000, v156
	v_pk_fma_f32 v[108:109], v[112:113], v[52:53], v[108:109]
	v_lshlrev_b32_e32 v114, 16, v157
	v_and_b32_e32 v115, 0xffff0000, v157
	v_pk_fma_f32 v[110:111], v[114:115], v[54:55], v[110:111]
	v_lshlrev_b32_e32 v112, 16, v166
	v_and_b32_e32 v113, 0xffff0000, v166
	v_pk_fma_f32 v[104:105], v[112:113], v[56:57], v[104:105]
	v_lshlrev_b32_e32 v114, 16, v167
	v_and_b32_e32 v115, 0xffff0000, v167
	v_pk_fma_f32 v[106:107], v[114:115], v[58:59], v[106:107]
	v_lshlrev_b32_e32 v112, 16, v168
	v_and_b32_e32 v113, 0xffff0000, v168
	v_pk_fma_f32 v[108:109], v[112:113], v[60:61], v[108:109]
	v_lshlrev_b32_e32 v114, 16, v169
	v_and_b32_e32 v115, 0xffff0000, v169
	v_pk_fma_f32 v[110:111], v[114:115], v[62:63], v[110:111]
	v_lshlrev_b32_e32 v112, 16, v178
	v_and_b32_e32 v113, 0xffff0000, v178
	v_pk_fma_f32 v[104:105], v[112:113], v[64:65], v[104:105]
	v_lshlrev_b32_e32 v114, 16, v179
	v_and_b32_e32 v115, 0xffff0000, v179
	v_pk_fma_f32 v[106:107], v[114:115], v[66:67], v[106:107]
	v_lshlrev_b32_e32 v112, 16, v180
	v_and_b32_e32 v113, 0xffff0000, v180
	v_pk_fma_f32 v[108:109], v[112:113], v[68:69], v[108:109]
	v_lshlrev_b32_e32 v114, 16, v181
	v_and_b32_e32 v115, 0xffff0000, v181
	v_pk_fma_f32 v[110:111], v[114:115], v[70:71], v[110:111]
	v_mov_b64_e32 v[132:133], s[28:29]
	v_and_b32_e32 v116, 0x7fffffff, v104
	v_and_b32_e32 v117, 0x7fffffff, v105
	v_pk_fma_f32 v[116:117], v[116:117], s[24:25], 1.0 op_sel_hi:[1,0,0]
	v_pk_mul_f32 v[218:219], v[104:105], v[104:105]
	v_rcp_f32_e32 v116, v116
	v_rcp_f32_e32 v117, v117
	v_pk_mul_f32 v[218:219], v[218:219], s[38:39] op_sel_hi:[1,0]
	v_and_b32_e32 v118, 0x7fffffff, v106
	v_and_b32_e32 v119, 0x7fffffff, v107
	v_pk_fma_f32 v[118:119], v[118:119], s[24:25], 1.0 op_sel_hi:[1,0,0]
	v_pk_mul_f32 v[220:221], v[106:107], v[106:107]
	v_rcp_f32_e32 v118, v118
	v_rcp_f32_e32 v119, v119
	v_pk_mul_f32 v[220:221], v[220:221], s[38:39] op_sel_hi:[1,0]
	v_and_b32_e32 v120, 0x7fffffff, v108
	v_and_b32_e32 v121, 0x7fffffff, v109
	v_pk_fma_f32 v[120:121], v[120:121], s[24:25], 1.0 op_sel_hi:[1,0,0]
	v_pk_mul_f32 v[222:223], v[108:109], v[108:109]
	v_rcp_f32_e32 v120, v120
	v_rcp_f32_e32 v121, v121
	v_pk_mul_f32 v[222:223], v[222:223], s[38:39] op_sel_hi:[1,0]
	v_and_b32_e32 v122, 0x7fffffff, v110
	v_and_b32_e32 v123, 0x7fffffff, v111
	v_pk_fma_f32 v[122:123], v[122:123], s[24:25], 1.0 op_sel_hi:[1,0,0]
	v_pk_mul_f32 v[224:225], v[110:111], v[110:111]
	v_rcp_f32_e32 v122, v122
	v_rcp_f32_e32 v123, v123
	v_pk_mul_f32 v[224:225], v[224:225], s[38:39] op_sel_hi:[1,0]
	v_pk_fma_f32 v[124:125], v[116:117], s[26:27], v[132:133] op_sel_hi:[1,0,0]
	v_exp_f32_e32 v218, v218
	v_pk_fma_f32 v[124:125], v[116:117], v[124:125], s[30:31] op_sel_hi:[1,1,0]
	v_exp_f32_e32 v219, v219
	v_pk_fma_f32 v[124:125], v[116:117], v[124:125], s[34:35] op_sel_hi:[1,1,0]
	v_pk_fma_f32 v[124:125], v[116:117], v[124:125], s[36:37] op_sel_hi:[1,1,0]
	v_pk_mul_f32 v[124:125], v[116:117], v[124:125]
	v_pk_fma_f32 v[126:127], v[118:119], s[26:27], v[132:133] op_sel_hi:[1,0,0]
	v_exp_f32_e32 v220, v220
	v_pk_fma_f32 v[126:127], v[118:119], v[126:127], s[30:31] op_sel_hi:[1,1,0]
	v_exp_f32_e32 v221, v221
	v_pk_fma_f32 v[126:127], v[118:119], v[126:127], s[34:35] op_sel_hi:[1,1,0]
	v_pk_fma_f32 v[126:127], v[118:119], v[126:127], s[36:37] op_sel_hi:[1,1,0]
	v_pk_mul_f32 v[126:127], v[118:119], v[126:127]
	v_pk_fma_f32 v[128:129], v[120:121], s[26:27], v[132:133] op_sel_hi:[1,0,0]
	v_exp_f32_e32 v222, v222
	v_pk_fma_f32 v[128:129], v[120:121], v[128:129], s[30:31] op_sel_hi:[1,1,0]
	v_exp_f32_e32 v223, v223
	v_pk_fma_f32 v[128:129], v[120:121], v[128:129], s[34:35] op_sel_hi:[1,1,0]
	v_pk_fma_f32 v[128:129], v[120:121], v[128:129], s[36:37] op_sel_hi:[1,1,0]
	v_pk_mul_f32 v[128:129], v[120:121], v[128:129]
	v_pk_fma_f32 v[130:131], v[122:123], s[26:27], v[132:133] op_sel_hi:[1,0,0]
	v_exp_f32_e32 v224, v224
	v_pk_fma_f32 v[130:131], v[122:123], v[130:131], s[30:31] op_sel_hi:[1,1,0]
	v_exp_f32_e32 v225, v225
	v_pk_fma_f32 v[130:131], v[122:123], v[130:131], s[34:35] op_sel_hi:[1,1,0]
	v_pk_fma_f32 v[130:131], v[122:123], v[130:131], s[36:37] op_sel_hi:[1,1,0]
	v_pk_mul_f32 v[130:131], v[122:123], v[130:131]
	v_pk_mul_f32 v[124:125], v[218:219], v[124:125]
	v_pk_mul_f32 v[218:219], v[104:105], v[124:125]
	v_pk_fma_f32 v[124:125], v[104:105], v[124:125], v[104:105] neg_lo:[1,0,0] neg_hi:[1,0,0]
	v_cmp_gt_f32_e64 s[8:9], 0, v104
	v_cmp_gt_f32_e64 s[22:23], 0, v105
	v_lshlrev_b32_e32 v112, 16, v80
	v_and_b32_e32 v113, 0xffff0000, v80
	v_cndmask_b32_e64 v104, v124, v218, s[8:9]
	v_cndmask_b32_e64 v105, v125, v219, s[22:23]
	v_pk_mul_f32 v[104:105], v[104:105], v[112:113]
	v_cvt_pk_bf16_f32 v226, v104, v105
	v_pk_mul_f32 v[126:127], v[220:221], v[126:127]
	v_pk_mul_f32 v[220:221], v[106:107], v[126:127]
	v_pk_fma_f32 v[126:127], v[106:107], v[126:127], v[106:107] neg_lo:[1,0,0] neg_hi:[1,0,0]
	v_cmp_gt_f32_e64 s[8:9], 0, v106
	v_cmp_gt_f32_e64 s[22:23], 0, v107
	v_lshlrev_b32_e32 v112, 16, v81
	v_and_b32_e32 v113, 0xffff0000, v81
	v_cndmask_b32_e64 v106, v126, v220, s[8:9]
	v_cndmask_b32_e64 v107, v127, v221, s[22:23]
	v_pk_mul_f32 v[106:107], v[106:107], v[112:113]
	v_cvt_pk_bf16_f32 v227, v106, v107
	v_pk_mul_f32 v[128:129], v[222:223], v[128:129]
	v_pk_mul_f32 v[222:223], v[108:109], v[128:129]
	v_pk_fma_f32 v[128:129], v[108:109], v[128:129], v[108:109] neg_lo:[1,0,0] neg_hi:[1,0,0]
	v_cmp_gt_f32_e64 s[8:9], 0, v108
	v_cmp_gt_f32_e64 s[22:23], 0, v109
	v_lshlrev_b32_e32 v112, 16, v82
	v_and_b32_e32 v113, 0xffff0000, v82
	v_cndmask_b32_e64 v108, v128, v222, s[8:9]
	v_cndmask_b32_e64 v109, v129, v223, s[22:23]
	v_pk_mul_f32 v[108:109], v[108:109], v[112:113]
	v_cvt_pk_bf16_f32 v228, v108, v109
	v_pk_mul_f32 v[130:131], v[224:225], v[130:131]
	v_pk_mul_f32 v[224:225], v[110:111], v[130:131]
	v_pk_fma_f32 v[130:131], v[110:111], v[130:131], v[110:111] neg_lo:[1,0,0] neg_hi:[1,0,0]
	v_cmp_gt_f32_e64 s[8:9], 0, v110
	v_cmp_gt_f32_e64 s[22:23], 0, v111
	v_lshlrev_b32_e32 v112, 16, v83
	v_and_b32_e32 v113, 0xffff0000, v83
	v_cndmask_b32_e64 v110, v130, v224, s[8:9]
	v_cndmask_b32_e64 v111, v131, v225, s[22:23]
	v_pk_mul_f32 v[110:111], v[110:111], v[112:113]
	v_cvt_pk_bf16_f32 v229, v110, v111
	global_store_dwordx4 v140, v[226:229], s[14:15]
	v_add_u32_e32 v140, 0x2c00, v140
	global_load_dwordx4 v[146:149], v136, s[14:15]
	global_load_dwordx4 v[150:153], v137, s[14:15]
	global_load_dwordx4 v[154:157], v138, s[14:15]
	v_add_u32_e32 v136, 0x2c00, v136
	v_add_u32_e32 v137, 0x2c00, v137
	v_add_u32_e32 v138, 0x2c00, v138
	global_load_dwordx4 v[100:103], v139, s[14:15]
	v_add_u32_e32 v139, 0x2c00, v139
	s_waitcnt vmcnt(16)
	v_mov_b64_e32 v[104:105], v[72:73]
	v_mov_b64_e32 v[106:107], v[74:75]
	v_mov_b64_e32 v[108:109], v[76:77]
	v_mov_b64_e32 v[110:111], v[78:79]
	v_lshlrev_b32_e32 v112, 16, v158
	v_and_b32_e32 v113, 0xffff0000, v158
	v_pk_fma_f32 v[104:105], v[112:113], v[0:1], v[104:105]
	v_lshlrev_b32_e32 v114, 16, v159
	v_and_b32_e32 v115, 0xffff0000, v159
	v_pk_fma_f32 v[106:107], v[114:115], v[2:3], v[106:107]
	v_lshlrev_b32_e32 v112, 16, v160
	v_and_b32_e32 v113, 0xffff0000, v160
	v_pk_fma_f32 v[108:109], v[112:113], v[4:5], v[108:109]
	v_lshlrev_b32_e32 v114, 16, v161
	v_and_b32_e32 v115, 0xffff0000, v161
	v_pk_fma_f32 v[110:111], v[114:115], v[6:7], v[110:111]
	v_lshlrev_b32_e32 v112, 16, v170
	v_and_b32_e32 v113, 0xffff0000, v170
	v_pk_fma_f32 v[104:105], v[112:113], v[8:9], v[104:105]
	v_lshlrev_b32_e32 v114, 16, v171
	v_and_b32_e32 v115, 0xffff0000, v171
	v_pk_fma_f32 v[106:107], v[114:115], v[10:11], v[106:107]
	v_lshlrev_b32_e32 v112, 16, v172
	v_and_b32_e32 v113, 0xffff0000, v172
	v_pk_fma_f32 v[108:109], v[112:113], v[12:13], v[108:109]
	v_lshlrev_b32_e32 v114, 16, v173
	v_and_b32_e32 v115, 0xffff0000, v173
	v_pk_fma_f32 v[110:111], v[114:115], v[14:15], v[110:111]
	v_lshlrev_b32_e32 v112, 16, v182
	v_and_b32_e32 v113, 0xffff0000, v182
	v_pk_fma_f32 v[104:105], v[112:113], v[16:17], v[104:105]
	v_lshlrev_b32_e32 v114, 16, v183
	v_and_b32_e32 v115, 0xffff0000, v183
	v_pk_fma_f32 v[106:107], v[114:115], v[18:19], v[106:107]
	v_lshlrev_b32_e32 v112, 16, v184
	v_and_b32_e32 v113, 0xffff0000, v184
	v_pk_fma_f32 v[108:109], v[112:113], v[20:21], v[108:109]
	v_lshlrev_b32_e32 v114, 16, v185
	v_and_b32_e32 v115, 0xffff0000, v185
	v_pk_fma_f32 v[110:111], v[114:115], v[22:23], v[110:111]
	v_lshlrev_b32_e32 v112, 16, v162
	v_and_b32_e32 v113, 0xffff0000, v162
	v_pk_fma_f32 v[104:105], v[112:113], v[24:25], v[104:105]
	v_lshlrev_b32_e32 v114, 16, v163
	v_and_b32_e32 v115, 0xffff0000, v163
	v_pk_fma_f32 v[106:107], v[114:115], v[26:27], v[106:107]
	v_lshlrev_b32_e32 v112, 16, v164
	v_and_b32_e32 v113, 0xffff0000, v164
	v_pk_fma_f32 v[108:109], v[112:113], v[28:29], v[108:109]
	v_lshlrev_b32_e32 v114, 16, v165
	v_and_b32_e32 v115, 0xffff0000, v165
	v_pk_fma_f32 v[110:111], v[114:115], v[30:31], v[110:111]
	v_lshlrev_b32_e32 v112, 16, v174
	v_and_b32_e32 v113, 0xffff0000, v174
	v_pk_fma_f32 v[104:105], v[112:113], v[32:33], v[104:105]
	v_lshlrev_b32_e32 v114, 16, v175
	v_and_b32_e32 v115, 0xffff0000, v175
	v_pk_fma_f32 v[106:107], v[114:115], v[34:35], v[106:107]
	v_lshlrev_b32_e32 v112, 16, v176
	v_and_b32_e32 v113, 0xffff0000, v176
	v_pk_fma_f32 v[108:109], v[112:113], v[36:37], v[108:109]
	v_lshlrev_b32_e32 v114, 16, v177
	v_and_b32_e32 v115, 0xffff0000, v177
	v_pk_fma_f32 v[110:111], v[114:115], v[38:39], v[110:111]
	v_lshlrev_b32_e32 v112, 16, v186
	v_and_b32_e32 v113, 0xffff0000, v186
	v_pk_fma_f32 v[104:105], v[112:113], v[40:41], v[104:105]
	v_lshlrev_b32_e32 v114, 16, v187
	v_and_b32_e32 v115, 0xffff0000, v187
	v_pk_fma_f32 v[106:107], v[114:115], v[42:43], v[106:107]
	v_lshlrev_b32_e32 v112, 16, v188
	v_and_b32_e32 v113, 0xffff0000, v188
	v_pk_fma_f32 v[108:109], v[112:113], v[44:45], v[108:109]
	v_lshlrev_b32_e32 v114, 16, v189
	v_and_b32_e32 v115, 0xffff0000, v189
	v_pk_fma_f32 v[110:111], v[114:115], v[46:47], v[110:111]
	v_lshlrev_b32_e32 v112, 16, v166
	v_and_b32_e32 v113, 0xffff0000, v166
	v_pk_fma_f32 v[104:105], v[112:113], v[48:49], v[104:105]
	v_lshlrev_b32_e32 v114, 16, v167
	v_and_b32_e32 v115, 0xffff0000, v167
	v_pk_fma_f32 v[106:107], v[114:115], v[50:51], v[106:107]
	v_lshlrev_b32_e32 v112, 16, v168
	v_and_b32_e32 v113, 0xffff0000, v168
	v_pk_fma_f32 v[108:109], v[112:113], v[52:53], v[108:109]
	v_lshlrev_b32_e32 v114, 16, v169
	v_and_b32_e32 v115, 0xffff0000, v169
	v_pk_fma_f32 v[110:111], v[114:115], v[54:55], v[110:111]
	v_lshlrev_b32_e32 v112, 16, v178
	v_and_b32_e32 v113, 0xffff0000, v178
	v_pk_fma_f32 v[104:105], v[112:113], v[56:57], v[104:105]
	v_lshlrev_b32_e32 v114, 16, v179
	v_and_b32_e32 v115, 0xffff0000, v179
	v_pk_fma_f32 v[106:107], v[114:115], v[58:59], v[106:107]
	v_lshlrev_b32_e32 v112, 16, v180
	v_and_b32_e32 v113, 0xffff0000, v180
	v_pk_fma_f32 v[108:109], v[112:113], v[60:61], v[108:109]
	v_lshlrev_b32_e32 v114, 16, v181
	v_and_b32_e32 v115, 0xffff0000, v181
	v_pk_fma_f32 v[110:111], v[114:115], v[62:63], v[110:111]
	v_lshlrev_b32_e32 v112, 16, v190
	v_and_b32_e32 v113, 0xffff0000, v190
	v_pk_fma_f32 v[104:105], v[112:113], v[64:65], v[104:105]
	v_lshlrev_b32_e32 v114, 16, v191
	v_and_b32_e32 v115, 0xffff0000, v191
	v_pk_fma_f32 v[106:107], v[114:115], v[66:67], v[106:107]
	v_lshlrev_b32_e32 v112, 16, v192
	v_and_b32_e32 v113, 0xffff0000, v192
	v_pk_fma_f32 v[108:109], v[112:113], v[68:69], v[108:109]
	v_lshlrev_b32_e32 v114, 16, v193
	v_and_b32_e32 v115, 0xffff0000, v193
	v_pk_fma_f32 v[110:111], v[114:115], v[70:71], v[110:111]
	v_mov_b64_e32 v[132:133], s[28:29]
	v_and_b32_e32 v116, 0x7fffffff, v104
	v_and_b32_e32 v117, 0x7fffffff, v105
	v_pk_fma_f32 v[116:117], v[116:117], s[24:25], 1.0 op_sel_hi:[1,0,0]
	v_pk_mul_f32 v[218:219], v[104:105], v[104:105]
	v_rcp_f32_e32 v116, v116
	v_rcp_f32_e32 v117, v117
	v_pk_mul_f32 v[218:219], v[218:219], s[38:39] op_sel_hi:[1,0]
	v_and_b32_e32 v118, 0x7fffffff, v106
	v_and_b32_e32 v119, 0x7fffffff, v107
	v_pk_fma_f32 v[118:119], v[118:119], s[24:25], 1.0 op_sel_hi:[1,0,0]
	v_pk_mul_f32 v[220:221], v[106:107], v[106:107]
	v_rcp_f32_e32 v118, v118
	v_rcp_f32_e32 v119, v119
	v_pk_mul_f32 v[220:221], v[220:221], s[38:39] op_sel_hi:[1,0]
	v_and_b32_e32 v120, 0x7fffffff, v108
	v_and_b32_e32 v121, 0x7fffffff, v109
	v_pk_fma_f32 v[120:121], v[120:121], s[24:25], 1.0 op_sel_hi:[1,0,0]
	v_pk_mul_f32 v[222:223], v[108:109], v[108:109]
	v_rcp_f32_e32 v120, v120
	v_rcp_f32_e32 v121, v121
	v_pk_mul_f32 v[222:223], v[222:223], s[38:39] op_sel_hi:[1,0]
	v_and_b32_e32 v122, 0x7fffffff, v110
	v_and_b32_e32 v123, 0x7fffffff, v111
	v_pk_fma_f32 v[122:123], v[122:123], s[24:25], 1.0 op_sel_hi:[1,0,0]
	v_pk_mul_f32 v[224:225], v[110:111], v[110:111]
	v_rcp_f32_e32 v122, v122
	v_rcp_f32_e32 v123, v123
	v_pk_mul_f32 v[224:225], v[224:225], s[38:39] op_sel_hi:[1,0]
	v_pk_fma_f32 v[124:125], v[116:117], s[26:27], v[132:133] op_sel_hi:[1,0,0]
	v_exp_f32_e32 v218, v218
	v_pk_fma_f32 v[124:125], v[116:117], v[124:125], s[30:31] op_sel_hi:[1,1,0]
	v_exp_f32_e32 v219, v219
	v_pk_fma_f32 v[124:125], v[116:117], v[124:125], s[34:35] op_sel_hi:[1,1,0]
	v_pk_fma_f32 v[124:125], v[116:117], v[124:125], s[36:37] op_sel_hi:[1,1,0]
	v_pk_mul_f32 v[124:125], v[116:117], v[124:125]
	v_pk_fma_f32 v[126:127], v[118:119], s[26:27], v[132:133] op_sel_hi:[1,0,0]
	v_exp_f32_e32 v220, v220
	v_pk_fma_f32 v[126:127], v[118:119], v[126:127], s[30:31] op_sel_hi:[1,1,0]
	v_exp_f32_e32 v221, v221
	v_pk_fma_f32 v[126:127], v[118:119], v[126:127], s[34:35] op_sel_hi:[1,1,0]
	v_pk_fma_f32 v[126:127], v[118:119], v[126:127], s[36:37] op_sel_hi:[1,1,0]
	v_pk_mul_f32 v[126:127], v[118:119], v[126:127]
	v_pk_fma_f32 v[128:129], v[120:121], s[26:27], v[132:133] op_sel_hi:[1,0,0]
	v_exp_f32_e32 v222, v222
	v_pk_fma_f32 v[128:129], v[120:121], v[128:129], s[30:31] op_sel_hi:[1,1,0]
	v_exp_f32_e32 v223, v223
	v_pk_fma_f32 v[128:129], v[120:121], v[128:129], s[34:35] op_sel_hi:[1,1,0]
	v_pk_fma_f32 v[128:129], v[120:121], v[128:129], s[36:37] op_sel_hi:[1,1,0]
	v_pk_mul_f32 v[128:129], v[120:121], v[128:129]
	v_pk_fma_f32 v[130:131], v[122:123], s[26:27], v[132:133] op_sel_hi:[1,0,0]
	v_exp_f32_e32 v224, v224
	v_pk_fma_f32 v[130:131], v[122:123], v[130:131], s[30:31] op_sel_hi:[1,1,0]
	v_exp_f32_e32 v225, v225
	v_pk_fma_f32 v[130:131], v[122:123], v[130:131], s[34:35] op_sel_hi:[1,1,0]
	v_pk_fma_f32 v[130:131], v[122:123], v[130:131], s[36:37] op_sel_hi:[1,1,0]
	v_pk_mul_f32 v[130:131], v[122:123], v[130:131]
	v_pk_mul_f32 v[124:125], v[218:219], v[124:125]
	v_pk_mul_f32 v[218:219], v[104:105], v[124:125]
	v_pk_fma_f32 v[124:125], v[104:105], v[124:125], v[104:105] neg_lo:[1,0,0] neg_hi:[1,0,0]
	v_cmp_gt_f32_e64 s[8:9], 0, v104
	v_cmp_gt_f32_e64 s[22:23], 0, v105
	v_lshlrev_b32_e32 v112, 16, v84
	v_and_b32_e32 v113, 0xffff0000, v84
	v_cndmask_b32_e64 v104, v124, v218, s[8:9]
	v_cndmask_b32_e64 v105, v125, v219, s[22:23]
	v_pk_mul_f32 v[104:105], v[104:105], v[112:113]
	v_cvt_pk_bf16_f32 v226, v104, v105
	v_pk_mul_f32 v[126:127], v[220:221], v[126:127]
	v_pk_mul_f32 v[220:221], v[106:107], v[126:127]
	v_pk_fma_f32 v[126:127], v[106:107], v[126:127], v[106:107] neg_lo:[1,0,0] neg_hi:[1,0,0]
	v_cmp_gt_f32_e64 s[8:9], 0, v106
	v_cmp_gt_f32_e64 s[22:23], 0, v107
	v_lshlrev_b32_e32 v112, 16, v85
	v_and_b32_e32 v113, 0xffff0000, v85
	v_cndmask_b32_e64 v106, v126, v220, s[8:9]
	v_cndmask_b32_e64 v107, v127, v221, s[22:23]
	v_pk_mul_f32 v[106:107], v[106:107], v[112:113]
	v_cvt_pk_bf16_f32 v227, v106, v107
	v_pk_mul_f32 v[128:129], v[222:223], v[128:129]
	v_pk_mul_f32 v[222:223], v[108:109], v[128:129]
	v_pk_fma_f32 v[128:129], v[108:109], v[128:129], v[108:109] neg_lo:[1,0,0] neg_hi:[1,0,0]
	v_cmp_gt_f32_e64 s[8:9], 0, v108
	v_cmp_gt_f32_e64 s[22:23], 0, v109
	v_lshlrev_b32_e32 v112, 16, v86
	v_and_b32_e32 v113, 0xffff0000, v86
	v_cndmask_b32_e64 v108, v128, v222, s[8:9]
	v_cndmask_b32_e64 v109, v129, v223, s[22:23]
	v_pk_mul_f32 v[108:109], v[108:109], v[112:113]
	v_cvt_pk_bf16_f32 v228, v108, v109
	v_pk_mul_f32 v[130:131], v[224:225], v[130:131]
	v_pk_mul_f32 v[224:225], v[110:111], v[130:131]
	v_pk_fma_f32 v[130:131], v[110:111], v[130:131], v[110:111] neg_lo:[1,0,0] neg_hi:[1,0,0]
	v_cmp_gt_f32_e64 s[8:9], 0, v110
	v_cmp_gt_f32_e64 s[22:23], 0, v111
	v_lshlrev_b32_e32 v112, 16, v87
	v_and_b32_e32 v113, 0xffff0000, v87
	v_cndmask_b32_e64 v110, v130, v224, s[8:9]
	v_cndmask_b32_e64 v111, v131, v225, s[22:23]
	v_pk_mul_f32 v[110:111], v[110:111], v[112:113]
	v_cvt_pk_bf16_f32 v229, v110, v111
	global_store_dwordx4 v140, v[226:229], s[14:15]
	v_add_u32_e32 v140, 0x2c00, v140
	global_load_dwordx4 v[158:161], v136, s[14:15]
	global_load_dwordx4 v[162:165], v137, s[14:15]
	global_load_dwordx4 v[166:169], v138, s[14:15]
	v_add_u32_e32 v136, 0x2c00, v136
	v_add_u32_e32 v137, 0x2c00, v137
	v_add_u32_e32 v138, 0x2c00, v138
	global_load_dwordx4 v[80:83], v139, s[14:15]
	v_add_u32_e32 v139, 0x2c00, v139
	s_waitcnt vmcnt(16)
	v_mov_b64_e32 v[104:105], v[72:73]
	v_mov_b64_e32 v[106:107], v[74:75]
	v_mov_b64_e32 v[108:109], v[76:77]
	v_mov_b64_e32 v[110:111], v[78:79]
	v_lshlrev_b32_e32 v112, 16, v170
	v_and_b32_e32 v113, 0xffff0000, v170
	v_pk_fma_f32 v[104:105], v[112:113], v[0:1], v[104:105]
	v_lshlrev_b32_e32 v114, 16, v171
	v_and_b32_e32 v115, 0xffff0000, v171
	v_pk_fma_f32 v[106:107], v[114:115], v[2:3], v[106:107]
	v_lshlrev_b32_e32 v112, 16, v172
	v_and_b32_e32 v113, 0xffff0000, v172
	v_pk_fma_f32 v[108:109], v[112:113], v[4:5], v[108:109]
	v_lshlrev_b32_e32 v114, 16, v173
	v_and_b32_e32 v115, 0xffff0000, v173
	v_pk_fma_f32 v[110:111], v[114:115], v[6:7], v[110:111]
	v_lshlrev_b32_e32 v112, 16, v182
	v_and_b32_e32 v113, 0xffff0000, v182
	v_pk_fma_f32 v[104:105], v[112:113], v[8:9], v[104:105]
	v_lshlrev_b32_e32 v114, 16, v183
	v_and_b32_e32 v115, 0xffff0000, v183
	v_pk_fma_f32 v[106:107], v[114:115], v[10:11], v[106:107]
	v_lshlrev_b32_e32 v112, 16, v184
	v_and_b32_e32 v113, 0xffff0000, v184
	v_pk_fma_f32 v[108:109], v[112:113], v[12:13], v[108:109]
	v_lshlrev_b32_e32 v114, 16, v185
	v_and_b32_e32 v115, 0xffff0000, v185
	v_pk_fma_f32 v[110:111], v[114:115], v[14:15], v[110:111]
	v_lshlrev_b32_e32 v112, 16, v194
	v_and_b32_e32 v113, 0xffff0000, v194
	v_pk_fma_f32 v[104:105], v[112:113], v[16:17], v[104:105]
	v_lshlrev_b32_e32 v114, 16, v195
	v_and_b32_e32 v115, 0xffff0000, v195
	v_pk_fma_f32 v[106:107], v[114:115], v[18:19], v[106:107]
	v_lshlrev_b32_e32 v112, 16, v196
	v_and_b32_e32 v113, 0xffff0000, v196
	v_pk_fma_f32 v[108:109], v[112:113], v[20:21], v[108:109]
	v_lshlrev_b32_e32 v114, 16, v197
	v_and_b32_e32 v115, 0xffff0000, v197
	v_pk_fma_f32 v[110:111], v[114:115], v[22:23], v[110:111]
	v_lshlrev_b32_e32 v112, 16, v174
	v_and_b32_e32 v113, 0xffff0000, v174
	v_pk_fma_f32 v[104:105], v[112:113], v[24:25], v[104:105]
	v_lshlrev_b32_e32 v114, 16, v175
	v_and_b32_e32 v115, 0xffff0000, v175
	v_pk_fma_f32 v[106:107], v[114:115], v[26:27], v[106:107]
	v_lshlrev_b32_e32 v112, 16, v176
	v_and_b32_e32 v113, 0xffff0000, v176
	v_pk_fma_f32 v[108:109], v[112:113], v[28:29], v[108:109]
	v_lshlrev_b32_e32 v114, 16, v177
	v_and_b32_e32 v115, 0xffff0000, v177
	v_pk_fma_f32 v[110:111], v[114:115], v[30:31], v[110:111]
	v_lshlrev_b32_e32 v112, 16, v186
	v_and_b32_e32 v113, 0xffff0000, v186
	v_pk_fma_f32 v[104:105], v[112:113], v[32:33], v[104:105]
	v_lshlrev_b32_e32 v114, 16, v187
	v_and_b32_e32 v115, 0xffff0000, v187
	v_pk_fma_f32 v[106:107], v[114:115], v[34:35], v[106:107]
	v_lshlrev_b32_e32 v112, 16, v188
	v_and_b32_e32 v113, 0xffff0000, v188
	v_pk_fma_f32 v[108:109], v[112:113], v[36:37], v[108:109]
	v_lshlrev_b32_e32 v114, 16, v189
	v_and_b32_e32 v115, 0xffff0000, v189
	v_pk_fma_f32 v[110:111], v[114:115], v[38:39], v[110:111]
	v_lshlrev_b32_e32 v112, 16, v198
	v_and_b32_e32 v113, 0xffff0000, v198
	v_pk_fma_f32 v[104:105], v[112:113], v[40:41], v[104:105]
	v_lshlrev_b32_e32 v114, 16, v199
	v_and_b32_e32 v115, 0xffff0000, v199
	v_pk_fma_f32 v[106:107], v[114:115], v[42:43], v[106:107]
	v_lshlrev_b32_e32 v112, 16, v200
	v_and_b32_e32 v113, 0xffff0000, v200
	v_pk_fma_f32 v[108:109], v[112:113], v[44:45], v[108:109]
	v_lshlrev_b32_e32 v114, 16, v201
	v_and_b32_e32 v115, 0xffff0000, v201
	v_pk_fma_f32 v[110:111], v[114:115], v[46:47], v[110:111]
	v_lshlrev_b32_e32 v112, 16, v178
	v_and_b32_e32 v113, 0xffff0000, v178
	v_pk_fma_f32 v[104:105], v[112:113], v[48:49], v[104:105]
	v_lshlrev_b32_e32 v114, 16, v179
	v_and_b32_e32 v115, 0xffff0000, v179
	v_pk_fma_f32 v[106:107], v[114:115], v[50:51], v[106:107]
	v_lshlrev_b32_e32 v112, 16, v180
	v_and_b32_e32 v113, 0xffff0000, v180
	v_pk_fma_f32 v[108:109], v[112:113], v[52:53], v[108:109]
	v_lshlrev_b32_e32 v114, 16, v181
	v_and_b32_e32 v115, 0xffff0000, v181
	v_pk_fma_f32 v[110:111], v[114:115], v[54:55], v[110:111]
	v_lshlrev_b32_e32 v112, 16, v190
	v_and_b32_e32 v113, 0xffff0000, v190
	v_pk_fma_f32 v[104:105], v[112:113], v[56:57], v[104:105]
	v_lshlrev_b32_e32 v114, 16, v191
	v_and_b32_e32 v115, 0xffff0000, v191
	v_pk_fma_f32 v[106:107], v[114:115], v[58:59], v[106:107]
	v_lshlrev_b32_e32 v112, 16, v192
	v_and_b32_e32 v113, 0xffff0000, v192
	v_pk_fma_f32 v[108:109], v[112:113], v[60:61], v[108:109]
	v_lshlrev_b32_e32 v114, 16, v193
	v_and_b32_e32 v115, 0xffff0000, v193
	v_pk_fma_f32 v[110:111], v[114:115], v[62:63], v[110:111]
	v_lshlrev_b32_e32 v112, 16, v202
	v_and_b32_e32 v113, 0xffff0000, v202
	v_pk_fma_f32 v[104:105], v[112:113], v[64:65], v[104:105]
	v_lshlrev_b32_e32 v114, 16, v203
	v_and_b32_e32 v115, 0xffff0000, v203
	v_pk_fma_f32 v[106:107], v[114:115], v[66:67], v[106:107]
	v_lshlrev_b32_e32 v112, 16, v204
	v_and_b32_e32 v113, 0xffff0000, v204
	v_pk_fma_f32 v[108:109], v[112:113], v[68:69], v[108:109]
	v_lshlrev_b32_e32 v114, 16, v205
	v_and_b32_e32 v115, 0xffff0000, v205
	v_pk_fma_f32 v[110:111], v[114:115], v[70:71], v[110:111]
	v_mov_b64_e32 v[132:133], s[28:29]
	v_and_b32_e32 v116, 0x7fffffff, v104
	v_and_b32_e32 v117, 0x7fffffff, v105
	v_pk_fma_f32 v[116:117], v[116:117], s[24:25], 1.0 op_sel_hi:[1,0,0]
	v_pk_mul_f32 v[218:219], v[104:105], v[104:105]
	v_rcp_f32_e32 v116, v116
	v_rcp_f32_e32 v117, v117
	v_pk_mul_f32 v[218:219], v[218:219], s[38:39] op_sel_hi:[1,0]
	v_and_b32_e32 v118, 0x7fffffff, v106
	v_and_b32_e32 v119, 0x7fffffff, v107
	v_pk_fma_f32 v[118:119], v[118:119], s[24:25], 1.0 op_sel_hi:[1,0,0]
	v_pk_mul_f32 v[220:221], v[106:107], v[106:107]
	v_rcp_f32_e32 v118, v118
	v_rcp_f32_e32 v119, v119
	v_pk_mul_f32 v[220:221], v[220:221], s[38:39] op_sel_hi:[1,0]
	v_and_b32_e32 v120, 0x7fffffff, v108
	v_and_b32_e32 v121, 0x7fffffff, v109
	v_pk_fma_f32 v[120:121], v[120:121], s[24:25], 1.0 op_sel_hi:[1,0,0]
	v_pk_mul_f32 v[222:223], v[108:109], v[108:109]
	v_rcp_f32_e32 v120, v120
	v_rcp_f32_e32 v121, v121
	v_pk_mul_f32 v[222:223], v[222:223], s[38:39] op_sel_hi:[1,0]
	v_and_b32_e32 v122, 0x7fffffff, v110
	v_and_b32_e32 v123, 0x7fffffff, v111
	v_pk_fma_f32 v[122:123], v[122:123], s[24:25], 1.0 op_sel_hi:[1,0,0]
	v_pk_mul_f32 v[224:225], v[110:111], v[110:111]
	v_rcp_f32_e32 v122, v122
	v_rcp_f32_e32 v123, v123
	v_pk_mul_f32 v[224:225], v[224:225], s[38:39] op_sel_hi:[1,0]
	v_pk_fma_f32 v[124:125], v[116:117], s[26:27], v[132:133] op_sel_hi:[1,0,0]
	v_exp_f32_e32 v218, v218
	v_pk_fma_f32 v[124:125], v[116:117], v[124:125], s[30:31] op_sel_hi:[1,1,0]
	v_exp_f32_e32 v219, v219
	v_pk_fma_f32 v[124:125], v[116:117], v[124:125], s[34:35] op_sel_hi:[1,1,0]
	v_pk_fma_f32 v[124:125], v[116:117], v[124:125], s[36:37] op_sel_hi:[1,1,0]
	v_pk_mul_f32 v[124:125], v[116:117], v[124:125]
	v_pk_fma_f32 v[126:127], v[118:119], s[26:27], v[132:133] op_sel_hi:[1,0,0]
	v_exp_f32_e32 v220, v220
	v_pk_fma_f32 v[126:127], v[118:119], v[126:127], s[30:31] op_sel_hi:[1,1,0]
	v_exp_f32_e32 v221, v221
	v_pk_fma_f32 v[126:127], v[118:119], v[126:127], s[34:35] op_sel_hi:[1,1,0]
	v_pk_fma_f32 v[126:127], v[118:119], v[126:127], s[36:37] op_sel_hi:[1,1,0]
	v_pk_mul_f32 v[126:127], v[118:119], v[126:127]
	v_pk_fma_f32 v[128:129], v[120:121], s[26:27], v[132:133] op_sel_hi:[1,0,0]
	v_exp_f32_e32 v222, v222
	v_pk_fma_f32 v[128:129], v[120:121], v[128:129], s[30:31] op_sel_hi:[1,1,0]
	v_exp_f32_e32 v223, v223
	v_pk_fma_f32 v[128:129], v[120:121], v[128:129], s[34:35] op_sel_hi:[1,1,0]
	v_pk_fma_f32 v[128:129], v[120:121], v[128:129], s[36:37] op_sel_hi:[1,1,0]
	v_pk_mul_f32 v[128:129], v[120:121], v[128:129]
	v_pk_fma_f32 v[130:131], v[122:123], s[26:27], v[132:133] op_sel_hi:[1,0,0]
	v_exp_f32_e32 v224, v224
	v_pk_fma_f32 v[130:131], v[122:123], v[130:131], s[30:31] op_sel_hi:[1,1,0]
	v_exp_f32_e32 v225, v225
	v_pk_fma_f32 v[130:131], v[122:123], v[130:131], s[34:35] op_sel_hi:[1,1,0]
	v_pk_fma_f32 v[130:131], v[122:123], v[130:131], s[36:37] op_sel_hi:[1,1,0]
	v_pk_mul_f32 v[130:131], v[122:123], v[130:131]
	v_pk_mul_f32 v[124:125], v[218:219], v[124:125]
	v_pk_mul_f32 v[218:219], v[104:105], v[124:125]
	v_pk_fma_f32 v[124:125], v[104:105], v[124:125], v[104:105] neg_lo:[1,0,0] neg_hi:[1,0,0]
	v_cmp_gt_f32_e64 s[8:9], 0, v104
	v_cmp_gt_f32_e64 s[22:23], 0, v105
	v_lshlrev_b32_e32 v112, 16, v88
	v_and_b32_e32 v113, 0xffff0000, v88
	v_cndmask_b32_e64 v104, v124, v218, s[8:9]
	v_cndmask_b32_e64 v105, v125, v219, s[22:23]
	v_pk_mul_f32 v[104:105], v[104:105], v[112:113]
	v_cvt_pk_bf16_f32 v226, v104, v105
	v_pk_mul_f32 v[126:127], v[220:221], v[126:127]
	v_pk_mul_f32 v[220:221], v[106:107], v[126:127]
	v_pk_fma_f32 v[126:127], v[106:107], v[126:127], v[106:107] neg_lo:[1,0,0] neg_hi:[1,0,0]
	v_cmp_gt_f32_e64 s[8:9], 0, v106
	v_cmp_gt_f32_e64 s[22:23], 0, v107
	v_lshlrev_b32_e32 v112, 16, v89
	v_and_b32_e32 v113, 0xffff0000, v89
	v_cndmask_b32_e64 v106, v126, v220, s[8:9]
	v_cndmask_b32_e64 v107, v127, v221, s[22:23]
	v_pk_mul_f32 v[106:107], v[106:107], v[112:113]
	v_cvt_pk_bf16_f32 v227, v106, v107
	v_pk_mul_f32 v[128:129], v[222:223], v[128:129]
	v_pk_mul_f32 v[222:223], v[108:109], v[128:129]
	v_pk_fma_f32 v[128:129], v[108:109], v[128:129], v[108:109] neg_lo:[1,0,0] neg_hi:[1,0,0]
	v_cmp_gt_f32_e64 s[8:9], 0, v108
	v_cmp_gt_f32_e64 s[22:23], 0, v109
	v_lshlrev_b32_e32 v112, 16, v90
	v_and_b32_e32 v113, 0xffff0000, v90
	v_cndmask_b32_e64 v108, v128, v222, s[8:9]
	v_cndmask_b32_e64 v109, v129, v223, s[22:23]
	v_pk_mul_f32 v[108:109], v[108:109], v[112:113]
	v_cvt_pk_bf16_f32 v228, v108, v109
	v_pk_mul_f32 v[130:131], v[224:225], v[130:131]
	v_pk_mul_f32 v[224:225], v[110:111], v[130:131]
	v_pk_fma_f32 v[130:131], v[110:111], v[130:131], v[110:111] neg_lo:[1,0,0] neg_hi:[1,0,0]
	v_cmp_gt_f32_e64 s[8:9], 0, v110
	v_cmp_gt_f32_e64 s[22:23], 0, v111
	v_lshlrev_b32_e32 v112, 16, v91
	v_and_b32_e32 v113, 0xffff0000, v91
	v_cndmask_b32_e64 v110, v130, v224, s[8:9]
	v_cndmask_b32_e64 v111, v131, v225, s[22:23]
	v_pk_mul_f32 v[110:111], v[110:111], v[112:113]
	v_cvt_pk_bf16_f32 v229, v110, v111
	global_store_dwordx4 v140, v[226:229], s[14:15]
	v_add_u32_e32 v140, 0x2c00, v140
	global_load_dwordx4 v[170:173], v136, s[14:15]
	global_load_dwordx4 v[174:177], v137, s[14:15]
	global_load_dwordx4 v[178:181], v138, s[14:15]
	v_add_u32_e32 v136, 0x2c00, v136
	v_add_u32_e32 v137, 0x2c00, v137
	v_add_u32_e32 v138, 0x2c00, v138
	global_load_dwordx4 v[84:87], v139, s[14:15]
	v_add_u32_e32 v139, 0x2c00, v139
	s_waitcnt vmcnt(16)
	v_mov_b64_e32 v[104:105], v[72:73]
	v_mov_b64_e32 v[106:107], v[74:75]
	v_mov_b64_e32 v[108:109], v[76:77]
	v_mov_b64_e32 v[110:111], v[78:79]
	v_lshlrev_b32_e32 v112, 16, v182
	v_and_b32_e32 v113, 0xffff0000, v182
	v_pk_fma_f32 v[104:105], v[112:113], v[0:1], v[104:105]
	v_lshlrev_b32_e32 v114, 16, v183
	v_and_b32_e32 v115, 0xffff0000, v183
	v_pk_fma_f32 v[106:107], v[114:115], v[2:3], v[106:107]
	v_lshlrev_b32_e32 v112, 16, v184
	v_and_b32_e32 v113, 0xffff0000, v184
	v_pk_fma_f32 v[108:109], v[112:113], v[4:5], v[108:109]
	v_lshlrev_b32_e32 v114, 16, v185
	v_and_b32_e32 v115, 0xffff0000, v185
	v_pk_fma_f32 v[110:111], v[114:115], v[6:7], v[110:111]
	v_lshlrev_b32_e32 v112, 16, v194
	v_and_b32_e32 v113, 0xffff0000, v194
	v_pk_fma_f32 v[104:105], v[112:113], v[8:9], v[104:105]
	v_lshlrev_b32_e32 v114, 16, v195
	v_and_b32_e32 v115, 0xffff0000, v195
	v_pk_fma_f32 v[106:107], v[114:115], v[10:11], v[106:107]
	v_lshlrev_b32_e32 v112, 16, v196
	v_and_b32_e32 v113, 0xffff0000, v196
	v_pk_fma_f32 v[108:109], v[112:113], v[12:13], v[108:109]
	v_lshlrev_b32_e32 v114, 16, v197
	v_and_b32_e32 v115, 0xffff0000, v197
	v_pk_fma_f32 v[110:111], v[114:115], v[14:15], v[110:111]
	v_lshlrev_b32_e32 v112, 16, v206
	v_and_b32_e32 v113, 0xffff0000, v206
	v_pk_fma_f32 v[104:105], v[112:113], v[16:17], v[104:105]
	v_lshlrev_b32_e32 v114, 16, v207
	v_and_b32_e32 v115, 0xffff0000, v207
	v_pk_fma_f32 v[106:107], v[114:115], v[18:19], v[106:107]
	v_lshlrev_b32_e32 v112, 16, v208
	v_and_b32_e32 v113, 0xffff0000, v208
	v_pk_fma_f32 v[108:109], v[112:113], v[20:21], v[108:109]
	v_lshlrev_b32_e32 v114, 16, v209
	v_and_b32_e32 v115, 0xffff0000, v209
	v_pk_fma_f32 v[110:111], v[114:115], v[22:23], v[110:111]
	v_lshlrev_b32_e32 v112, 16, v186
	v_and_b32_e32 v113, 0xffff0000, v186
	v_pk_fma_f32 v[104:105], v[112:113], v[24:25], v[104:105]
	v_lshlrev_b32_e32 v114, 16, v187
	v_and_b32_e32 v115, 0xffff0000, v187
	v_pk_fma_f32 v[106:107], v[114:115], v[26:27], v[106:107]
	v_lshlrev_b32_e32 v112, 16, v188
	v_and_b32_e32 v113, 0xffff0000, v188
	v_pk_fma_f32 v[108:109], v[112:113], v[28:29], v[108:109]
	v_lshlrev_b32_e32 v114, 16, v189
	v_and_b32_e32 v115, 0xffff0000, v189
	v_pk_fma_f32 v[110:111], v[114:115], v[30:31], v[110:111]
	v_lshlrev_b32_e32 v112, 16, v198
	v_and_b32_e32 v113, 0xffff0000, v198
	v_pk_fma_f32 v[104:105], v[112:113], v[32:33], v[104:105]
	v_lshlrev_b32_e32 v114, 16, v199
	v_and_b32_e32 v115, 0xffff0000, v199
	v_pk_fma_f32 v[106:107], v[114:115], v[34:35], v[106:107]
	v_lshlrev_b32_e32 v112, 16, v200
	v_and_b32_e32 v113, 0xffff0000, v200
	v_pk_fma_f32 v[108:109], v[112:113], v[36:37], v[108:109]
	v_lshlrev_b32_e32 v114, 16, v201
	v_and_b32_e32 v115, 0xffff0000, v201
	v_pk_fma_f32 v[110:111], v[114:115], v[38:39], v[110:111]
	v_lshlrev_b32_e32 v112, 16, v210
	v_and_b32_e32 v113, 0xffff0000, v210
	v_pk_fma_f32 v[104:105], v[112:113], v[40:41], v[104:105]
	v_lshlrev_b32_e32 v114, 16, v211
	v_and_b32_e32 v115, 0xffff0000, v211
	v_pk_fma_f32 v[106:107], v[114:115], v[42:43], v[106:107]
	v_lshlrev_b32_e32 v112, 16, v212
	v_and_b32_e32 v113, 0xffff0000, v212
	v_pk_fma_f32 v[108:109], v[112:113], v[44:45], v[108:109]
	v_lshlrev_b32_e32 v114, 16, v213
	v_and_b32_e32 v115, 0xffff0000, v213
	v_pk_fma_f32 v[110:111], v[114:115], v[46:47], v[110:111]
	v_lshlrev_b32_e32 v112, 16, v190
	v_and_b32_e32 v113, 0xffff0000, v190
	v_pk_fma_f32 v[104:105], v[112:113], v[48:49], v[104:105]
	v_lshlrev_b32_e32 v114, 16, v191
	v_and_b32_e32 v115, 0xffff0000, v191
	v_pk_fma_f32 v[106:107], v[114:115], v[50:51], v[106:107]
	v_lshlrev_b32_e32 v112, 16, v192
	v_and_b32_e32 v113, 0xffff0000, v192
	v_pk_fma_f32 v[108:109], v[112:113], v[52:53], v[108:109]
	v_lshlrev_b32_e32 v114, 16, v193
	v_and_b32_e32 v115, 0xffff0000, v193
	v_pk_fma_f32 v[110:111], v[114:115], v[54:55], v[110:111]
	v_lshlrev_b32_e32 v112, 16, v202
	v_and_b32_e32 v113, 0xffff0000, v202
	v_pk_fma_f32 v[104:105], v[112:113], v[56:57], v[104:105]
	v_lshlrev_b32_e32 v114, 16, v203
	v_and_b32_e32 v115, 0xffff0000, v203
	v_pk_fma_f32 v[106:107], v[114:115], v[58:59], v[106:107]
	v_lshlrev_b32_e32 v112, 16, v204
	v_and_b32_e32 v113, 0xffff0000, v204
	v_pk_fma_f32 v[108:109], v[112:113], v[60:61], v[108:109]
	v_lshlrev_b32_e32 v114, 16, v205
	v_and_b32_e32 v115, 0xffff0000, v205
	v_pk_fma_f32 v[110:111], v[114:115], v[62:63], v[110:111]
	v_lshlrev_b32_e32 v112, 16, v214
	v_and_b32_e32 v113, 0xffff0000, v214
	v_pk_fma_f32 v[104:105], v[112:113], v[64:65], v[104:105]
	v_lshlrev_b32_e32 v114, 16, v215
	v_and_b32_e32 v115, 0xffff0000, v215
	v_pk_fma_f32 v[106:107], v[114:115], v[66:67], v[106:107]
	v_lshlrev_b32_e32 v112, 16, v216
	v_and_b32_e32 v113, 0xffff0000, v216
	v_pk_fma_f32 v[108:109], v[112:113], v[68:69], v[108:109]
	v_lshlrev_b32_e32 v114, 16, v217
	v_and_b32_e32 v115, 0xffff0000, v217
	v_pk_fma_f32 v[110:111], v[114:115], v[70:71], v[110:111]
	v_mov_b64_e32 v[132:133], s[28:29]
	v_and_b32_e32 v116, 0x7fffffff, v104
	v_and_b32_e32 v117, 0x7fffffff, v105
	v_pk_fma_f32 v[116:117], v[116:117], s[24:25], 1.0 op_sel_hi:[1,0,0]
	v_pk_mul_f32 v[218:219], v[104:105], v[104:105]
	v_rcp_f32_e32 v116, v116
	v_rcp_f32_e32 v117, v117
	v_pk_mul_f32 v[218:219], v[218:219], s[38:39] op_sel_hi:[1,0]
	v_and_b32_e32 v118, 0x7fffffff, v106
	v_and_b32_e32 v119, 0x7fffffff, v107
	v_pk_fma_f32 v[118:119], v[118:119], s[24:25], 1.0 op_sel_hi:[1,0,0]
	v_pk_mul_f32 v[220:221], v[106:107], v[106:107]
	v_rcp_f32_e32 v118, v118
	v_rcp_f32_e32 v119, v119
	v_pk_mul_f32 v[220:221], v[220:221], s[38:39] op_sel_hi:[1,0]
	v_and_b32_e32 v120, 0x7fffffff, v108
	v_and_b32_e32 v121, 0x7fffffff, v109
	v_pk_fma_f32 v[120:121], v[120:121], s[24:25], 1.0 op_sel_hi:[1,0,0]
	v_pk_mul_f32 v[222:223], v[108:109], v[108:109]
	v_rcp_f32_e32 v120, v120
	v_rcp_f32_e32 v121, v121
	v_pk_mul_f32 v[222:223], v[222:223], s[38:39] op_sel_hi:[1,0]
	v_and_b32_e32 v122, 0x7fffffff, v110
	v_and_b32_e32 v123, 0x7fffffff, v111
	v_pk_fma_f32 v[122:123], v[122:123], s[24:25], 1.0 op_sel_hi:[1,0,0]
	v_pk_mul_f32 v[224:225], v[110:111], v[110:111]
	v_rcp_f32_e32 v122, v122
	v_rcp_f32_e32 v123, v123
	v_pk_mul_f32 v[224:225], v[224:225], s[38:39] op_sel_hi:[1,0]
	v_pk_fma_f32 v[124:125], v[116:117], s[26:27], v[132:133] op_sel_hi:[1,0,0]
	v_exp_f32_e32 v218, v218
	v_pk_fma_f32 v[124:125], v[116:117], v[124:125], s[30:31] op_sel_hi:[1,1,0]
	v_exp_f32_e32 v219, v219
	v_pk_fma_f32 v[124:125], v[116:117], v[124:125], s[34:35] op_sel_hi:[1,1,0]
	v_pk_fma_f32 v[124:125], v[116:117], v[124:125], s[36:37] op_sel_hi:[1,1,0]
	v_pk_mul_f32 v[124:125], v[116:117], v[124:125]
	v_pk_fma_f32 v[126:127], v[118:119], s[26:27], v[132:133] op_sel_hi:[1,0,0]
	v_exp_f32_e32 v220, v220
	v_pk_fma_f32 v[126:127], v[118:119], v[126:127], s[30:31] op_sel_hi:[1,1,0]
	v_exp_f32_e32 v221, v221
	v_pk_fma_f32 v[126:127], v[118:119], v[126:127], s[34:35] op_sel_hi:[1,1,0]
	v_pk_fma_f32 v[126:127], v[118:119], v[126:127], s[36:37] op_sel_hi:[1,1,0]
	v_pk_mul_f32 v[126:127], v[118:119], v[126:127]
	v_pk_fma_f32 v[128:129], v[120:121], s[26:27], v[132:133] op_sel_hi:[1,0,0]
	v_exp_f32_e32 v222, v222
	v_pk_fma_f32 v[128:129], v[120:121], v[128:129], s[30:31] op_sel_hi:[1,1,0]
	v_exp_f32_e32 v223, v223
	v_pk_fma_f32 v[128:129], v[120:121], v[128:129], s[34:35] op_sel_hi:[1,1,0]
	v_pk_fma_f32 v[128:129], v[120:121], v[128:129], s[36:37] op_sel_hi:[1,1,0]
	v_pk_mul_f32 v[128:129], v[120:121], v[128:129]
	v_pk_fma_f32 v[130:131], v[122:123], s[26:27], v[132:133] op_sel_hi:[1,0,0]
	v_exp_f32_e32 v224, v224
	v_pk_fma_f32 v[130:131], v[122:123], v[130:131], s[30:31] op_sel_hi:[1,1,0]
	v_exp_f32_e32 v225, v225
	v_pk_fma_f32 v[130:131], v[122:123], v[130:131], s[34:35] op_sel_hi:[1,1,0]
	v_pk_fma_f32 v[130:131], v[122:123], v[130:131], s[36:37] op_sel_hi:[1,1,0]
	v_pk_mul_f32 v[130:131], v[122:123], v[130:131]
	v_pk_mul_f32 v[124:125], v[218:219], v[124:125]
	v_pk_mul_f32 v[218:219], v[104:105], v[124:125]
	v_pk_fma_f32 v[124:125], v[104:105], v[124:125], v[104:105] neg_lo:[1,0,0] neg_hi:[1,0,0]
	v_cmp_gt_f32_e64 s[8:9], 0, v104
	v_cmp_gt_f32_e64 s[22:23], 0, v105
	v_lshlrev_b32_e32 v112, 16, v92
	v_and_b32_e32 v113, 0xffff0000, v92
	v_cndmask_b32_e64 v104, v124, v218, s[8:9]
	v_cndmask_b32_e64 v105, v125, v219, s[22:23]
	v_pk_mul_f32 v[104:105], v[104:105], v[112:113]
	v_cvt_pk_bf16_f32 v226, v104, v105
	v_pk_mul_f32 v[126:127], v[220:221], v[126:127]
	v_pk_mul_f32 v[220:221], v[106:107], v[126:127]
	v_pk_fma_f32 v[126:127], v[106:107], v[126:127], v[106:107] neg_lo:[1,0,0] neg_hi:[1,0,0]
	v_cmp_gt_f32_e64 s[8:9], 0, v106
	v_cmp_gt_f32_e64 s[22:23], 0, v107
	v_lshlrev_b32_e32 v112, 16, v93
	v_and_b32_e32 v113, 0xffff0000, v93
	v_cndmask_b32_e64 v106, v126, v220, s[8:9]
	v_cndmask_b32_e64 v107, v127, v221, s[22:23]
	v_pk_mul_f32 v[106:107], v[106:107], v[112:113]
	v_cvt_pk_bf16_f32 v227, v106, v107
	v_pk_mul_f32 v[128:129], v[222:223], v[128:129]
	v_pk_mul_f32 v[222:223], v[108:109], v[128:129]
	v_pk_fma_f32 v[128:129], v[108:109], v[128:129], v[108:109] neg_lo:[1,0,0] neg_hi:[1,0,0]
	v_cmp_gt_f32_e64 s[8:9], 0, v108
	v_cmp_gt_f32_e64 s[22:23], 0, v109
	v_lshlrev_b32_e32 v112, 16, v94
	v_and_b32_e32 v113, 0xffff0000, v94
	v_cndmask_b32_e64 v108, v128, v222, s[8:9]
	v_cndmask_b32_e64 v109, v129, v223, s[22:23]
	v_pk_mul_f32 v[108:109], v[108:109], v[112:113]
	v_cvt_pk_bf16_f32 v228, v108, v109
	v_pk_mul_f32 v[130:131], v[224:225], v[130:131]
	v_pk_mul_f32 v[224:225], v[110:111], v[130:131]
	v_pk_fma_f32 v[130:131], v[110:111], v[130:131], v[110:111] neg_lo:[1,0,0] neg_hi:[1,0,0]
	v_cmp_gt_f32_e64 s[8:9], 0, v110
	v_cmp_gt_f32_e64 s[22:23], 0, v111
	v_lshlrev_b32_e32 v112, 16, v95
	v_and_b32_e32 v113, 0xffff0000, v95
	v_cndmask_b32_e64 v110, v130, v224, s[8:9]
	v_cndmask_b32_e64 v111, v131, v225, s[22:23]
	v_pk_mul_f32 v[110:111], v[110:111], v[112:113]
	v_cvt_pk_bf16_f32 v229, v110, v111
	global_store_dwordx4 v140, v[226:229], s[14:15]
	v_add_u32_e32 v140, 0x2c00, v140
	global_load_dwordx4 v[182:185], v136, s[14:15]
	global_load_dwordx4 v[186:189], v137, s[14:15]
	global_load_dwordx4 v[190:193], v138, s[14:15]
	v_add_u32_e32 v136, 0x2c00, v136
	v_add_u32_e32 v137, 0x2c00, v137
	v_add_u32_e32 v138, 0x2c00, v138
	global_load_dwordx4 v[88:91], v139, s[14:15]
	v_add_u32_e32 v139, 0x2c00, v139
	s_waitcnt vmcnt(16)
	v_mov_b64_e32 v[104:105], v[72:73]
	v_mov_b64_e32 v[106:107], v[74:75]
	v_mov_b64_e32 v[108:109], v[76:77]
	v_mov_b64_e32 v[110:111], v[78:79]
	v_lshlrev_b32_e32 v112, 16, v194
	v_and_b32_e32 v113, 0xffff0000, v194
	v_pk_fma_f32 v[104:105], v[112:113], v[0:1], v[104:105]
	v_lshlrev_b32_e32 v114, 16, v195
	v_and_b32_e32 v115, 0xffff0000, v195
	v_pk_fma_f32 v[106:107], v[114:115], v[2:3], v[106:107]
	v_lshlrev_b32_e32 v112, 16, v196
	v_and_b32_e32 v113, 0xffff0000, v196
	v_pk_fma_f32 v[108:109], v[112:113], v[4:5], v[108:109]
	v_lshlrev_b32_e32 v114, 16, v197
	v_and_b32_e32 v115, 0xffff0000, v197
	v_pk_fma_f32 v[110:111], v[114:115], v[6:7], v[110:111]
	v_lshlrev_b32_e32 v112, 16, v206
	v_and_b32_e32 v113, 0xffff0000, v206
	v_pk_fma_f32 v[104:105], v[112:113], v[8:9], v[104:105]
	v_lshlrev_b32_e32 v114, 16, v207
	v_and_b32_e32 v115, 0xffff0000, v207
	v_pk_fma_f32 v[106:107], v[114:115], v[10:11], v[106:107]
	v_lshlrev_b32_e32 v112, 16, v208
	v_and_b32_e32 v113, 0xffff0000, v208
	v_pk_fma_f32 v[108:109], v[112:113], v[12:13], v[108:109]
	v_lshlrev_b32_e32 v114, 16, v209
	v_and_b32_e32 v115, 0xffff0000, v209
	v_pk_fma_f32 v[110:111], v[114:115], v[14:15], v[110:111]
	v_lshlrev_b32_e32 v112, 16, v146
	v_and_b32_e32 v113, 0xffff0000, v146
	v_pk_fma_f32 v[104:105], v[112:113], v[16:17], v[104:105]
	v_lshlrev_b32_e32 v114, 16, v147
	v_and_b32_e32 v115, 0xffff0000, v147
	v_pk_fma_f32 v[106:107], v[114:115], v[18:19], v[106:107]
	v_lshlrev_b32_e32 v112, 16, v148
	v_and_b32_e32 v113, 0xffff0000, v148
	v_pk_fma_f32 v[108:109], v[112:113], v[20:21], v[108:109]
	v_lshlrev_b32_e32 v114, 16, v149
	v_and_b32_e32 v115, 0xffff0000, v149
	v_pk_fma_f32 v[110:111], v[114:115], v[22:23], v[110:111]
	v_lshlrev_b32_e32 v112, 16, v198
	v_and_b32_e32 v113, 0xffff0000, v198
	v_pk_fma_f32 v[104:105], v[112:113], v[24:25], v[104:105]
	v_lshlrev_b32_e32 v114, 16, v199
	v_and_b32_e32 v115, 0xffff0000, v199
	v_pk_fma_f32 v[106:107], v[114:115], v[26:27], v[106:107]
	v_lshlrev_b32_e32 v112, 16, v200
	v_and_b32_e32 v113, 0xffff0000, v200
	v_pk_fma_f32 v[108:109], v[112:113], v[28:29], v[108:109]
	v_lshlrev_b32_e32 v114, 16, v201
	v_and_b32_e32 v115, 0xffff0000, v201
	v_pk_fma_f32 v[110:111], v[114:115], v[30:31], v[110:111]
	v_lshlrev_b32_e32 v112, 16, v210
	v_and_b32_e32 v113, 0xffff0000, v210
	v_pk_fma_f32 v[104:105], v[112:113], v[32:33], v[104:105]
	v_lshlrev_b32_e32 v114, 16, v211
	v_and_b32_e32 v115, 0xffff0000, v211
	v_pk_fma_f32 v[106:107], v[114:115], v[34:35], v[106:107]
	v_lshlrev_b32_e32 v112, 16, v212
	v_and_b32_e32 v113, 0xffff0000, v212
	v_pk_fma_f32 v[108:109], v[112:113], v[36:37], v[108:109]
	v_lshlrev_b32_e32 v114, 16, v213
	v_and_b32_e32 v115, 0xffff0000, v213
	v_pk_fma_f32 v[110:111], v[114:115], v[38:39], v[110:111]
	v_lshlrev_b32_e32 v112, 16, v150
	v_and_b32_e32 v113, 0xffff0000, v150
	v_pk_fma_f32 v[104:105], v[112:113], v[40:41], v[104:105]
	v_lshlrev_b32_e32 v114, 16, v151
	v_and_b32_e32 v115, 0xffff0000, v151
	v_pk_fma_f32 v[106:107], v[114:115], v[42:43], v[106:107]
	v_lshlrev_b32_e32 v112, 16, v152
	v_and_b32_e32 v113, 0xffff0000, v152
	v_pk_fma_f32 v[108:109], v[112:113], v[44:45], v[108:109]
	v_lshlrev_b32_e32 v114, 16, v153
	v_and_b32_e32 v115, 0xffff0000, v153
	v_pk_fma_f32 v[110:111], v[114:115], v[46:47], v[110:111]
	v_lshlrev_b32_e32 v112, 16, v202
	v_and_b32_e32 v113, 0xffff0000, v202
	v_pk_fma_f32 v[104:105], v[112:113], v[48:49], v[104:105]
	v_lshlrev_b32_e32 v114, 16, v203
	v_and_b32_e32 v115, 0xffff0000, v203
	v_pk_fma_f32 v[106:107], v[114:115], v[50:51], v[106:107]
	v_lshlrev_b32_e32 v112, 16, v204
	v_and_b32_e32 v113, 0xffff0000, v204
	v_pk_fma_f32 v[108:109], v[112:113], v[52:53], v[108:109]
	v_lshlrev_b32_e32 v114, 16, v205
	v_and_b32_e32 v115, 0xffff0000, v205
	v_pk_fma_f32 v[110:111], v[114:115], v[54:55], v[110:111]
	v_lshlrev_b32_e32 v112, 16, v214
	v_and_b32_e32 v113, 0xffff0000, v214
	v_pk_fma_f32 v[104:105], v[112:113], v[56:57], v[104:105]
	v_lshlrev_b32_e32 v114, 16, v215
	v_and_b32_e32 v115, 0xffff0000, v215
	v_pk_fma_f32 v[106:107], v[114:115], v[58:59], v[106:107]
	v_lshlrev_b32_e32 v112, 16, v216
	v_and_b32_e32 v113, 0xffff0000, v216
	v_pk_fma_f32 v[108:109], v[112:113], v[60:61], v[108:109]
	v_lshlrev_b32_e32 v114, 16, v217
	v_and_b32_e32 v115, 0xffff0000, v217
	v_pk_fma_f32 v[110:111], v[114:115], v[62:63], v[110:111]
	v_lshlrev_b32_e32 v112, 16, v154
	v_and_b32_e32 v113, 0xffff0000, v154
	v_pk_fma_f32 v[104:105], v[112:113], v[64:65], v[104:105]
	v_lshlrev_b32_e32 v114, 16, v155
	v_and_b32_e32 v115, 0xffff0000, v155
	v_pk_fma_f32 v[106:107], v[114:115], v[66:67], v[106:107]
	v_lshlrev_b32_e32 v112, 16, v156
	v_and_b32_e32 v113, 0xffff0000, v156
	v_pk_fma_f32 v[108:109], v[112:113], v[68:69], v[108:109]
	v_lshlrev_b32_e32 v114, 16, v157
	v_and_b32_e32 v115, 0xffff0000, v157
	v_pk_fma_f32 v[110:111], v[114:115], v[70:71], v[110:111]
	v_mov_b64_e32 v[132:133], s[28:29]
	v_and_b32_e32 v116, 0x7fffffff, v104
	v_and_b32_e32 v117, 0x7fffffff, v105
	v_pk_fma_f32 v[116:117], v[116:117], s[24:25], 1.0 op_sel_hi:[1,0,0]
	v_pk_mul_f32 v[218:219], v[104:105], v[104:105]
	v_rcp_f32_e32 v116, v116
	v_rcp_f32_e32 v117, v117
	v_pk_mul_f32 v[218:219], v[218:219], s[38:39] op_sel_hi:[1,0]
	v_and_b32_e32 v118, 0x7fffffff, v106
	v_and_b32_e32 v119, 0x7fffffff, v107
	v_pk_fma_f32 v[118:119], v[118:119], s[24:25], 1.0 op_sel_hi:[1,0,0]
	v_pk_mul_f32 v[220:221], v[106:107], v[106:107]
	v_rcp_f32_e32 v118, v118
	v_rcp_f32_e32 v119, v119
	v_pk_mul_f32 v[220:221], v[220:221], s[38:39] op_sel_hi:[1,0]
	v_and_b32_e32 v120, 0x7fffffff, v108
	v_and_b32_e32 v121, 0x7fffffff, v109
	v_pk_fma_f32 v[120:121], v[120:121], s[24:25], 1.0 op_sel_hi:[1,0,0]
	v_pk_mul_f32 v[222:223], v[108:109], v[108:109]
	v_rcp_f32_e32 v120, v120
	v_rcp_f32_e32 v121, v121
	v_pk_mul_f32 v[222:223], v[222:223], s[38:39] op_sel_hi:[1,0]
	v_and_b32_e32 v122, 0x7fffffff, v110
	v_and_b32_e32 v123, 0x7fffffff, v111
	v_pk_fma_f32 v[122:123], v[122:123], s[24:25], 1.0 op_sel_hi:[1,0,0]
	v_pk_mul_f32 v[224:225], v[110:111], v[110:111]
	v_rcp_f32_e32 v122, v122
	v_rcp_f32_e32 v123, v123
	v_pk_mul_f32 v[224:225], v[224:225], s[38:39] op_sel_hi:[1,0]
	v_pk_fma_f32 v[124:125], v[116:117], s[26:27], v[132:133] op_sel_hi:[1,0,0]
	v_exp_f32_e32 v218, v218
	v_pk_fma_f32 v[124:125], v[116:117], v[124:125], s[30:31] op_sel_hi:[1,1,0]
	v_exp_f32_e32 v219, v219
	v_pk_fma_f32 v[124:125], v[116:117], v[124:125], s[34:35] op_sel_hi:[1,1,0]
	v_pk_fma_f32 v[124:125], v[116:117], v[124:125], s[36:37] op_sel_hi:[1,1,0]
	v_pk_mul_f32 v[124:125], v[116:117], v[124:125]
	v_pk_fma_f32 v[126:127], v[118:119], s[26:27], v[132:133] op_sel_hi:[1,0,0]
	v_exp_f32_e32 v220, v220
	v_pk_fma_f32 v[126:127], v[118:119], v[126:127], s[30:31] op_sel_hi:[1,1,0]
	v_exp_f32_e32 v221, v221
	v_pk_fma_f32 v[126:127], v[118:119], v[126:127], s[34:35] op_sel_hi:[1,1,0]
	v_pk_fma_f32 v[126:127], v[118:119], v[126:127], s[36:37] op_sel_hi:[1,1,0]
	v_pk_mul_f32 v[126:127], v[118:119], v[126:127]
	v_pk_fma_f32 v[128:129], v[120:121], s[26:27], v[132:133] op_sel_hi:[1,0,0]
	v_exp_f32_e32 v222, v222
	v_pk_fma_f32 v[128:129], v[120:121], v[128:129], s[30:31] op_sel_hi:[1,1,0]
	v_exp_f32_e32 v223, v223
	v_pk_fma_f32 v[128:129], v[120:121], v[128:129], s[34:35] op_sel_hi:[1,1,0]
	v_pk_fma_f32 v[128:129], v[120:121], v[128:129], s[36:37] op_sel_hi:[1,1,0]
	v_pk_mul_f32 v[128:129], v[120:121], v[128:129]
	v_pk_fma_f32 v[130:131], v[122:123], s[26:27], v[132:133] op_sel_hi:[1,0,0]
	v_exp_f32_e32 v224, v224
	v_pk_fma_f32 v[130:131], v[122:123], v[130:131], s[30:31] op_sel_hi:[1,1,0]
	v_exp_f32_e32 v225, v225
	v_pk_fma_f32 v[130:131], v[122:123], v[130:131], s[34:35] op_sel_hi:[1,1,0]
	v_pk_fma_f32 v[130:131], v[122:123], v[130:131], s[36:37] op_sel_hi:[1,1,0]
	v_pk_mul_f32 v[130:131], v[122:123], v[130:131]
	v_pk_mul_f32 v[124:125], v[218:219], v[124:125]
	v_pk_mul_f32 v[218:219], v[104:105], v[124:125]
	v_pk_fma_f32 v[124:125], v[104:105], v[124:125], v[104:105] neg_lo:[1,0,0] neg_hi:[1,0,0]
	v_cmp_gt_f32_e64 s[8:9], 0, v104
	v_cmp_gt_f32_e64 s[22:23], 0, v105
	v_lshlrev_b32_e32 v112, 16, v96
	v_and_b32_e32 v113, 0xffff0000, v96
	v_cndmask_b32_e64 v104, v124, v218, s[8:9]
	v_cndmask_b32_e64 v105, v125, v219, s[22:23]
	v_pk_mul_f32 v[104:105], v[104:105], v[112:113]
	v_cvt_pk_bf16_f32 v226, v104, v105
	v_pk_mul_f32 v[126:127], v[220:221], v[126:127]
	v_pk_mul_f32 v[220:221], v[106:107], v[126:127]
	v_pk_fma_f32 v[126:127], v[106:107], v[126:127], v[106:107] neg_lo:[1,0,0] neg_hi:[1,0,0]
	v_cmp_gt_f32_e64 s[8:9], 0, v106
	v_cmp_gt_f32_e64 s[22:23], 0, v107
	v_lshlrev_b32_e32 v112, 16, v97
	v_and_b32_e32 v113, 0xffff0000, v97
	v_cndmask_b32_e64 v106, v126, v220, s[8:9]
	v_cndmask_b32_e64 v107, v127, v221, s[22:23]
	v_pk_mul_f32 v[106:107], v[106:107], v[112:113]
	v_cvt_pk_bf16_f32 v227, v106, v107
	v_pk_mul_f32 v[128:129], v[222:223], v[128:129]
	v_pk_mul_f32 v[222:223], v[108:109], v[128:129]
	v_pk_fma_f32 v[128:129], v[108:109], v[128:129], v[108:109] neg_lo:[1,0,0] neg_hi:[1,0,0]
	v_cmp_gt_f32_e64 s[8:9], 0, v108
	v_cmp_gt_f32_e64 s[22:23], 0, v109
	v_lshlrev_b32_e32 v112, 16, v98
	v_and_b32_e32 v113, 0xffff0000, v98
	v_cndmask_b32_e64 v108, v128, v222, s[8:9]
	v_cndmask_b32_e64 v109, v129, v223, s[22:23]
	v_pk_mul_f32 v[108:109], v[108:109], v[112:113]
	v_cvt_pk_bf16_f32 v228, v108, v109
	v_pk_mul_f32 v[130:131], v[224:225], v[130:131]
	v_pk_mul_f32 v[224:225], v[110:111], v[130:131]
	v_pk_fma_f32 v[130:131], v[110:111], v[130:131], v[110:111] neg_lo:[1,0,0] neg_hi:[1,0,0]
	v_cmp_gt_f32_e64 s[8:9], 0, v110
	v_cmp_gt_f32_e64 s[22:23], 0, v111
	v_lshlrev_b32_e32 v112, 16, v99
	v_and_b32_e32 v113, 0xffff0000, v99
	v_cndmask_b32_e64 v110, v130, v224, s[8:9]
	v_cndmask_b32_e64 v111, v131, v225, s[22:23]
	v_pk_mul_f32 v[110:111], v[110:111], v[112:113]
	v_cvt_pk_bf16_f32 v229, v110, v111
	global_store_dwordx4 v140, v[226:229], s[14:15]
	v_add_u32_e32 v140, 0x2c00, v140
	global_load_dwordx4 v[194:197], v136, s[14:15]
	global_load_dwordx4 v[198:201], v137, s[14:15]
	global_load_dwordx4 v[202:205], v138, s[14:15]
	v_add_u32_e32 v136, 0x2c00, v136
	v_add_u32_e32 v137, 0x2c00, v137
	v_add_u32_e32 v138, 0x2c00, v138
	global_load_dwordx4 v[92:95], v139, s[14:15]
	v_add_u32_e32 v139, 0x2c00, v139
	s_waitcnt vmcnt(16)
	v_mov_b64_e32 v[104:105], v[72:73]
	v_mov_b64_e32 v[106:107], v[74:75]
	v_mov_b64_e32 v[108:109], v[76:77]
	v_mov_b64_e32 v[110:111], v[78:79]
	v_lshlrev_b32_e32 v112, 16, v206
	v_and_b32_e32 v113, 0xffff0000, v206
	v_pk_fma_f32 v[104:105], v[112:113], v[0:1], v[104:105]
	v_lshlrev_b32_e32 v114, 16, v207
	v_and_b32_e32 v115, 0xffff0000, v207
	v_pk_fma_f32 v[106:107], v[114:115], v[2:3], v[106:107]
	v_lshlrev_b32_e32 v112, 16, v208
	v_and_b32_e32 v113, 0xffff0000, v208
	v_pk_fma_f32 v[108:109], v[112:113], v[4:5], v[108:109]
	v_lshlrev_b32_e32 v114, 16, v209
	v_and_b32_e32 v115, 0xffff0000, v209
	v_pk_fma_f32 v[110:111], v[114:115], v[6:7], v[110:111]
	v_lshlrev_b32_e32 v112, 16, v146
	v_and_b32_e32 v113, 0xffff0000, v146
	v_pk_fma_f32 v[104:105], v[112:113], v[8:9], v[104:105]
	v_lshlrev_b32_e32 v114, 16, v147
	v_and_b32_e32 v115, 0xffff0000, v147
	v_pk_fma_f32 v[106:107], v[114:115], v[10:11], v[106:107]
	v_lshlrev_b32_e32 v112, 16, v148
	v_and_b32_e32 v113, 0xffff0000, v148
	v_pk_fma_f32 v[108:109], v[112:113], v[12:13], v[108:109]
	v_lshlrev_b32_e32 v114, 16, v149
	v_and_b32_e32 v115, 0xffff0000, v149
	v_pk_fma_f32 v[110:111], v[114:115], v[14:15], v[110:111]
	v_lshlrev_b32_e32 v112, 16, v158
	v_and_b32_e32 v113, 0xffff0000, v158
	v_pk_fma_f32 v[104:105], v[112:113], v[16:17], v[104:105]
	v_lshlrev_b32_e32 v114, 16, v159
	v_and_b32_e32 v115, 0xffff0000, v159
	v_pk_fma_f32 v[106:107], v[114:115], v[18:19], v[106:107]
	v_lshlrev_b32_e32 v112, 16, v160
	v_and_b32_e32 v113, 0xffff0000, v160
	v_pk_fma_f32 v[108:109], v[112:113], v[20:21], v[108:109]
	v_lshlrev_b32_e32 v114, 16, v161
	v_and_b32_e32 v115, 0xffff0000, v161
	v_pk_fma_f32 v[110:111], v[114:115], v[22:23], v[110:111]
	v_lshlrev_b32_e32 v112, 16, v210
	v_and_b32_e32 v113, 0xffff0000, v210
	v_pk_fma_f32 v[104:105], v[112:113], v[24:25], v[104:105]
	v_lshlrev_b32_e32 v114, 16, v211
	v_and_b32_e32 v115, 0xffff0000, v211
	v_pk_fma_f32 v[106:107], v[114:115], v[26:27], v[106:107]
	v_lshlrev_b32_e32 v112, 16, v212
	v_and_b32_e32 v113, 0xffff0000, v212
	v_pk_fma_f32 v[108:109], v[112:113], v[28:29], v[108:109]
	v_lshlrev_b32_e32 v114, 16, v213
	v_and_b32_e32 v115, 0xffff0000, v213
	v_pk_fma_f32 v[110:111], v[114:115], v[30:31], v[110:111]
	v_lshlrev_b32_e32 v112, 16, v150
	v_and_b32_e32 v113, 0xffff0000, v150
	v_pk_fma_f32 v[104:105], v[112:113], v[32:33], v[104:105]
	v_lshlrev_b32_e32 v114, 16, v151
	v_and_b32_e32 v115, 0xffff0000, v151
	v_pk_fma_f32 v[106:107], v[114:115], v[34:35], v[106:107]
	v_lshlrev_b32_e32 v112, 16, v152
	v_and_b32_e32 v113, 0xffff0000, v152
	v_pk_fma_f32 v[108:109], v[112:113], v[36:37], v[108:109]
	v_lshlrev_b32_e32 v114, 16, v153
	v_and_b32_e32 v115, 0xffff0000, v153
	v_pk_fma_f32 v[110:111], v[114:115], v[38:39], v[110:111]
	v_lshlrev_b32_e32 v112, 16, v162
	v_and_b32_e32 v113, 0xffff0000, v162
	v_pk_fma_f32 v[104:105], v[112:113], v[40:41], v[104:105]
	v_lshlrev_b32_e32 v114, 16, v163
	v_and_b32_e32 v115, 0xffff0000, v163
	v_pk_fma_f32 v[106:107], v[114:115], v[42:43], v[106:107]
	v_lshlrev_b32_e32 v112, 16, v164
	v_and_b32_e32 v113, 0xffff0000, v164
	v_pk_fma_f32 v[108:109], v[112:113], v[44:45], v[108:109]
	v_lshlrev_b32_e32 v114, 16, v165
	v_and_b32_e32 v115, 0xffff0000, v165
	v_pk_fma_f32 v[110:111], v[114:115], v[46:47], v[110:111]
	v_lshlrev_b32_e32 v112, 16, v214
	v_and_b32_e32 v113, 0xffff0000, v214
	v_pk_fma_f32 v[104:105], v[112:113], v[48:49], v[104:105]
	v_lshlrev_b32_e32 v114, 16, v215
	v_and_b32_e32 v115, 0xffff0000, v215
	v_pk_fma_f32 v[106:107], v[114:115], v[50:51], v[106:107]
	v_lshlrev_b32_e32 v112, 16, v216
	v_and_b32_e32 v113, 0xffff0000, v216
	v_pk_fma_f32 v[108:109], v[112:113], v[52:53], v[108:109]
	v_lshlrev_b32_e32 v114, 16, v217
	v_and_b32_e32 v115, 0xffff0000, v217
	v_pk_fma_f32 v[110:111], v[114:115], v[54:55], v[110:111]
	v_lshlrev_b32_e32 v112, 16, v154
	v_and_b32_e32 v113, 0xffff0000, v154
	v_pk_fma_f32 v[104:105], v[112:113], v[56:57], v[104:105]
	v_lshlrev_b32_e32 v114, 16, v155
	v_and_b32_e32 v115, 0xffff0000, v155
	v_pk_fma_f32 v[106:107], v[114:115], v[58:59], v[106:107]
	v_lshlrev_b32_e32 v112, 16, v156
	v_and_b32_e32 v113, 0xffff0000, v156
	v_pk_fma_f32 v[108:109], v[112:113], v[60:61], v[108:109]
	v_lshlrev_b32_e32 v114, 16, v157
	v_and_b32_e32 v115, 0xffff0000, v157
	v_pk_fma_f32 v[110:111], v[114:115], v[62:63], v[110:111]
	v_lshlrev_b32_e32 v112, 16, v166
	v_and_b32_e32 v113, 0xffff0000, v166
	v_pk_fma_f32 v[104:105], v[112:113], v[64:65], v[104:105]
	v_lshlrev_b32_e32 v114, 16, v167
	v_and_b32_e32 v115, 0xffff0000, v167
	v_pk_fma_f32 v[106:107], v[114:115], v[66:67], v[106:107]
	v_lshlrev_b32_e32 v112, 16, v168
	v_and_b32_e32 v113, 0xffff0000, v168
	v_pk_fma_f32 v[108:109], v[112:113], v[68:69], v[108:109]
	v_lshlrev_b32_e32 v114, 16, v169
	v_and_b32_e32 v115, 0xffff0000, v169
	v_pk_fma_f32 v[110:111], v[114:115], v[70:71], v[110:111]
	v_mov_b64_e32 v[132:133], s[28:29]
	v_and_b32_e32 v116, 0x7fffffff, v104
	v_and_b32_e32 v117, 0x7fffffff, v105
	v_pk_fma_f32 v[116:117], v[116:117], s[24:25], 1.0 op_sel_hi:[1,0,0]
	v_pk_mul_f32 v[218:219], v[104:105], v[104:105]
	v_rcp_f32_e32 v116, v116
	v_rcp_f32_e32 v117, v117
	v_pk_mul_f32 v[218:219], v[218:219], s[38:39] op_sel_hi:[1,0]
	v_and_b32_e32 v118, 0x7fffffff, v106
	v_and_b32_e32 v119, 0x7fffffff, v107
	v_pk_fma_f32 v[118:119], v[118:119], s[24:25], 1.0 op_sel_hi:[1,0,0]
	v_pk_mul_f32 v[220:221], v[106:107], v[106:107]
	v_rcp_f32_e32 v118, v118
	v_rcp_f32_e32 v119, v119
	v_pk_mul_f32 v[220:221], v[220:221], s[38:39] op_sel_hi:[1,0]
	v_and_b32_e32 v120, 0x7fffffff, v108
	v_and_b32_e32 v121, 0x7fffffff, v109
	v_pk_fma_f32 v[120:121], v[120:121], s[24:25], 1.0 op_sel_hi:[1,0,0]
	v_pk_mul_f32 v[222:223], v[108:109], v[108:109]
	v_rcp_f32_e32 v120, v120
	v_rcp_f32_e32 v121, v121
	v_pk_mul_f32 v[222:223], v[222:223], s[38:39] op_sel_hi:[1,0]
	v_and_b32_e32 v122, 0x7fffffff, v110
	v_and_b32_e32 v123, 0x7fffffff, v111
	v_pk_fma_f32 v[122:123], v[122:123], s[24:25], 1.0 op_sel_hi:[1,0,0]
	v_pk_mul_f32 v[224:225], v[110:111], v[110:111]
	v_rcp_f32_e32 v122, v122
	v_rcp_f32_e32 v123, v123
	v_pk_mul_f32 v[224:225], v[224:225], s[38:39] op_sel_hi:[1,0]
	v_pk_fma_f32 v[124:125], v[116:117], s[26:27], v[132:133] op_sel_hi:[1,0,0]
	v_exp_f32_e32 v218, v218
	v_pk_fma_f32 v[124:125], v[116:117], v[124:125], s[30:31] op_sel_hi:[1,1,0]
	v_exp_f32_e32 v219, v219
	v_pk_fma_f32 v[124:125], v[116:117], v[124:125], s[34:35] op_sel_hi:[1,1,0]
	v_pk_fma_f32 v[124:125], v[116:117], v[124:125], s[36:37] op_sel_hi:[1,1,0]
	v_pk_mul_f32 v[124:125], v[116:117], v[124:125]
	v_pk_fma_f32 v[126:127], v[118:119], s[26:27], v[132:133] op_sel_hi:[1,0,0]
	v_exp_f32_e32 v220, v220
	v_pk_fma_f32 v[126:127], v[118:119], v[126:127], s[30:31] op_sel_hi:[1,1,0]
	v_exp_f32_e32 v221, v221
	v_pk_fma_f32 v[126:127], v[118:119], v[126:127], s[34:35] op_sel_hi:[1,1,0]
	v_pk_fma_f32 v[126:127], v[118:119], v[126:127], s[36:37] op_sel_hi:[1,1,0]
	v_pk_mul_f32 v[126:127], v[118:119], v[126:127]
	v_pk_fma_f32 v[128:129], v[120:121], s[26:27], v[132:133] op_sel_hi:[1,0,0]
	v_exp_f32_e32 v222, v222
	v_pk_fma_f32 v[128:129], v[120:121], v[128:129], s[30:31] op_sel_hi:[1,1,0]
	v_exp_f32_e32 v223, v223
	v_pk_fma_f32 v[128:129], v[120:121], v[128:129], s[34:35] op_sel_hi:[1,1,0]
	v_pk_fma_f32 v[128:129], v[120:121], v[128:129], s[36:37] op_sel_hi:[1,1,0]
	v_pk_mul_f32 v[128:129], v[120:121], v[128:129]
	v_pk_fma_f32 v[130:131], v[122:123], s[26:27], v[132:133] op_sel_hi:[1,0,0]
	v_exp_f32_e32 v224, v224
	v_pk_fma_f32 v[130:131], v[122:123], v[130:131], s[30:31] op_sel_hi:[1,1,0]
	v_exp_f32_e32 v225, v225
	v_pk_fma_f32 v[130:131], v[122:123], v[130:131], s[34:35] op_sel_hi:[1,1,0]
	v_pk_fma_f32 v[130:131], v[122:123], v[130:131], s[36:37] op_sel_hi:[1,1,0]
	v_pk_mul_f32 v[130:131], v[122:123], v[130:131]
	v_pk_mul_f32 v[124:125], v[218:219], v[124:125]
	v_pk_mul_f32 v[218:219], v[104:105], v[124:125]
	v_pk_fma_f32 v[124:125], v[104:105], v[124:125], v[104:105] neg_lo:[1,0,0] neg_hi:[1,0,0]
	v_cmp_gt_f32_e64 s[8:9], 0, v104
	v_cmp_gt_f32_e64 s[22:23], 0, v105
	v_lshlrev_b32_e32 v112, 16, v100
	v_and_b32_e32 v113, 0xffff0000, v100
	v_cndmask_b32_e64 v104, v124, v218, s[8:9]
	v_cndmask_b32_e64 v105, v125, v219, s[22:23]
	v_pk_mul_f32 v[104:105], v[104:105], v[112:113]
	v_cvt_pk_bf16_f32 v226, v104, v105
	v_pk_mul_f32 v[126:127], v[220:221], v[126:127]
	v_pk_mul_f32 v[220:221], v[106:107], v[126:127]
	v_pk_fma_f32 v[126:127], v[106:107], v[126:127], v[106:107] neg_lo:[1,0,0] neg_hi:[1,0,0]
	v_cmp_gt_f32_e64 s[8:9], 0, v106
	v_cmp_gt_f32_e64 s[22:23], 0, v107
	v_lshlrev_b32_e32 v112, 16, v101
	v_and_b32_e32 v113, 0xffff0000, v101
	v_cndmask_b32_e64 v106, v126, v220, s[8:9]
	v_cndmask_b32_e64 v107, v127, v221, s[22:23]
	v_pk_mul_f32 v[106:107], v[106:107], v[112:113]
	v_cvt_pk_bf16_f32 v227, v106, v107
	v_pk_mul_f32 v[128:129], v[222:223], v[128:129]
	v_pk_mul_f32 v[222:223], v[108:109], v[128:129]
	v_pk_fma_f32 v[128:129], v[108:109], v[128:129], v[108:109] neg_lo:[1,0,0] neg_hi:[1,0,0]
	v_cmp_gt_f32_e64 s[8:9], 0, v108
	v_cmp_gt_f32_e64 s[22:23], 0, v109
	v_lshlrev_b32_e32 v112, 16, v102
	v_and_b32_e32 v113, 0xffff0000, v102
	v_cndmask_b32_e64 v108, v128, v222, s[8:9]
	v_cndmask_b32_e64 v109, v129, v223, s[22:23]
	v_pk_mul_f32 v[108:109], v[108:109], v[112:113]
	v_cvt_pk_bf16_f32 v228, v108, v109
	v_pk_mul_f32 v[130:131], v[224:225], v[130:131]
	v_pk_mul_f32 v[224:225], v[110:111], v[130:131]
	v_pk_fma_f32 v[130:131], v[110:111], v[130:131], v[110:111] neg_lo:[1,0,0] neg_hi:[1,0,0]
	v_cmp_gt_f32_e64 s[8:9], 0, v110
	v_cmp_gt_f32_e64 s[22:23], 0, v111
	v_lshlrev_b32_e32 v112, 16, v103
	v_and_b32_e32 v113, 0xffff0000, v103
	v_cndmask_b32_e64 v110, v130, v224, s[8:9]
	v_cndmask_b32_e64 v111, v131, v225, s[22:23]
	v_pk_mul_f32 v[110:111], v[110:111], v[112:113]
	v_cvt_pk_bf16_f32 v229, v110, v111
	global_store_dwordx4 v140, v[226:229], s[14:15]
	v_add_u32_e32 v140, 0x2c00, v140
	s_add_i32 s21, s21, -1
	s_cmp_lg_u32 s21, 0
	s_cbranch_scc1 .Lconv_cols
	s_waitcnt vmcnt(12)
	v_mov_b64_e32 v[104:105], v[72:73]
	v_mov_b64_e32 v[106:107], v[74:75]
	v_mov_b64_e32 v[108:109], v[76:77]
	v_mov_b64_e32 v[110:111], v[78:79]
	v_lshlrev_b32_e32 v112, 16, v146
	v_and_b32_e32 v113, 0xffff0000, v146
	v_pk_fma_f32 v[104:105], v[112:113], v[0:1], v[104:105]
	v_lshlrev_b32_e32 v114, 16, v147
	v_and_b32_e32 v115, 0xffff0000, v147
	v_pk_fma_f32 v[106:107], v[114:115], v[2:3], v[106:107]
	v_lshlrev_b32_e32 v112, 16, v148
	v_and_b32_e32 v113, 0xffff0000, v148
	v_pk_fma_f32 v[108:109], v[112:113], v[4:5], v[108:109]
	v_lshlrev_b32_e32 v114, 16, v149
	v_and_b32_e32 v115, 0xffff0000, v149
	v_pk_fma_f32 v[110:111], v[114:115], v[6:7], v[110:111]
	v_lshlrev_b32_e32 v112, 16, v158
	v_and_b32_e32 v113, 0xffff0000, v158
	v_pk_fma_f32 v[104:105], v[112:113], v[8:9], v[104:105]
	v_lshlrev_b32_e32 v114, 16, v159
	v_and_b32_e32 v115, 0xffff0000, v159
	v_pk_fma_f32 v[106:107], v[114:115], v[10:11], v[106:107]
	v_lshlrev_b32_e32 v112, 16, v160
	v_and_b32_e32 v113, 0xffff0000, v160
	v_pk_fma_f32 v[108:109], v[112:113], v[12:13], v[108:109]
	v_lshlrev_b32_e32 v114, 16, v161
	v_and_b32_e32 v115, 0xffff0000, v161
	v_pk_fma_f32 v[110:111], v[114:115], v[14:15], v[110:111]
	v_lshlrev_b32_e32 v112, 16, v170
	v_and_b32_e32 v113, 0xffff0000, v170
	v_pk_fma_f32 v[104:105], v[112:113], v[16:17], v[104:105]
	v_lshlrev_b32_e32 v114, 16, v171
	v_and_b32_e32 v115, 0xffff0000, v171
	v_pk_fma_f32 v[106:107], v[114:115], v[18:19], v[106:107]
	v_lshlrev_b32_e32 v112, 16, v172
	v_and_b32_e32 v113, 0xffff0000, v172
	v_pk_fma_f32 v[108:109], v[112:113], v[20:21], v[108:109]
	v_lshlrev_b32_e32 v114, 16, v173
	v_and_b32_e32 v115, 0xffff0000, v173
	v_pk_fma_f32 v[110:111], v[114:115], v[22:23], v[110:111]
	v_lshlrev_b32_e32 v112, 16, v150
	v_and_b32_e32 v113, 0xffff0000, v150
	v_pk_fma_f32 v[104:105], v[112:113], v[24:25], v[104:105]
	v_lshlrev_b32_e32 v114, 16, v151
	v_and_b32_e32 v115, 0xffff0000, v151
	v_pk_fma_f32 v[106:107], v[114:115], v[26:27], v[106:107]
	v_lshlrev_b32_e32 v112, 16, v152
	v_and_b32_e32 v113, 0xffff0000, v152
	v_pk_fma_f32 v[108:109], v[112:113], v[28:29], v[108:109]
	v_lshlrev_b32_e32 v114, 16, v153
	v_and_b32_e32 v115, 0xffff0000, v153
	v_pk_fma_f32 v[110:111], v[114:115], v[30:31], v[110:111]
	v_lshlrev_b32_e32 v112, 16, v162
	v_and_b32_e32 v113, 0xffff0000, v162
	v_pk_fma_f32 v[104:105], v[112:113], v[32:33], v[104:105]
	v_lshlrev_b32_e32 v114, 16, v163
	v_and_b32_e32 v115, 0xffff0000, v163
	v_pk_fma_f32 v[106:107], v[114:115], v[34:35], v[106:107]
	v_lshlrev_b32_e32 v112, 16, v164
	v_and_b32_e32 v113, 0xffff0000, v164
	v_pk_fma_f32 v[108:109], v[112:113], v[36:37], v[108:109]
	v_lshlrev_b32_e32 v114, 16, v165
	v_and_b32_e32 v115, 0xffff0000, v165
	v_pk_fma_f32 v[110:111], v[114:115], v[38:39], v[110:111]
	v_lshlrev_b32_e32 v112, 16, v174
	v_and_b32_e32 v113, 0xffff0000, v174
	v_pk_fma_f32 v[104:105], v[112:113], v[40:41], v[104:105]
	v_lshlrev_b32_e32 v114, 16, v175
	v_and_b32_e32 v115, 0xffff0000, v175
	v_pk_fma_f32 v[106:107], v[114:115], v[42:43], v[106:107]
	v_lshlrev_b32_e32 v112, 16, v176
	v_and_b32_e32 v113, 0xffff0000, v176
	v_pk_fma_f32 v[108:109], v[112:113], v[44:45], v[108:109]
	v_lshlrev_b32_e32 v114, 16, v177
	v_and_b32_e32 v115, 0xffff0000, v177
	v_pk_fma_f32 v[110:111], v[114:115], v[46:47], v[110:111]
	v_lshlrev_b32_e32 v112, 16, v154
	v_and_b32_e32 v113, 0xffff0000, v154
	v_pk_fma_f32 v[104:105], v[112:113], v[48:49], v[104:105]
	v_lshlrev_b32_e32 v114, 16, v155
	v_and_b32_e32 v115, 0xffff0000, v155
	v_pk_fma_f32 v[106:107], v[114:115], v[50:51], v[106:107]
	v_lshlrev_b32_e32 v112, 16, v156
	v_and_b32_e32 v113, 0xffff0000, v156
	v_pk_fma_f32 v[108:109], v[112:113], v[52:53], v[108:109]
	v_lshlrev_b32_e32 v114, 16, v157
	v_and_b32_e32 v115, 0xffff0000, v157
	v_pk_fma_f32 v[110:111], v[114:115], v[54:55], v[110:111]
	v_lshlrev_b32_e32 v112, 16, v166
	v_and_b32_e32 v113, 0xffff0000, v166
	v_pk_fma_f32 v[104:105], v[112:113], v[56:57], v[104:105]
	v_lshlrev_b32_e32 v114, 16, v167
	v_and_b32_e32 v115, 0xffff0000, v167
	v_pk_fma_f32 v[106:107], v[114:115], v[58:59], v[106:107]
	v_lshlrev_b32_e32 v112, 16, v168
	v_and_b32_e32 v113, 0xffff0000, v168
	v_pk_fma_f32 v[108:109], v[112:113], v[60:61], v[108:109]
	v_lshlrev_b32_e32 v114, 16, v169
	v_and_b32_e32 v115, 0xffff0000, v169
	v_pk_fma_f32 v[110:111], v[114:115], v[62:63], v[110:111]
	v_lshlrev_b32_e32 v112, 16, v178
	v_and_b32_e32 v113, 0xffff0000, v178
	v_pk_fma_f32 v[104:105], v[112:113], v[64:65], v[104:105]
	v_lshlrev_b32_e32 v114, 16, v179
	v_and_b32_e32 v115, 0xffff0000, v179
	v_pk_fma_f32 v[106:107], v[114:115], v[66:67], v[106:107]
	v_lshlrev_b32_e32 v112, 16, v180
	v_and_b32_e32 v113, 0xffff0000, v180
	v_pk_fma_f32 v[108:109], v[112:113], v[68:69], v[108:109]
	v_lshlrev_b32_e32 v114, 16, v181
	v_and_b32_e32 v115, 0xffff0000, v181
	v_pk_fma_f32 v[110:111], v[114:115], v[70:71], v[110:111]
	v_mov_b64_e32 v[132:133], s[28:29]
	v_and_b32_e32 v116, 0x7fffffff, v104
	v_and_b32_e32 v117, 0x7fffffff, v105
	v_pk_fma_f32 v[116:117], v[116:117], s[24:25], 1.0 op_sel_hi:[1,0,0]
	v_pk_mul_f32 v[218:219], v[104:105], v[104:105]
	v_rcp_f32_e32 v116, v116
	v_rcp_f32_e32 v117, v117
	v_pk_mul_f32 v[218:219], v[218:219], s[38:39] op_sel_hi:[1,0]
	v_and_b32_e32 v118, 0x7fffffff, v106
	v_and_b32_e32 v119, 0x7fffffff, v107
	v_pk_fma_f32 v[118:119], v[118:119], s[24:25], 1.0 op_sel_hi:[1,0,0]
	v_pk_mul_f32 v[220:221], v[106:107], v[106:107]
	v_rcp_f32_e32 v118, v118
	v_rcp_f32_e32 v119, v119
	v_pk_mul_f32 v[220:221], v[220:221], s[38:39] op_sel_hi:[1,0]
	v_and_b32_e32 v120, 0x7fffffff, v108
	v_and_b32_e32 v121, 0x7fffffff, v109
	v_pk_fma_f32 v[120:121], v[120:121], s[24:25], 1.0 op_sel_hi:[1,0,0]
	v_pk_mul_f32 v[222:223], v[108:109], v[108:109]
	v_rcp_f32_e32 v120, v120
	v_rcp_f32_e32 v121, v121
	v_pk_mul_f32 v[222:223], v[222:223], s[38:39] op_sel_hi:[1,0]
	v_and_b32_e32 v122, 0x7fffffff, v110
	v_and_b32_e32 v123, 0x7fffffff, v111
	v_pk_fma_f32 v[122:123], v[122:123], s[24:25], 1.0 op_sel_hi:[1,0,0]
	v_pk_mul_f32 v[224:225], v[110:111], v[110:111]
	v_rcp_f32_e32 v122, v122
	v_rcp_f32_e32 v123, v123
	v_pk_mul_f32 v[224:225], v[224:225], s[38:39] op_sel_hi:[1,0]
	v_pk_fma_f32 v[124:125], v[116:117], s[26:27], v[132:133] op_sel_hi:[1,0,0]
	v_exp_f32_e32 v218, v218
	v_pk_fma_f32 v[124:125], v[116:117], v[124:125], s[30:31] op_sel_hi:[1,1,0]
	v_exp_f32_e32 v219, v219
	v_pk_fma_f32 v[124:125], v[116:117], v[124:125], s[34:35] op_sel_hi:[1,1,0]
	v_pk_fma_f32 v[124:125], v[116:117], v[124:125], s[36:37] op_sel_hi:[1,1,0]
	v_pk_mul_f32 v[124:125], v[116:117], v[124:125]
	v_pk_fma_f32 v[126:127], v[118:119], s[26:27], v[132:133] op_sel_hi:[1,0,0]
	v_exp_f32_e32 v220, v220
	v_pk_fma_f32 v[126:127], v[118:119], v[126:127], s[30:31] op_sel_hi:[1,1,0]
	v_exp_f32_e32 v221, v221
	v_pk_fma_f32 v[126:127], v[118:119], v[126:127], s[34:35] op_sel_hi:[1,1,0]
	v_pk_fma_f32 v[126:127], v[118:119], v[126:127], s[36:37] op_sel_hi:[1,1,0]
	v_pk_mul_f32 v[126:127], v[118:119], v[126:127]
	v_pk_fma_f32 v[128:129], v[120:121], s[26:27], v[132:133] op_sel_hi:[1,0,0]
	v_exp_f32_e32 v222, v222
	v_pk_fma_f32 v[128:129], v[120:121], v[128:129], s[30:31] op_sel_hi:[1,1,0]
	v_exp_f32_e32 v223, v223
	v_pk_fma_f32 v[128:129], v[120:121], v[128:129], s[34:35] op_sel_hi:[1,1,0]
	v_pk_fma_f32 v[128:129], v[120:121], v[128:129], s[36:37] op_sel_hi:[1,1,0]
	v_pk_mul_f32 v[128:129], v[120:121], v[128:129]
	v_pk_fma_f32 v[130:131], v[122:123], s[26:27], v[132:133] op_sel_hi:[1,0,0]
	v_exp_f32_e32 v224, v224
	v_pk_fma_f32 v[130:131], v[122:123], v[130:131], s[30:31] op_sel_hi:[1,1,0]
	v_exp_f32_e32 v225, v225
	v_pk_fma_f32 v[130:131], v[122:123], v[130:131], s[34:35] op_sel_hi:[1,1,0]
	v_pk_fma_f32 v[130:131], v[122:123], v[130:131], s[36:37] op_sel_hi:[1,1,0]
	v_pk_mul_f32 v[130:131], v[122:123], v[130:131]
	v_pk_mul_f32 v[124:125], v[218:219], v[124:125]
	v_pk_mul_f32 v[218:219], v[104:105], v[124:125]
	v_pk_fma_f32 v[124:125], v[104:105], v[124:125], v[104:105] neg_lo:[1,0,0] neg_hi:[1,0,0]
	v_cmp_gt_f32_e64 s[8:9], 0, v104
	v_cmp_gt_f32_e64 s[22:23], 0, v105
	v_lshlrev_b32_e32 v112, 16, v80
	v_and_b32_e32 v113, 0xffff0000, v80
	v_cndmask_b32_e64 v104, v124, v218, s[8:9]
	v_cndmask_b32_e64 v105, v125, v219, s[22:23]
	v_pk_mul_f32 v[104:105], v[104:105], v[112:113]
	v_cvt_pk_bf16_f32 v226, v104, v105
	v_pk_mul_f32 v[126:127], v[220:221], v[126:127]
	v_pk_mul_f32 v[220:221], v[106:107], v[126:127]
	v_pk_fma_f32 v[126:127], v[106:107], v[126:127], v[106:107] neg_lo:[1,0,0] neg_hi:[1,0,0]
	v_cmp_gt_f32_e64 s[8:9], 0, v106
	v_cmp_gt_f32_e64 s[22:23], 0, v107
	v_lshlrev_b32_e32 v112, 16, v81
	v_and_b32_e32 v113, 0xffff0000, v81
	v_cndmask_b32_e64 v106, v126, v220, s[8:9]
	v_cndmask_b32_e64 v107, v127, v221, s[22:23]
	v_pk_mul_f32 v[106:107], v[106:107], v[112:113]
	v_cvt_pk_bf16_f32 v227, v106, v107
	v_pk_mul_f32 v[128:129], v[222:223], v[128:129]
	v_pk_mul_f32 v[222:223], v[108:109], v[128:129]
	v_pk_fma_f32 v[128:129], v[108:109], v[128:129], v[108:109] neg_lo:[1,0,0] neg_hi:[1,0,0]
	v_cmp_gt_f32_e64 s[8:9], 0, v108
	v_cmp_gt_f32_e64 s[22:23], 0, v109
	v_lshlrev_b32_e32 v112, 16, v82
	v_and_b32_e32 v113, 0xffff0000, v82
	v_cndmask_b32_e64 v108, v128, v222, s[8:9]
	v_cndmask_b32_e64 v109, v129, v223, s[22:23]
	v_pk_mul_f32 v[108:109], v[108:109], v[112:113]
	v_cvt_pk_bf16_f32 v228, v108, v109
	v_pk_mul_f32 v[130:131], v[224:225], v[130:131]
	v_pk_mul_f32 v[224:225], v[110:111], v[130:131]
	v_pk_fma_f32 v[130:131], v[110:111], v[130:131], v[110:111] neg_lo:[1,0,0] neg_hi:[1,0,0]
	v_cmp_gt_f32_e64 s[8:9], 0, v110
	v_cmp_gt_f32_e64 s[22:23], 0, v111
	v_lshlrev_b32_e32 v112, 16, v83
	v_and_b32_e32 v113, 0xffff0000, v83
	v_cndmask_b32_e64 v110, v130, v224, s[8:9]
	v_cndmask_b32_e64 v111, v131, v225, s[22:23]
	v_pk_mul_f32 v[110:111], v[110:111], v[112:113]
	v_cvt_pk_bf16_f32 v229, v110, v111
	global_store_dwordx4 v140, v[226:229], s[14:15]
	v_add_u32_e32 v140, 0x2c00, v140
	s_waitcnt vmcnt(8)
	v_cndmask_b32_e64 v182, v182, 0, s[6:7]
	v_cndmask_b32_e64 v183, v183, 0, s[6:7]
	v_cndmask_b32_e64 v184, v184, 0, s[6:7]
	v_cndmask_b32_e64 v185, v185, 0, s[6:7]
	v_cndmask_b32_e64 v186, v186, 0, s[6:7]
	v_cndmask_b32_e64 v187, v187, 0, s[6:7]
	v_cndmask_b32_e64 v188, v188, 0, s[6:7]
	v_cndmask_b32_e64 v189, v189, 0, s[6:7]
	v_cndmask_b32_e64 v190, v190, 0, s[6:7]
	v_cndmask_b32_e64 v191, v191, 0, s[6:7]
	v_cndmask_b32_e64 v192, v192, 0, s[6:7]
	v_cndmask_b32_e64 v193, v193, 0, s[6:7]
	v_mov_b64_e32 v[104:105], v[72:73]
	v_mov_b64_e32 v[106:107], v[74:75]
	v_mov_b64_e32 v[108:109], v[76:77]
	v_mov_b64_e32 v[110:111], v[78:79]
	v_lshlrev_b32_e32 v112, 16, v158
	v_and_b32_e32 v113, 0xffff0000, v158
	v_pk_fma_f32 v[104:105], v[112:113], v[0:1], v[104:105]
	v_lshlrev_b32_e32 v114, 16, v159
	v_and_b32_e32 v115, 0xffff0000, v159
	v_pk_fma_f32 v[106:107], v[114:115], v[2:3], v[106:107]
	v_lshlrev_b32_e32 v112, 16, v160
	v_and_b32_e32 v113, 0xffff0000, v160
	v_pk_fma_f32 v[108:109], v[112:113], v[4:5], v[108:109]
	v_lshlrev_b32_e32 v114, 16, v161
	v_and_b32_e32 v115, 0xffff0000, v161
	v_pk_fma_f32 v[110:111], v[114:115], v[6:7], v[110:111]
	v_lshlrev_b32_e32 v112, 16, v170
	v_and_b32_e32 v113, 0xffff0000, v170
	v_pk_fma_f32 v[104:105], v[112:113], v[8:9], v[104:105]
	v_lshlrev_b32_e32 v114, 16, v171
	v_and_b32_e32 v115, 0xffff0000, v171
	v_pk_fma_f32 v[106:107], v[114:115], v[10:11], v[106:107]
	v_lshlrev_b32_e32 v112, 16, v172
	v_and_b32_e32 v113, 0xffff0000, v172
	v_pk_fma_f32 v[108:109], v[112:113], v[12:13], v[108:109]
	v_lshlrev_b32_e32 v114, 16, v173
	v_and_b32_e32 v115, 0xffff0000, v173
	v_pk_fma_f32 v[110:111], v[114:115], v[14:15], v[110:111]
	v_lshlrev_b32_e32 v112, 16, v182
	v_and_b32_e32 v113, 0xffff0000, v182
	v_pk_fma_f32 v[104:105], v[112:113], v[16:17], v[104:105]
	v_lshlrev_b32_e32 v114, 16, v183
	v_and_b32_e32 v115, 0xffff0000, v183
	v_pk_fma_f32 v[106:107], v[114:115], v[18:19], v[106:107]
	v_lshlrev_b32_e32 v112, 16, v184
	v_and_b32_e32 v113, 0xffff0000, v184
	v_pk_fma_f32 v[108:109], v[112:113], v[20:21], v[108:109]
	v_lshlrev_b32_e32 v114, 16, v185
	v_and_b32_e32 v115, 0xffff0000, v185
	v_pk_fma_f32 v[110:111], v[114:115], v[22:23], v[110:111]
	v_lshlrev_b32_e32 v112, 16, v162
	v_and_b32_e32 v113, 0xffff0000, v162
	v_pk_fma_f32 v[104:105], v[112:113], v[24:25], v[104:105]
	v_lshlrev_b32_e32 v114, 16, v163
	v_and_b32_e32 v115, 0xffff0000, v163
	v_pk_fma_f32 v[106:107], v[114:115], v[26:27], v[106:107]
	v_lshlrev_b32_e32 v112, 16, v164
	v_and_b32_e32 v113, 0xffff0000, v164
	v_pk_fma_f32 v[108:109], v[112:113], v[28:29], v[108:109]
	v_lshlrev_b32_e32 v114, 16, v165
	v_and_b32_e32 v115, 0xffff0000, v165
	v_pk_fma_f32 v[110:111], v[114:115], v[30:31], v[110:111]
	v_lshlrev_b32_e32 v112, 16, v174
	v_and_b32_e32 v113, 0xffff0000, v174
	v_pk_fma_f32 v[104:105], v[112:113], v[32:33], v[104:105]
	v_lshlrev_b32_e32 v114, 16, v175
	v_and_b32_e32 v115, 0xffff0000, v175
	v_pk_fma_f32 v[106:107], v[114:115], v[34:35], v[106:107]
	v_lshlrev_b32_e32 v112, 16, v176
	v_and_b32_e32 v113, 0xffff0000, v176
	v_pk_fma_f32 v[108:109], v[112:113], v[36:37], v[108:109]
	v_lshlrev_b32_e32 v114, 16, v177
	v_and_b32_e32 v115, 0xffff0000, v177
	v_pk_fma_f32 v[110:111], v[114:115], v[38:39], v[110:111]
	v_lshlrev_b32_e32 v112, 16, v186
	v_and_b32_e32 v113, 0xffff0000, v186
	v_pk_fma_f32 v[104:105], v[112:113], v[40:41], v[104:105]
	v_lshlrev_b32_e32 v114, 16, v187
	v_and_b32_e32 v115, 0xffff0000, v187
	v_pk_fma_f32 v[106:107], v[114:115], v[42:43], v[106:107]
	v_lshlrev_b32_e32 v112, 16, v188
	v_and_b32_e32 v113, 0xffff0000, v188
	v_pk_fma_f32 v[108:109], v[112:113], v[44:45], v[108:109]
	v_lshlrev_b32_e32 v114, 16, v189
	v_and_b32_e32 v115, 0xffff0000, v189
	v_pk_fma_f32 v[110:111], v[114:115], v[46:47], v[110:111]
	v_lshlrev_b32_e32 v112, 16, v166
	v_and_b32_e32 v113, 0xffff0000, v166
	v_pk_fma_f32 v[104:105], v[112:113], v[48:49], v[104:105]
	v_lshlrev_b32_e32 v114, 16, v167
	v_and_b32_e32 v115, 0xffff0000, v167
	v_pk_fma_f32 v[106:107], v[114:115], v[50:51], v[106:107]
	v_lshlrev_b32_e32 v112, 16, v168
	v_and_b32_e32 v113, 0xffff0000, v168
	v_pk_fma_f32 v[108:109], v[112:113], v[52:53], v[108:109]
	v_lshlrev_b32_e32 v114, 16, v169
	v_and_b32_e32 v115, 0xffff0000, v169
	v_pk_fma_f32 v[110:111], v[114:115], v[54:55], v[110:111]
	v_lshlrev_b32_e32 v112, 16, v178
	v_and_b32_e32 v113, 0xffff0000, v178
	v_pk_fma_f32 v[104:105], v[112:113], v[56:57], v[104:105]
	v_lshlrev_b32_e32 v114, 16, v179
	v_and_b32_e32 v115, 0xffff0000, v179
	v_pk_fma_f32 v[106:107], v[114:115], v[58:59], v[106:107]
	v_lshlrev_b32_e32 v112, 16, v180
	v_and_b32_e32 v113, 0xffff0000, v180
	v_pk_fma_f32 v[108:109], v[112:113], v[60:61], v[108:109]
	v_lshlrev_b32_e32 v114, 16, v181
	v_and_b32_e32 v115, 0xffff0000, v181
	v_pk_fma_f32 v[110:111], v[114:115], v[62:63], v[110:111]
	v_lshlrev_b32_e32 v112, 16, v190
	v_and_b32_e32 v113, 0xffff0000, v190
	v_pk_fma_f32 v[104:105], v[112:113], v[64:65], v[104:105]
	v_lshlrev_b32_e32 v114, 16, v191
	v_and_b32_e32 v115, 0xffff0000, v191
	v_pk_fma_f32 v[106:107], v[114:115], v[66:67], v[106:107]
	v_lshlrev_b32_e32 v112, 16, v192
	v_and_b32_e32 v113, 0xffff0000, v192
	v_pk_fma_f32 v[108:109], v[112:113], v[68:69], v[108:109]
	v_lshlrev_b32_e32 v114, 16, v193
	v_and_b32_e32 v115, 0xffff0000, v193
	v_pk_fma_f32 v[110:111], v[114:115], v[70:71], v[110:111]
	v_mov_b64_e32 v[132:133], s[28:29]
	v_and_b32_e32 v116, 0x7fffffff, v104
	v_and_b32_e32 v117, 0x7fffffff, v105
	v_pk_fma_f32 v[116:117], v[116:117], s[24:25], 1.0 op_sel_hi:[1,0,0]
	v_pk_mul_f32 v[218:219], v[104:105], v[104:105]
	v_rcp_f32_e32 v116, v116
	v_rcp_f32_e32 v117, v117
	v_pk_mul_f32 v[218:219], v[218:219], s[38:39] op_sel_hi:[1,0]
	v_and_b32_e32 v118, 0x7fffffff, v106
	v_and_b32_e32 v119, 0x7fffffff, v107
	v_pk_fma_f32 v[118:119], v[118:119], s[24:25], 1.0 op_sel_hi:[1,0,0]
	v_pk_mul_f32 v[220:221], v[106:107], v[106:107]
	v_rcp_f32_e32 v118, v118
	v_rcp_f32_e32 v119, v119
	v_pk_mul_f32 v[220:221], v[220:221], s[38:39] op_sel_hi:[1,0]
	v_and_b32_e32 v120, 0x7fffffff, v108
	v_and_b32_e32 v121, 0x7fffffff, v109
	v_pk_fma_f32 v[120:121], v[120:121], s[24:25], 1.0 op_sel_hi:[1,0,0]
	v_pk_mul_f32 v[222:223], v[108:109], v[108:109]
	v_rcp_f32_e32 v120, v120
	v_rcp_f32_e32 v121, v121
	v_pk_mul_f32 v[222:223], v[222:223], s[38:39] op_sel_hi:[1,0]
	v_and_b32_e32 v122, 0x7fffffff, v110
	v_and_b32_e32 v123, 0x7fffffff, v111
	v_pk_fma_f32 v[122:123], v[122:123], s[24:25], 1.0 op_sel_hi:[1,0,0]
	v_pk_mul_f32 v[224:225], v[110:111], v[110:111]
	v_rcp_f32_e32 v122, v122
	v_rcp_f32_e32 v123, v123
	v_pk_mul_f32 v[224:225], v[224:225], s[38:39] op_sel_hi:[1,0]
	v_pk_fma_f32 v[124:125], v[116:117], s[26:27], v[132:133] op_sel_hi:[1,0,0]
	v_exp_f32_e32 v218, v218
	v_pk_fma_f32 v[124:125], v[116:117], v[124:125], s[30:31] op_sel_hi:[1,1,0]
	v_exp_f32_e32 v219, v219
	v_pk_fma_f32 v[124:125], v[116:117], v[124:125], s[34:35] op_sel_hi:[1,1,0]
	v_pk_fma_f32 v[124:125], v[116:117], v[124:125], s[36:37] op_sel_hi:[1,1,0]
	v_pk_mul_f32 v[124:125], v[116:117], v[124:125]
	v_pk_fma_f32 v[126:127], v[118:119], s[26:27], v[132:133] op_sel_hi:[1,0,0]
	v_exp_f32_e32 v220, v220
	v_pk_fma_f32 v[126:127], v[118:119], v[126:127], s[30:31] op_sel_hi:[1,1,0]
	v_exp_f32_e32 v221, v221
	v_pk_fma_f32 v[126:127], v[118:119], v[126:127], s[34:35] op_sel_hi:[1,1,0]
	v_pk_fma_f32 v[126:127], v[118:119], v[126:127], s[36:37] op_sel_hi:[1,1,0]
	v_pk_mul_f32 v[126:127], v[118:119], v[126:127]
	v_pk_fma_f32 v[128:129], v[120:121], s[26:27], v[132:133] op_sel_hi:[1,0,0]
	v_exp_f32_e32 v222, v222
	v_pk_fma_f32 v[128:129], v[120:121], v[128:129], s[30:31] op_sel_hi:[1,1,0]
	v_exp_f32_e32 v223, v223
	v_pk_fma_f32 v[128:129], v[120:121], v[128:129], s[34:35] op_sel_hi:[1,1,0]
	v_pk_fma_f32 v[128:129], v[120:121], v[128:129], s[36:37] op_sel_hi:[1,1,0]
	v_pk_mul_f32 v[128:129], v[120:121], v[128:129]
	v_pk_fma_f32 v[130:131], v[122:123], s[26:27], v[132:133] op_sel_hi:[1,0,0]
	v_exp_f32_e32 v224, v224
	v_pk_fma_f32 v[130:131], v[122:123], v[130:131], s[30:31] op_sel_hi:[1,1,0]
	v_exp_f32_e32 v225, v225
	v_pk_fma_f32 v[130:131], v[122:123], v[130:131], s[34:35] op_sel_hi:[1,1,0]
	v_pk_fma_f32 v[130:131], v[122:123], v[130:131], s[36:37] op_sel_hi:[1,1,0]
	v_pk_mul_f32 v[130:131], v[122:123], v[130:131]
	v_pk_mul_f32 v[124:125], v[218:219], v[124:125]
	v_pk_mul_f32 v[218:219], v[104:105], v[124:125]
	v_pk_fma_f32 v[124:125], v[104:105], v[124:125], v[104:105] neg_lo:[1,0,0] neg_hi:[1,0,0]
	v_cmp_gt_f32_e64 s[8:9], 0, v104
	v_cmp_gt_f32_e64 s[22:23], 0, v105
	v_lshlrev_b32_e32 v112, 16, v84
	v_and_b32_e32 v113, 0xffff0000, v84
	v_cndmask_b32_e64 v104, v124, v218, s[8:9]
	v_cndmask_b32_e64 v105, v125, v219, s[22:23]
	v_pk_mul_f32 v[104:105], v[104:105], v[112:113]
	v_cvt_pk_bf16_f32 v226, v104, v105
	v_pk_mul_f32 v[126:127], v[220:221], v[126:127]
	v_pk_mul_f32 v[220:221], v[106:107], v[126:127]
	v_pk_fma_f32 v[126:127], v[106:107], v[126:127], v[106:107] neg_lo:[1,0,0] neg_hi:[1,0,0]
	v_cmp_gt_f32_e64 s[8:9], 0, v106
	v_cmp_gt_f32_e64 s[22:23], 0, v107
	v_lshlrev_b32_e32 v112, 16, v85
	v_and_b32_e32 v113, 0xffff0000, v85
	v_cndmask_b32_e64 v106, v126, v220, s[8:9]
	v_cndmask_b32_e64 v107, v127, v221, s[22:23]
	v_pk_mul_f32 v[106:107], v[106:107], v[112:113]
	v_cvt_pk_bf16_f32 v227, v106, v107
	v_pk_mul_f32 v[128:129], v[222:223], v[128:129]
	v_pk_mul_f32 v[222:223], v[108:109], v[128:129]
	v_pk_fma_f32 v[128:129], v[108:109], v[128:129], v[108:109] neg_lo:[1,0,0] neg_hi:[1,0,0]
	v_cmp_gt_f32_e64 s[8:9], 0, v108
	v_cmp_gt_f32_e64 s[22:23], 0, v109
	v_lshlrev_b32_e32 v112, 16, v86
	v_and_b32_e32 v113, 0xffff0000, v86
	v_cndmask_b32_e64 v108, v128, v222, s[8:9]
	v_cndmask_b32_e64 v109, v129, v223, s[22:23]
	v_pk_mul_f32 v[108:109], v[108:109], v[112:113]
	v_cvt_pk_bf16_f32 v228, v108, v109
	v_pk_mul_f32 v[130:131], v[224:225], v[130:131]
	v_pk_mul_f32 v[224:225], v[110:111], v[130:131]
	v_pk_fma_f32 v[130:131], v[110:111], v[130:131], v[110:111] neg_lo:[1,0,0] neg_hi:[1,0,0]
	v_cmp_gt_f32_e64 s[8:9], 0, v110
	v_cmp_gt_f32_e64 s[22:23], 0, v111
	v_lshlrev_b32_e32 v112, 16, v87
	v_and_b32_e32 v113, 0xffff0000, v87
	v_cndmask_b32_e64 v110, v130, v224, s[8:9]
	v_cndmask_b32_e64 v111, v131, v225, s[22:23]
	v_pk_mul_f32 v[110:111], v[110:111], v[112:113]
	v_cvt_pk_bf16_f32 v229, v110, v111
	global_store_dwordx4 v140, v[226:229], s[14:15]
	v_add_u32_e32 v140, 0x2c00, v140
	v_add_u32_e32 v230, s27, v230
	s_nop 1
	v_readfirstlane_b32 s22, v230
	s_cmp_lt_u32 s22, 0x58000
	s_cbranch_scc1 .Lconv_item
